# GEMM K-loops: removed the redundant s_waitcnt lgkmcnt(0) after each barrier at the head of the MFMA blocks (the pre-barrier wait already covers the fragment reads)
# speedup vs baseline: 1.0191x; 1.0014x over previous
; #define PG8_STAGE(bufoff, gbase, voff) do { _Pragma("unroll") for (int _i = 0; _i < 2; ++_i) \
;         __builtin_amdgcn_global_load_lds((const unsigned*)((const char*)(gbase) + (voff)[_i]), (PG8_LAS unsigned*)(lds + (bufoff) + ldsw + _i * 8192), 16, 0, 0); } while (0)
; #define PG8_LDA(dst, b, h) do { _Pragma("unroll") for (int m = 0; m < 4; ++m) _Pragma("unroll") for (int k = 0; k < 2; ++k) dst[m][k] = *(const PG8_LAS bf16x8*)(lds + PG8_SA(b, h) + aoff + m * 2048 + k * 1024); } while (0)
; #define PG8_LDB(dst, b, h) do { _Pragma("unroll") for (int n = 0; n < 2; ++n) _Pragma("unroll") for (int k = 0; k < 2; ++k) dst[n][k] = *(const PG8_LAS bf16x8*)(lds + PG8_SB(b, h) + boff + n * 2048 + k * 1024); } while (0)
; #define PG8_MMA(ai, bj, At, Bt) do { __builtin_amdgcn_s_setprio(1); _Pragma("unroll") for (int m = 0; m < 4; ++m) _Pragma("unroll") for (int n = 0; n < 2; ++n) _Pragma("unroll") for (int k = 0; k < 2; ++k) \
;         acc[ai][bj][m][n] = __builtin_amdgcn_mfma_f32_16x16x32_bf16(Bt[n][k], At[m][k], acc[ai][bj][m][n], 0, 0, 0); __builtin_amdgcn_s_setprio(0); } while (0)
; template <class Epi, class Sched, bool ALIGN_EPI = false, bool SP2 = false>
; __device__ __forceinline__ void gemm_phase(PG8_LAS unsigned char* lds, const Gemm g, const Sched& S, const Epi& E, const int tid_in) {
;     ...
;         for (int t = 0; t < nt; t += 2) {
;             if constexpr (Epi::KSPLIT > 0) { if (t == Epi::KSPLIT / BK) E.midk(acc, cur, wr, wc, fr, fq); }
;             const bool last = (t == nt - 2);
;             const char* a1 = cA + (size_t)(t + 1) * kstep;
;             const char* a2 = last ? nA : cA + (size_t)(t + 2) * kstep; const char* b2 = last ? nB : cB + (size_t)(t + 2) * kstep;
;             const char* a3 = a2 + kstep; const char* b3 = b2 + kstep;
;             if (last && has_next) S.a_ready(nxt);
;             if constexpr (SP2) {
;             PG8_LDB(B0, 0, 0); PG8_LDB(B1, 0, 1); PG8_SCHED; PG8_LDA(At, 0, 0); PG8_STAGE(PG8_SA(1, 1), a1 + hstep, voffA);
;             PG8_WAIT_V(8); PG8_WAIT_L(0); PG8_BAR; PG8_MMA(0, 0, At, B0); PG8_MMA(0, 1, At, B1); PG8_BAR; PG8_SCHED;
;             PG8_LDA(At, 0, 1); PG8_STAGE(PG8_SB(0, 0), b2, voffB); PG8_STAGE(PG8_SB(0, 1), b2 + hstep, voffB); PG8_STAGE(PG8_SA(0, 0), a2, voffA);
;             PG8_WAIT_V(8); PG8_WAIT_L(0); PG8_BAR; PG8_MMA(1, 0, At, B0); PG8_MMA(1, 1, At, B1); PG8_BAR; PG8_SCHED;
.LBB0_352:
	s_mov_b32 m0, s49
	s_nop 0
	global_load_lds_dwordx4 v132, s[100:101]
	s_add_u32 s38, s34, 0xfff80080
	s_addc_u32 s39, s35, -1
	s_add_i32 s58, 0, 0x10000
	s_cmp_eq_u32 s57, 28
	s_cselect_b32 s43, s27, s39
	s_cselect_b32 s42, s53, s38
	v_add_u32_e32 v145, s58, v142
	s_cselect_b32 s39, s25, s56
	s_cselect_b32 s38, s54, s55
	s_add_i32 s60, 0, 0x14000
	ds_read_b128 v[146:149], v145
	ds_read_b128 v[150:153], v145 offset:1024
	ds_read_b128 v[154:157], v145 offset:2048
	ds_read_b128 v[158:161], v145 offset:3072
	v_add_u32_e32 v145, s60, v142
	ds_read_b128 v[162:165], v145
	ds_read_b128 v[166:169], v145 offset:1024
	ds_read_b128 v[170:173], v145 offset:2048
	ds_read_b128 v[174:177], v145 offset:3072
	s_add_i32 m0, s44, 0xc000
	ds_read_b128 v[178:181], v144
	ds_read_b128 v[182:185], v144 offset:1024
	ds_read_b128 v[186:189], v144 offset:2048
	ds_read_b128 v[190:193], v144 offset:3072
	ds_read_b128 v[194:197], v144 offset:4096
	ds_read_b128 v[198:201], v144 offset:5120
	ds_read_b128 v[202:205], v144 offset:6144
	ds_read_b128 v[208:211], v144 offset:7168
	global_load_lds_dwordx4 v138, s[34:35]
	s_add_i32 m0, s44, 0xe000
	s_nop 0
	global_load_lds_dwordx4 v140, s[34:35]
	s_waitcnt vmcnt(8)
	s_waitcnt lgkmcnt(0)
	s_barrier
	s_setprio 1
	v_mfma_f32_16x16x32_bf16 v[126:129], v[146:149], v[178:181], v[126:129]
	v_mfma_f32_16x16x32_bf16 v[122:125], v[154:157], v[178:181], v[122:125]
	v_mfma_f32_16x16x32_bf16 v[114:117], v[146:149], v[186:189], v[114:117]
	v_mfma_f32_16x16x32_bf16 v[106:109], v[154:157], v[186:189], v[106:109]
	v_mfma_f32_16x16x32_bf16 v[98:101], v[146:149], v[194:197], v[98:101]
	v_mfma_f32_16x16x32_bf16 v[90:93], v[154:157], v[194:197], v[90:93]
	v_mfma_f32_16x16x32_bf16 v[82:85], v[146:149], v[202:205], v[82:85]
	v_mfma_f32_16x16x32_bf16 v[74:77], v[154:157], v[202:205], v[74:77]
	v_mfma_f32_16x16x32_bf16 v[126:129], v[150:153], v[182:185], v[126:129]
	v_mfma_f32_16x16x32_bf16 v[122:125], v[158:161], v[182:185], v[122:125]
	v_mfma_f32_16x16x32_bf16 v[114:117], v[150:153], v[190:193], v[114:117]
	v_mfma_f32_16x16x32_bf16 v[106:109], v[158:161], v[190:193], v[106:109]
	v_mfma_f32_16x16x32_bf16 v[98:101], v[150:153], v[198:201], v[98:101]
	v_mfma_f32_16x16x32_bf16 v[90:93], v[158:161], v[198:201], v[90:93]
	v_mfma_f32_16x16x32_bf16 v[82:85], v[150:153], v[208:211], v[82:85]
	v_mfma_f32_16x16x32_bf16 v[74:77], v[158:161], v[208:211], v[74:77]
	s_setprio 0
	s_setprio 1
	v_mfma_f32_16x16x32_bf16 v[118:121], v[162:165], v[178:181], v[118:121]
	v_mfma_f32_16x16x32_bf16 v[110:113], v[170:173], v[178:181], v[110:113]
	v_mfma_f32_16x16x32_bf16 v[102:105], v[162:165], v[186:189], v[102:105]
	v_mfma_f32_16x16x32_bf16 v[94:97], v[170:173], v[186:189], v[94:97]
	v_mfma_f32_16x16x32_bf16 v[86:89], v[162:165], v[194:197], v[86:89]
	v_mfma_f32_16x16x32_bf16 v[78:81], v[170:173], v[194:197], v[78:81]
	v_mfma_f32_16x16x32_bf16 v[70:73], v[162:165], v[202:205], v[70:73]
	v_mfma_f32_16x16x32_bf16 v[66:69], v[170:173], v[202:205], v[66:69]
	v_mfma_f32_16x16x32_bf16 v[118:121], v[166:169], v[182:185], v[118:121]
	v_mfma_f32_16x16x32_bf16 v[110:113], v[174:177], v[182:185], v[110:113]
	v_mfma_f32_16x16x32_bf16 v[102:105], v[166:169], v[190:193], v[102:105]
	v_mfma_f32_16x16x32_bf16 v[94:97], v[174:177], v[190:193], v[94:97]
	v_mfma_f32_16x16x32_bf16 v[86:89], v[166:169], v[198:201], v[86:89]
	v_mfma_f32_16x16x32_bf16 v[78:81], v[174:177], v[198:201], v[78:81]
	v_mfma_f32_16x16x32_bf16 v[70:73], v[166:169], v[208:211], v[70:73]
	v_mfma_f32_16x16x32_bf16 v[66:69], v[174:177], v[208:211], v[66:69]
	s_setprio 0
	s_barrier
	s_add_i32 s58, s58, s19
	s_add_u32 s98, s38, 0x80
	s_addc_u32 s99, s39, 0
	s_mov_b32 m0, s58
	ds_read_b128 v[178:181], v144 offset:16384
	ds_read_b128 v[182:185], v144 offset:17408
	ds_read_b128 v[186:189], v144 offset:18432
	ds_read_b128 v[190:193], v144 offset:19456
	ds_read_b128 v[194:197], v144 offset:20480
	ds_read_b128 v[198:201], v144 offset:21504
	ds_read_b128 v[202:205], v144 offset:22528
	ds_read_b128 v[208:211], v144 offset:23552
	global_load_lds_dwordx4 v134, s[38:39]
	s_add_i32 m0, s58, 0x2000
	s_add_u32 s58, s38, 0x80000
	s_addc_u32 s59, s39, 0
	s_add_i32 s60, s60, s19
	global_load_lds_dwordx4 v130, s[38:39]
	s_mov_b32 m0, s60
	s_add_u32 s100, s42, 0x80
	s_addc_u32 s101, s43, 0
	global_load_lds_dwordx4 v134, s[58:59]
	s_add_i32 m0, s60, 0x2000
	s_nop 0
	global_load_lds_dwordx4 v130, s[58:59]
	s_mov_b32 m0, s44
	s_nop 0
	global_load_lds_dwordx4 v136, s[42:43]
	s_waitcnt vmcnt(7)
	s_waitcnt lgkmcnt(0)
	s_barrier
	s_setprio 1
	v_mfma_f32_16x16x32_bf16 v[62:65], v[146:149], v[178:181], v[62:65]
	v_mfma_f32_16x16x32_bf16 v[58:61], v[154:157], v[178:181], v[58:61]
	v_mfma_f32_16x16x32_bf16 v[50:53], v[146:149], v[186:189], v[50:53]
	v_mfma_f32_16x16x32_bf16 v[42:45], v[154:157], v[186:189], v[42:45]
	v_mfma_f32_16x16x32_bf16 v[34:37], v[146:149], v[194:197], v[34:37]
	v_mfma_f32_16x16x32_bf16 v[26:29], v[154:157], v[194:197], v[26:29]
	v_mfma_f32_16x16x32_bf16 v[16:19], v[146:149], v[202:205], v[16:19]
	v_mfma_f32_16x16x32_bf16 v[8:11], v[154:157], v[202:205], v[8:11]
	v_mfma_f32_16x16x32_bf16 v[62:65], v[150:153], v[182:185], v[62:65]
	v_mfma_f32_16x16x32_bf16 v[58:61], v[158:161], v[182:185], v[58:61]
	v_mfma_f32_16x16x32_bf16 v[50:53], v[150:153], v[190:193], v[50:53]
	v_mfma_f32_16x16x32_bf16 v[42:45], v[158:161], v[190:193], v[42:45]
	v_mfma_f32_16x16x32_bf16 v[34:37], v[150:153], v[198:201], v[34:37]
	v_mfma_f32_16x16x32_bf16 v[26:29], v[158:161], v[198:201], v[26:29]
	v_mfma_f32_16x16x32_bf16 v[16:19], v[150:153], v[208:211], v[16:19]
	v_mfma_f32_16x16x32_bf16 v[8:11], v[158:161], v[208:211], v[8:11]
	s_setprio 0
	s_setprio 1
	v_mfma_f32_16x16x32_bf16 v[54:57], v[162:165], v[178:181], v[54:57]
	v_mfma_f32_16x16x32_bf16 v[46:49], v[170:173], v[178:181], v[46:49]
	v_mfma_f32_16x16x32_bf16 v[38:41], v[162:165], v[186:189], v[38:41]
	v_mfma_f32_16x16x32_bf16 v[30:33], v[170:173], v[186:189], v[30:33]
	v_mfma_f32_16x16x32_bf16 v[22:25], v[162:165], v[194:197], v[22:25]
	v_mfma_f32_16x16x32_bf16 v[12:15], v[170:173], v[194:197], v[12:15]
	v_mfma_f32_16x16x32_bf16 v[4:7], v[162:165], v[202:205], v[4:7]
	v_mfma_f32_16x16x32_bf16 v[0:3], v[170:173], v[202:205], v[0:3]
	v_mfma_f32_16x16x32_bf16 v[54:57], v[166:169], v[182:185], v[54:57]
	v_mfma_f32_16x16x32_bf16 v[46:49], v[174:177], v[182:185], v[46:49]
	v_mfma_f32_16x16x32_bf16 v[38:41], v[166:169], v[190:193], v[38:41]
	v_mfma_f32_16x16x32_bf16 v[30:33], v[174:177], v[190:193], v[30:33]
	v_mfma_f32_16x16x32_bf16 v[22:25], v[166:169], v[198:201], v[22:25]
	v_mfma_f32_16x16x32_bf16 v[12:15], v[174:177], v[198:201], v[12:15]
	v_mfma_f32_16x16x32_bf16 v[4:7], v[166:169], v[208:211], v[4:7]
	v_mfma_f32_16x16x32_bf16 v[0:3], v[174:177], v[208:211], v[0:3]
	s_setprio 0
	s_barrier
; #define PG8_STAGE(bufoff, gbase, voff) do { _Pragma("unroll") for (int _i = 0; _i < 2; ++_i) \
;         __builtin_amdgcn_global_load_lds((const unsigned*)((const char*)(gbase) + (voff)[_i]), (PG8_LAS unsigned*)(lds + (bufoff) + ldsw + _i * 8192), 16, 0, 0); } while (0)
; #define PG8_LDA(dst, b, h) do { _Pragma("unroll") for (int m = 0; m < 4; ++m) _Pragma("unroll") for (int k = 0; k < 2; ++k) dst[m][k] = *(const PG8_LAS bf16x8*)(lds + PG8_SA(b, h) + aoff + m * 2048 + k * 1024); } while (0)
; #define PG8_LDB(dst, b, h) do { _Pragma("unroll") for (int n = 0; n < 2; ++n) _Pragma("unroll") for (int k = 0; k < 2; ++k) dst[n][k] = *(const PG8_LAS bf16x8*)(lds + PG8_SB(b, h) + boff + n * 2048 + k * 1024); } while (0)
; #define PG8_MMA(ai, bj, At, Bt) do { __builtin_amdgcn_s_setprio(1); _Pragma("unroll") for (int m = 0; m < 4; ++m) _Pragma("unroll") for (int n = 0; n < 2; ++n) _Pragma("unroll") for (int k = 0; k < 2; ++k) \
;         acc[ai][bj][m][n] = __builtin_amdgcn_mfma_f32_16x16x32_bf16(Bt[n][k], At[m][k], acc[ai][bj][m][n], 0, 0, 0); __builtin_amdgcn_s_setprio(0); } while (0)
; #define PG8_WAIT_V(n) asm volatile("s_waitcnt vmcnt(" #n ")" ::: "memory")
; template <class Epi, class Sched, bool ALIGN_EPI = false, bool SP2 = false>
; __device__ __forceinline__ void gemm_phase(PG8_LAS unsigned char* lds, const Gemm g, const Sched& S, const Epi& E, const int tid_in) {
;     ...
;         for (int t = 0; t < nt; t += 2) {
;             if constexpr (Epi::KSPLIT > 0) { if (t == Epi::KSPLIT / BK) E.midk(acc, cur, wr, wc, fr, fq); }
;             const bool last = (t == nt - 2);
;             const char* a1 = cA + (size_t)(t + 1) * kstep;
;             const char* a2 = last ? nA : cA + (size_t)(t + 2) * kstep; const char* b2 = last ? nB : cB + (size_t)(t + 2) * kstep;
;             const char* a3 = a2 + kstep; const char* b3 = b2 + kstep;
;     ...
;             PG8_LDB(B0, 1, 0); PG8_LDB(B1, 1, 1); PG8_SCHED; PG8_LDA(At, 1, 0); PG8_STAGE(PG8_SA(0, 1), a2 + hstep, voffA);
;             PG8_WAIT_V(8); PG8_WAIT_L(0); PG8_BAR; PG8_MMA(0, 0, At, B0); PG8_MMA(0, 1, At, B1); PG8_BAR; PG8_SCHED;
;             PG8_LDA(At, 1, 1); PG8_STAGE(PG8_SB(1, 0), b3, voffB); PG8_STAGE(PG8_SB(1, 1), b3 + hstep, voffB); PG8_STAGE(PG8_SA(1, 0), a3, voffA);
;             PG8_WAIT_V(8); PG8_WAIT_L(0); PG8_BAR; PG8_MMA(1, 0, At, B0); PG8_MMA(1, 1, At, B1); PG8_BAR; PG8_SCHED;
	s_add_i32 s58, 0, 0x18000
	v_add_u32_e32 v145, s58, v142
	s_add_i32 s59, 0, 0x1c000
	ds_read_b128 v[146:149], v145
	ds_read_b128 v[150:153], v145 offset:1024
	ds_read_b128 v[154:157], v145 offset:2048
	ds_read_b128 v[158:161], v145 offset:3072
	v_add_u32_e32 v145, s59, v142
	ds_read_b128 v[162:165], v145
	ds_read_b128 v[166:169], v145 offset:1024
	ds_read_b128 v[170:173], v145 offset:2048
	ds_read_b128 v[174:177], v145 offset:3072
	s_mov_b32 m0, s45
	s_nop 0
	global_load_lds_dwordx4 v132, s[42:43]
	s_add_u32 s42, s42, 0x80000
	s_addc_u32 s43, s43, 0
	s_mov_b32 m0, s46
	ds_read_b128 v[178:181], v144 offset:32768
	ds_read_b128 v[182:185], v144 offset:33792
	ds_read_b128 v[186:189], v144 offset:34816
	ds_read_b128 v[190:193], v144 offset:35840
	ds_read_b128 v[194:197], v144 offset:36864
	ds_read_b128 v[198:201], v144 offset:37888
	ds_read_b128 v[202:205], v144 offset:38912
	ds_read_b128 v[208:211], v144 offset:39936
	global_load_lds_dwordx4 v136, s[42:43]
	s_mov_b32 m0, s47
	s_nop 0
	global_load_lds_dwordx4 v132, s[42:43]
	s_waitcnt vmcnt(8)
	s_waitcnt lgkmcnt(0)
	s_barrier
	s_setprio 1
	v_mfma_f32_16x16x32_bf16 v[126:129], v[146:149], v[178:181], v[126:129]
	v_mfma_f32_16x16x32_bf16 v[122:125], v[154:157], v[178:181], v[122:125]
	v_mfma_f32_16x16x32_bf16 v[114:117], v[146:149], v[186:189], v[114:117]
	v_mfma_f32_16x16x32_bf16 v[106:109], v[154:157], v[186:189], v[106:109]
	v_mfma_f32_16x16x32_bf16 v[98:101], v[146:149], v[194:197], v[98:101]
	v_mfma_f32_16x16x32_bf16 v[90:93], v[154:157], v[194:197], v[90:93]
	v_mfma_f32_16x16x32_bf16 v[82:85], v[146:149], v[202:205], v[82:85]
	v_mfma_f32_16x16x32_bf16 v[74:77], v[154:157], v[202:205], v[74:77]
	v_mfma_f32_16x16x32_bf16 v[126:129], v[150:153], v[182:185], v[126:129]
	v_mfma_f32_16x16x32_bf16 v[122:125], v[158:161], v[182:185], v[122:125]
	v_mfma_f32_16x16x32_bf16 v[114:117], v[150:153], v[190:193], v[114:117]
	v_mfma_f32_16x16x32_bf16 v[106:109], v[158:161], v[190:193], v[106:109]
	v_mfma_f32_16x16x32_bf16 v[98:101], v[150:153], v[198:201], v[98:101]
	v_mfma_f32_16x16x32_bf16 v[90:93], v[158:161], v[198:201], v[90:93]
	v_mfma_f32_16x16x32_bf16 v[82:85], v[150:153], v[208:211], v[82:85]
	v_mfma_f32_16x16x32_bf16 v[74:77], v[158:161], v[208:211], v[74:77]
	s_setprio 0
	s_setprio 1
	v_mfma_f32_16x16x32_bf16 v[118:121], v[162:165], v[178:181], v[118:121]
	v_mfma_f32_16x16x32_bf16 v[110:113], v[170:173], v[178:181], v[110:113]
	v_mfma_f32_16x16x32_bf16 v[102:105], v[162:165], v[186:189], v[102:105]
	v_mfma_f32_16x16x32_bf16 v[94:97], v[170:173], v[186:189], v[94:97]
	v_mfma_f32_16x16x32_bf16 v[86:89], v[162:165], v[194:197], v[86:89]
	v_mfma_f32_16x16x32_bf16 v[78:81], v[170:173], v[194:197], v[78:81]
	v_mfma_f32_16x16x32_bf16 v[70:73], v[162:165], v[202:205], v[70:73]
	v_mfma_f32_16x16x32_bf16 v[66:69], v[170:173], v[202:205], v[66:69]
	v_mfma_f32_16x16x32_bf16 v[118:121], v[166:169], v[182:185], v[118:121]
	v_mfma_f32_16x16x32_bf16 v[110:113], v[174:177], v[182:185], v[110:113]
	v_mfma_f32_16x16x32_bf16 v[102:105], v[166:169], v[190:193], v[102:105]
	v_mfma_f32_16x16x32_bf16 v[94:97], v[174:177], v[190:193], v[94:97]
	v_mfma_f32_16x16x32_bf16 v[86:89], v[166:169], v[198:201], v[86:89]
	v_mfma_f32_16x16x32_bf16 v[78:81], v[174:177], v[198:201], v[78:81]
	v_mfma_f32_16x16x32_bf16 v[70:73], v[166:169], v[208:211], v[70:73]
	v_mfma_f32_16x16x32_bf16 v[66:69], v[174:177], v[208:211], v[66:69]
	s_setprio 0
	s_barrier
	s_add_i32 s42, s58, s19
	s_mov_b32 m0, s42
	ds_read_b128 v[178:181], v144 offset:49152
	ds_read_b128 v[182:185], v144 offset:50176
	ds_read_b128 v[186:189], v144 offset:51200
	ds_read_b128 v[190:193], v144 offset:52224
	ds_read_b128 v[194:197], v144 offset:53248
	ds_read_b128 v[198:201], v144 offset:54272
	ds_read_b128 v[202:205], v144 offset:55296
	ds_read_b128 v[208:211], v144 offset:56320
	global_load_lds_dwordx4 v134, s[98:99]
	s_add_i32 m0, s42, 0x2000
	s_add_u32 s38, s38, 0x80080
	s_addc_u32 s39, s39, 0
	s_add_i32 s42, s59, s19
	global_load_lds_dwordx4 v130, s[98:99]
	s_mov_b32 m0, s42
	s_nop 0
	global_load_lds_dwordx4 v134, s[38:39]
	s_add_i32 m0, s42, 0x2000
	s_nop 0
	global_load_lds_dwordx4 v130, s[38:39]
	s_mov_b32 m0, s48
	s_nop 0
	global_load_lds_dwordx4 v136, s[100:101]
	s_waitcnt vmcnt(7)
	s_waitcnt lgkmcnt(0)
	s_barrier
	s_setprio 1
	v_mfma_f32_16x16x32_bf16 v[62:65], v[146:149], v[178:181], v[62:65]
	v_mfma_f32_16x16x32_bf16 v[58:61], v[154:157], v[178:181], v[58:61]
	v_mfma_f32_16x16x32_bf16 v[50:53], v[146:149], v[186:189], v[50:53]
	v_mfma_f32_16x16x32_bf16 v[42:45], v[154:157], v[186:189], v[42:45]
	v_mfma_f32_16x16x32_bf16 v[34:37], v[146:149], v[194:197], v[34:37]
	v_mfma_f32_16x16x32_bf16 v[26:29], v[154:157], v[194:197], v[26:29]
	v_mfma_f32_16x16x32_bf16 v[16:19], v[146:149], v[202:205], v[16:19]
	v_mfma_f32_16x16x32_bf16 v[8:11], v[154:157], v[202:205], v[8:11]
	v_mfma_f32_16x16x32_bf16 v[62:65], v[150:153], v[182:185], v[62:65]
	v_mfma_f32_16x16x32_bf16 v[58:61], v[158:161], v[182:185], v[58:61]
	v_mfma_f32_16x16x32_bf16 v[50:53], v[150:153], v[190:193], v[50:53]
	v_mfma_f32_16x16x32_bf16 v[42:45], v[158:161], v[190:193], v[42:45]
	v_mfma_f32_16x16x32_bf16 v[34:37], v[150:153], v[198:201], v[34:37]
	v_mfma_f32_16x16x32_bf16 v[26:29], v[158:161], v[198:201], v[26:29]
	v_mfma_f32_16x16x32_bf16 v[16:19], v[150:153], v[208:211], v[16:19]
	v_mfma_f32_16x16x32_bf16 v[8:11], v[158:161], v[208:211], v[8:11]
	s_setprio 0
	s_setprio 1
	v_mfma_f32_16x16x32_bf16 v[54:57], v[162:165], v[178:181], v[54:57]
	v_mfma_f32_16x16x32_bf16 v[46:49], v[170:173], v[178:181], v[46:49]
	v_mfma_f32_16x16x32_bf16 v[38:41], v[162:165], v[186:189], v[38:41]
	v_mfma_f32_16x16x32_bf16 v[30:33], v[170:173], v[186:189], v[30:33]
	v_mfma_f32_16x16x32_bf16 v[22:25], v[162:165], v[194:197], v[22:25]
	v_mfma_f32_16x16x32_bf16 v[12:15], v[170:173], v[194:197], v[12:15]
	v_mfma_f32_16x16x32_bf16 v[4:7], v[162:165], v[202:205], v[4:7]
	v_mfma_f32_16x16x32_bf16 v[0:3], v[170:173], v[202:205], v[0:3]
	v_mfma_f32_16x16x32_bf16 v[54:57], v[166:169], v[182:185], v[54:57]
	v_mfma_f32_16x16x32_bf16 v[46:49], v[174:177], v[182:185], v[46:49]
	v_mfma_f32_16x16x32_bf16 v[38:41], v[166:169], v[190:193], v[38:41]
	v_mfma_f32_16x16x32_bf16 v[30:33], v[174:177], v[190:193], v[30:33]
	v_mfma_f32_16x16x32_bf16 v[22:25], v[166:169], v[198:201], v[22:25]
	v_mfma_f32_16x16x32_bf16 v[12:15], v[174:177], v[198:201], v[12:15]
	v_mfma_f32_16x16x32_bf16 v[4:7], v[166:169], v[208:211], v[4:7]
	v_mfma_f32_16x16x32_bf16 v[0:3], v[174:177], v[208:211], v[0:3]
	s_setprio 0
	s_barrier
	s_add_i32 s57, s57, 2
	s_add_u32 s34, s34, 0x100
	s_addc_u32 s35, s35, 0
	s_add_u32 s55, s55, 0x100
	s_addc_u32 s56, s56, 0
	s_cmp_gt_u32 s57, 29
	s_cbranch_scc0 .LBB0_352
	s_and_b64 vcc, exec, s[22:23]
	s_cbranch_vccz .LBB0_355
	s_barrier

; #define PG8_STAGE(bufoff, gbase, voff) do { _Pragma("unroll") for (int _i = 0; _i < 2; ++_i) \
;         __builtin_amdgcn_global_load_lds((const unsigned*)((const char*)(gbase) + (voff)[_i]), (PG8_LAS unsigned*)(lds + (bufoff) + ldsw + _i * 8192), 16, 0, 0); } while (0)
; #define PG8_LDA(dst, b, h) do { _Pragma("unroll") for (int m = 0; m < 4; ++m) _Pragma("unroll") for (int k = 0; k < 2; ++k) dst[m][k] = *(const PG8_LAS bf16x8*)(lds + PG8_SA(b, h) + aoff + m * 2048 + k * 1024); } while (0)
; #define PG8_LDB(dst, b, h) do { _Pragma("unroll") for (int n = 0; n < 2; ++n) _Pragma("unroll") for (int k = 0; k < 2; ++k) dst[n][k] = *(const PG8_LAS bf16x8*)(lds + PG8_SB(b, h) + boff + n * 2048 + k * 1024); } while (0)
; template <class Epi, class Sched, bool ALIGN_EPI = false, bool SP2 = false>
; __device__ __forceinline__ void gemm_phase(PG8_LAS unsigned char* lds, const Gemm g, const Sched& S, const Epi& E, const int tid_in) {
;     ...
;             const bool last = (t == nt - 2);
;             const char* a1 = cA + (size_t)(t + 1) * kstep;
;             const char* a2 = last ? nA : cA + (size_t)(t + 2) * kstep; const char* b2 = last ? nB : cB + (size_t)(t + 2) * kstep;
;             const char* a3 = a2 + kstep; const char* b3 = b2 + kstep;
;             if (last && has_next) S.a_ready(nxt);
;             if constexpr (SP2) {
;             PG8_LDB(B0, 0, 0); PG8_LDB(B1, 0, 1); PG8_SCHED; PG8_LDA(At, 0, 0); PG8_STAGE(PG8_SA(1, 1), a1 + hstep, voffA);
;             PG8_WAIT_V(8); PG8_WAIT_L(0); PG8_BAR; PG8_MMA(0, 0, At, B0); PG8_MMA(0, 1, At, B1); PG8_BAR; PG8_SCHED;
;             PG8_LDA(At, 0, 1); PG8_STAGE(PG8_SB(0, 0), b2, voffB); PG8_STAGE(PG8_SB(0, 1), b2 + hstep, voffB); PG8_STAGE(PG8_SA(0, 0), a2, voffA);
;             PG8_WAIT_V(8); PG8_WAIT_L(0); PG8_BAR; PG8_MMA(1, 0, At, B0); PG8_MMA(1, 1, At, B1); PG8_BAR; PG8_SCHED;
;             PG8_LDB(B0, 1, 0); PG8_LDB(B1, 1, 1); PG8_SCHED; PG8_LDA(At, 1, 0); PG8_STAGE(PG8_SA(0, 1), a2 + hstep, voffA);
;             PG8_WAIT_V(8); PG8_WAIT_L(0); PG8_BAR; PG8_MMA(0, 0, At, B0); PG8_MMA(0, 1, At, B1); PG8_BAR; PG8_SCHED;
;             PG8_LDA(At, 1, 1); PG8_STAGE(PG8_SB(1, 0), b3, voffB); PG8_STAGE(PG8_SB(1, 1), b3 + hstep, voffB); PG8_STAGE(PG8_SA(1, 0), a3, voffA);
;             PG8_WAIT_V(8); PG8_WAIT_L(0); PG8_BAR; PG8_MMA(1, 0, At, B0); PG8_MMA(1, 1, At, B1); PG8_BAR; PG8_SCHED;
.LBB0_374:
	s_mov_b32 m0, s49
	s_nop 0
	global_load_lds_dwordx4 v134, s[100:101]
	s_add_u32 s38, s34, 0xfff80080
	s_addc_u32 s39, s35, -1
	s_add_i32 s55, 0, 0x10000
	s_cmp_eq_u32 s54, 28
	s_cselect_b32 s43, s21, s39
	s_cselect_b32 s42, s25, s38
	v_add_u32_e32 v144, s55, v21
	s_cselect_b32 s39, s23, s53
	s_cselect_b32 s38, s51, s52
	s_add_i32 s58, 0, 0x14000
	ds_read_b128 v[148:151], v144
	ds_read_b128 v[152:155], v144 offset:1024
	ds_read_b128 v[156:159], v144 offset:2048
	ds_read_b128 v[160:163], v144 offset:3072
	v_add_u32_e32 v144, s58, v21
	ds_read_b128 v[164:167], v144
	ds_read_b128 v[168:171], v144 offset:1024
	ds_read_b128 v[172:175], v144 offset:2048
	ds_read_b128 v[176:179], v144 offset:3072
	s_add_i32 m0, s44, 0xc000
	ds_read_b128 v[180:183], v147
	ds_read_b128 v[184:187], v147 offset:1024
	ds_read_b128 v[188:191], v147 offset:2048
	ds_read_b128 v[192:195], v147 offset:3072
	ds_read_b128 v[196:199], v147 offset:4096
	ds_read_b128 v[200:203], v147 offset:5120
	ds_read_b128 v[208:211], v147 offset:6144
	ds_read_b128 v[212:215], v147 offset:7168
	global_load_lds_dwordx4 v140, s[34:35]
	s_add_i32 m0, s44, 0xe000
	s_nop 0
	global_load_lds_dwordx4 v142, s[34:35]
	s_waitcnt vmcnt(8)
	s_waitcnt lgkmcnt(0)
	s_barrier
	s_setprio 1
	v_mfma_f32_16x16x32_bf16 v[126:129], v[148:151], v[180:183], v[126:129]
	v_mfma_f32_16x16x32_bf16 v[122:125], v[156:159], v[180:183], v[122:125]
	v_mfma_f32_16x16x32_bf16 v[118:121], v[148:151], v[188:191], v[118:121]
	v_mfma_f32_16x16x32_bf16 v[110:113], v[156:159], v[188:191], v[110:113]
	v_mfma_f32_16x16x32_bf16 v[102:105], v[148:151], v[196:199], v[102:105]
	v_mfma_f32_16x16x32_bf16 v[94:97], v[156:159], v[196:199], v[94:97]
	v_mfma_f32_16x16x32_bf16 v[86:89], v[148:151], v[208:211], v[86:89]
	v_mfma_f32_16x16x32_bf16 v[78:81], v[156:159], v[208:211], v[78:81]
	v_mfma_f32_16x16x32_bf16 v[126:129], v[152:155], v[184:187], v[126:129]
	v_mfma_f32_16x16x32_bf16 v[122:125], v[160:163], v[184:187], v[122:125]
	v_mfma_f32_16x16x32_bf16 v[118:121], v[152:155], v[192:195], v[118:121]
	v_mfma_f32_16x16x32_bf16 v[110:113], v[160:163], v[192:195], v[110:113]
	v_mfma_f32_16x16x32_bf16 v[102:105], v[152:155], v[200:203], v[102:105]
	v_mfma_f32_16x16x32_bf16 v[94:97], v[160:163], v[200:203], v[94:97]
	v_mfma_f32_16x16x32_bf16 v[86:89], v[152:155], v[212:215], v[86:89]
	v_mfma_f32_16x16x32_bf16 v[78:81], v[160:163], v[212:215], v[78:81]
	s_setprio 0
	s_setprio 1
	v_mfma_f32_16x16x32_bf16 v[114:117], v[164:167], v[180:183], v[114:117]
	v_mfma_f32_16x16x32_bf16 v[106:109], v[172:175], v[180:183], v[106:109]
	v_mfma_f32_16x16x32_bf16 v[98:101], v[164:167], v[188:191], v[98:101]
	v_mfma_f32_16x16x32_bf16 v[90:93], v[172:175], v[188:191], v[90:93]
	v_mfma_f32_16x16x32_bf16 v[82:85], v[164:167], v[196:199], v[82:85]
	v_mfma_f32_16x16x32_bf16 v[74:77], v[172:175], v[196:199], v[74:77]
	v_mfma_f32_16x16x32_bf16 v[70:73], v[164:167], v[208:211], v[70:73]
	v_mfma_f32_16x16x32_bf16 v[66:69], v[172:175], v[208:211], v[66:69]
	v_mfma_f32_16x16x32_bf16 v[114:117], v[168:171], v[184:187], v[114:117]
	v_mfma_f32_16x16x32_bf16 v[106:109], v[176:179], v[184:187], v[106:109]
	v_mfma_f32_16x16x32_bf16 v[98:101], v[168:171], v[192:195], v[98:101]
	v_mfma_f32_16x16x32_bf16 v[90:93], v[176:179], v[192:195], v[90:93]
	v_mfma_f32_16x16x32_bf16 v[82:85], v[168:171], v[200:203], v[82:85]
	v_mfma_f32_16x16x32_bf16 v[74:77], v[176:179], v[200:203], v[74:77]
	v_mfma_f32_16x16x32_bf16 v[70:73], v[168:171], v[212:215], v[70:73]
	v_mfma_f32_16x16x32_bf16 v[66:69], v[176:179], v[212:215], v[66:69]
	s_setprio 0
	s_barrier
	s_add_i32 s55, s55, s19
	s_add_u32 s98, s38, 0x80
	s_addc_u32 s99, s39, 0
	s_mov_b32 m0, s55
	ds_read_b128 v[180:183], v147 offset:16384
	ds_read_b128 v[184:187], v147 offset:17408
	ds_read_b128 v[188:191], v147 offset:18432
	ds_read_b128 v[192:195], v147 offset:19456
	ds_read_b128 v[196:199], v147 offset:20480
	ds_read_b128 v[200:203], v147 offset:21504
	ds_read_b128 v[208:211], v147 offset:22528
	ds_read_b128 v[212:215], v147 offset:23552
	global_load_lds_dwordx4 v132, s[38:39]
	s_add_i32 m0, s55, 0x2000
	s_add_u32 s56, s38, 0x80000
	s_addc_u32 s57, s39, 0
	s_add_i32 s55, s58, s19
	global_load_lds_dwordx4 v136, s[38:39]
	s_mov_b32 m0, s55
	s_add_u32 s100, s42, 0x80
	s_addc_u32 s101, s43, 0
	global_load_lds_dwordx4 v132, s[56:57]
	s_add_i32 m0, s55, 0x2000
	s_nop 0
	global_load_lds_dwordx4 v136, s[56:57]
	s_mov_b32 m0, s44
	s_nop 0
	global_load_lds_dwordx4 v130, s[42:43]
	s_waitcnt vmcnt(7)
	s_waitcnt lgkmcnt(0)
	s_barrier
	s_setprio 1
	v_mfma_f32_16x16x32_bf16 v[62:65], v[148:151], v[180:183], v[62:65]
	v_mfma_f32_16x16x32_bf16 v[58:61], v[156:159], v[180:183], v[58:61]
	v_mfma_f32_16x16x32_bf16 v[54:57], v[148:151], v[188:191], v[54:57]
	v_mfma_f32_16x16x32_bf16 v[46:49], v[156:159], v[188:191], v[46:49]
	v_mfma_f32_16x16x32_bf16 v[38:41], v[148:151], v[196:199], v[38:41]
	v_mfma_f32_16x16x32_bf16 v[30:33], v[156:159], v[196:199], v[30:33]
	v_mfma_f32_16x16x32_bf16 v[22:25], v[148:151], v[208:211], v[22:25]
	v_mfma_f32_16x16x32_bf16 v[12:15], v[156:159], v[208:211], v[12:15]
	v_mfma_f32_16x16x32_bf16 v[62:65], v[152:155], v[184:187], v[62:65]
	v_mfma_f32_16x16x32_bf16 v[58:61], v[160:163], v[184:187], v[58:61]
	v_mfma_f32_16x16x32_bf16 v[54:57], v[152:155], v[192:195], v[54:57]
	v_mfma_f32_16x16x32_bf16 v[46:49], v[160:163], v[192:195], v[46:49]
	v_mfma_f32_16x16x32_bf16 v[38:41], v[152:155], v[200:203], v[38:41]
	v_mfma_f32_16x16x32_bf16 v[30:33], v[160:163], v[200:203], v[30:33]
	v_mfma_f32_16x16x32_bf16 v[22:25], v[152:155], v[212:215], v[22:25]
	v_mfma_f32_16x16x32_bf16 v[12:15], v[160:163], v[212:215], v[12:15]
	s_setprio 0
	s_setprio 1
	v_mfma_f32_16x16x32_bf16 v[50:53], v[164:167], v[180:183], v[50:53]
	v_mfma_f32_16x16x32_bf16 v[42:45], v[172:175], v[180:183], v[42:45]
	v_mfma_f32_16x16x32_bf16 v[34:37], v[164:167], v[188:191], v[34:37]
	v_mfma_f32_16x16x32_bf16 v[26:29], v[172:175], v[188:191], v[26:29]
	v_mfma_f32_16x16x32_bf16 v[16:19], v[164:167], v[196:199], v[16:19]
	v_mfma_f32_16x16x32_bf16 v[8:11], v[172:175], v[196:199], v[8:11]
	v_mfma_f32_16x16x32_bf16 v[4:7], v[164:167], v[208:211], v[4:7]
	v_mfma_f32_16x16x32_bf16 v[0:3], v[172:175], v[208:211], v[0:3]
	v_mfma_f32_16x16x32_bf16 v[50:53], v[168:171], v[184:187], v[50:53]
	v_mfma_f32_16x16x32_bf16 v[42:45], v[176:179], v[184:187], v[42:45]
	v_mfma_f32_16x16x32_bf16 v[34:37], v[168:171], v[192:195], v[34:37]
	v_mfma_f32_16x16x32_bf16 v[26:29], v[176:179], v[192:195], v[26:29]
	v_mfma_f32_16x16x32_bf16 v[16:19], v[168:171], v[200:203], v[16:19]
	v_mfma_f32_16x16x32_bf16 v[8:11], v[176:179], v[200:203], v[8:11]
	v_mfma_f32_16x16x32_bf16 v[4:7], v[168:171], v[212:215], v[4:7]
	v_mfma_f32_16x16x32_bf16 v[0:3], v[176:179], v[212:215], v[0:3]
	s_setprio 0
	s_barrier
; #define PG8_STAGE(bufoff, gbase, voff) do { _Pragma("unroll") for (int _i = 0; _i < 2; ++_i) \
;         __builtin_amdgcn_global_load_lds((const unsigned*)((const char*)(gbase) + (voff)[_i]), (PG8_LAS unsigned*)(lds + (bufoff) + ldsw + _i * 8192), 16, 0, 0); } while (0)
; #define PG8_LDA(dst, b, h) do { _Pragma("unroll") for (int m = 0; m < 4; ++m) _Pragma("unroll") for (int k = 0; k < 2; ++k) dst[m][k] = *(const PG8_LAS bf16x8*)(lds + PG8_SA(b, h) + aoff + m * 2048 + k * 1024); } while (0)
; #define PG8_LDB(dst, b, h) do { _Pragma("unroll") for (int n = 0; n < 2; ++n) _Pragma("unroll") for (int k = 0; k < 2; ++k) dst[n][k] = *(const PG8_LAS bf16x8*)(lds + PG8_SB(b, h) + boff + n * 2048 + k * 1024); } while (0)
; #define PG8_MMA(ai, bj, At, Bt) do { __builtin_amdgcn_s_setprio(1); _Pragma("unroll") for (int m = 0; m < 4; ++m) _Pragma("unroll") for (int n = 0; n < 2; ++n) _Pragma("unroll") for (int k = 0; k < 2; ++k) \
;         acc[ai][bj][m][n] = __builtin_amdgcn_mfma_f32_16x16x32_bf16(Bt[n][k], At[m][k], acc[ai][bj][m][n], 0, 0, 0); __builtin_amdgcn_s_setprio(0); } while (0)
; #define PG8_WAIT_V(n) asm volatile("s_waitcnt vmcnt(" #n ")" ::: "memory")
; #define PG8_WAIT_L(n) asm volatile("s_waitcnt lgkmcnt(" #n ")" ::: "memory")
; #define PG8_BAR __builtin_amdgcn_s_barrier()
; #define PG8_SCHED __builtin_amdgcn_sched_barrier(0)
; template <class Epi, class Sched, bool ALIGN_EPI = false, bool SP2 = false>
; __device__ __forceinline__ void gemm_phase(PG8_LAS unsigned char* lds, const Gemm g, const Sched& S, const Epi& E, const int tid_in) {
;     ...
;         for (int t = 0; t < nt; t += 2) {
;     ...
;             PG8_LDB(B0, 1, 0); PG8_LDB(B1, 1, 1); PG8_SCHED; PG8_LDA(At, 1, 0); PG8_STAGE(PG8_SA(0, 1), a2 + hstep, voffA);
;             PG8_WAIT_V(8); PG8_WAIT_L(0); PG8_BAR; PG8_MMA(0, 0, At, B0); PG8_MMA(0, 1, At, B1); PG8_BAR; PG8_SCHED;
;             PG8_LDA(At, 1, 1); PG8_STAGE(PG8_SB(1, 0), b3, voffB); PG8_STAGE(PG8_SB(1, 1), b3 + hstep, voffB); PG8_STAGE(PG8_SA(1, 0), a3, voffA);
;             PG8_WAIT_V(8); PG8_WAIT_L(0); PG8_BAR; PG8_MMA(1, 0, At, B0); PG8_MMA(1, 1, At, B1); PG8_BAR; PG8_SCHED;
	s_add_i32 s55, 0, 0x18000
	s_add_i32 s56, 0, 0x1c000
	v_add_u32_e32 v160, s55, v21
	v_add_u32_e32 v176, s56, v21
	ds_read_b128 v[148:151], v160
	ds_read_b128 v[152:155], v160 offset:1024
	ds_read_b128 v[156:159], v160 offset:2048
	ds_read_b128 v[160:163], v160 offset:3072
	ds_read_b128 v[164:167], v176
	ds_read_b128 v[168:171], v176 offset:1024
	ds_read_b128 v[172:175], v176 offset:2048
	ds_read_b128 v[176:179], v176 offset:3072
	s_mov_b32 m0, s45
	s_nop 0
	global_load_lds_dwordx4 v134, s[42:43]
	s_add_u32 s42, s42, 0x80000
	s_addc_u32 s43, s43, 0
	s_mov_b32 m0, s46
	ds_read_b128 v[180:183], v147 offset:32768
	ds_read_b128 v[184:187], v147 offset:33792
	ds_read_b128 v[188:191], v147 offset:34816
	ds_read_b128 v[192:195], v147 offset:35840
	ds_read_b128 v[196:199], v147 offset:36864
	ds_read_b128 v[200:203], v147 offset:37888
	ds_read_b128 v[208:211], v147 offset:38912
	ds_read_b128 v[212:215], v147 offset:39936
	global_load_lds_dwordx4 v130, s[42:43]
	s_mov_b32 m0, s47
	s_nop 0
	global_load_lds_dwordx4 v134, s[42:43]
	s_waitcnt vmcnt(8)
	s_waitcnt lgkmcnt(0)
	s_barrier
	s_setprio 1
	v_mfma_f32_16x16x32_bf16 v[126:129], v[148:151], v[180:183], v[126:129]
	v_mfma_f32_16x16x32_bf16 v[122:125], v[156:159], v[180:183], v[122:125]
	v_mfma_f32_16x16x32_bf16 v[118:121], v[148:151], v[188:191], v[118:121]
	v_mfma_f32_16x16x32_bf16 v[110:113], v[156:159], v[188:191], v[110:113]
	v_mfma_f32_16x16x32_bf16 v[102:105], v[148:151], v[196:199], v[102:105]
	v_mfma_f32_16x16x32_bf16 v[94:97], v[156:159], v[196:199], v[94:97]
	v_mfma_f32_16x16x32_bf16 v[86:89], v[148:151], v[208:211], v[86:89]
	v_mfma_f32_16x16x32_bf16 v[78:81], v[156:159], v[208:211], v[78:81]
	v_mfma_f32_16x16x32_bf16 v[126:129], v[152:155], v[184:187], v[126:129]
	v_mfma_f32_16x16x32_bf16 v[122:125], v[160:163], v[184:187], v[122:125]
	v_mfma_f32_16x16x32_bf16 v[118:121], v[152:155], v[192:195], v[118:121]
	v_mfma_f32_16x16x32_bf16 v[110:113], v[160:163], v[192:195], v[110:113]
	v_mfma_f32_16x16x32_bf16 v[102:105], v[152:155], v[200:203], v[102:105]
	v_mfma_f32_16x16x32_bf16 v[94:97], v[160:163], v[200:203], v[94:97]
	v_mfma_f32_16x16x32_bf16 v[86:89], v[152:155], v[212:215], v[86:89]
	v_mfma_f32_16x16x32_bf16 v[78:81], v[160:163], v[212:215], v[78:81]
	s_setprio 0
	s_setprio 1
	v_mfma_f32_16x16x32_bf16 v[114:117], v[164:167], v[180:183], v[114:117]
	v_mfma_f32_16x16x32_bf16 v[106:109], v[172:175], v[180:183], v[106:109]
	v_mfma_f32_16x16x32_bf16 v[98:101], v[164:167], v[188:191], v[98:101]
	v_mfma_f32_16x16x32_bf16 v[90:93], v[172:175], v[188:191], v[90:93]
	v_mfma_f32_16x16x32_bf16 v[82:85], v[164:167], v[196:199], v[82:85]
	v_mfma_f32_16x16x32_bf16 v[74:77], v[172:175], v[196:199], v[74:77]
	v_mfma_f32_16x16x32_bf16 v[70:73], v[164:167], v[208:211], v[70:73]
	v_mfma_f32_16x16x32_bf16 v[66:69], v[172:175], v[208:211], v[66:69]
	v_mfma_f32_16x16x32_bf16 v[114:117], v[168:171], v[184:187], v[114:117]
	v_mfma_f32_16x16x32_bf16 v[106:109], v[176:179], v[184:187], v[106:109]
	v_mfma_f32_16x16x32_bf16 v[98:101], v[168:171], v[192:195], v[98:101]
	v_mfma_f32_16x16x32_bf16 v[90:93], v[176:179], v[192:195], v[90:93]
	v_mfma_f32_16x16x32_bf16 v[82:85], v[168:171], v[200:203], v[82:85]
	v_mfma_f32_16x16x32_bf16 v[74:77], v[176:179], v[200:203], v[74:77]
	v_mfma_f32_16x16x32_bf16 v[70:73], v[168:171], v[212:215], v[70:73]
	v_mfma_f32_16x16x32_bf16 v[66:69], v[176:179], v[212:215], v[66:69]
	s_setprio 0
	s_barrier
	s_add_i32 s42, s55, s19
	s_mov_b32 m0, s42
	ds_read_b128 v[180:183], v147 offset:49152
	ds_read_b128 v[184:187], v147 offset:50176
	ds_read_b128 v[188:191], v147 offset:51200
	ds_read_b128 v[192:195], v147 offset:52224
	ds_read_b128 v[196:199], v147 offset:53248
	ds_read_b128 v[200:203], v147 offset:54272
	ds_read_b128 v[208:211], v147 offset:55296
	ds_read_b128 v[212:215], v147 offset:56320
	global_load_lds_dwordx4 v132, s[98:99]
	s_add_i32 m0, s42, 0x2000
	s_add_u32 s38, s38, 0x80080
	s_addc_u32 s39, s39, 0
	s_add_i32 s42, s56, s19
	global_load_lds_dwordx4 v136, s[98:99]
	s_mov_b32 m0, s42
	s_nop 0
	global_load_lds_dwordx4 v132, s[38:39]
	s_add_i32 m0, s42, 0x2000
	s_nop 0
	global_load_lds_dwordx4 v136, s[38:39]
	s_mov_b32 m0, s48
	s_nop 0
	global_load_lds_dwordx4 v130, s[100:101]
	s_waitcnt vmcnt(7)
	s_waitcnt lgkmcnt(0)
	s_barrier
	s_setprio 1
	v_mfma_f32_16x16x32_bf16 v[62:65], v[148:151], v[180:183], v[62:65]
	v_mfma_f32_16x16x32_bf16 v[58:61], v[156:159], v[180:183], v[58:61]
	v_mfma_f32_16x16x32_bf16 v[54:57], v[148:151], v[188:191], v[54:57]
	v_mfma_f32_16x16x32_bf16 v[46:49], v[156:159], v[188:191], v[46:49]
	v_mfma_f32_16x16x32_bf16 v[38:41], v[148:151], v[196:199], v[38:41]
	v_mfma_f32_16x16x32_bf16 v[30:33], v[156:159], v[196:199], v[30:33]
	v_mfma_f32_16x16x32_bf16 v[22:25], v[148:151], v[208:211], v[22:25]
	v_mfma_f32_16x16x32_bf16 v[12:15], v[156:159], v[208:211], v[12:15]
	v_mfma_f32_16x16x32_bf16 v[62:65], v[152:155], v[184:187], v[62:65]
	v_mfma_f32_16x16x32_bf16 v[58:61], v[160:163], v[184:187], v[58:61]
	v_mfma_f32_16x16x32_bf16 v[54:57], v[152:155], v[192:195], v[54:57]
	v_mfma_f32_16x16x32_bf16 v[46:49], v[160:163], v[192:195], v[46:49]
	v_mfma_f32_16x16x32_bf16 v[38:41], v[152:155], v[200:203], v[38:41]
	v_mfma_f32_16x16x32_bf16 v[30:33], v[160:163], v[200:203], v[30:33]
	v_mfma_f32_16x16x32_bf16 v[22:25], v[152:155], v[212:215], v[22:25]
	v_mfma_f32_16x16x32_bf16 v[12:15], v[160:163], v[212:215], v[12:15]
	s_setprio 0
	s_setprio 1
	v_mfma_f32_16x16x32_bf16 v[50:53], v[164:167], v[180:183], v[50:53]
	v_mfma_f32_16x16x32_bf16 v[42:45], v[172:175], v[180:183], v[42:45]
	v_mfma_f32_16x16x32_bf16 v[34:37], v[164:167], v[188:191], v[34:37]
	v_mfma_f32_16x16x32_bf16 v[26:29], v[172:175], v[188:191], v[26:29]
	v_mfma_f32_16x16x32_bf16 v[16:19], v[164:167], v[196:199], v[16:19]
	v_mfma_f32_16x16x32_bf16 v[8:11], v[172:175], v[196:199], v[8:11]
	v_mfma_f32_16x16x32_bf16 v[4:7], v[164:167], v[208:211], v[4:7]
	v_mfma_f32_16x16x32_bf16 v[0:3], v[172:175], v[208:211], v[0:3]
	v_mfma_f32_16x16x32_bf16 v[50:53], v[168:171], v[184:187], v[50:53]
	v_mfma_f32_16x16x32_bf16 v[42:45], v[176:179], v[184:187], v[42:45]
	v_mfma_f32_16x16x32_bf16 v[34:37], v[168:171], v[192:195], v[34:37]
	v_mfma_f32_16x16x32_bf16 v[26:29], v[176:179], v[192:195], v[26:29]
	v_mfma_f32_16x16x32_bf16 v[16:19], v[168:171], v[200:203], v[16:19]
	v_mfma_f32_16x16x32_bf16 v[8:11], v[176:179], v[200:203], v[8:11]
	v_mfma_f32_16x16x32_bf16 v[4:7], v[168:171], v[212:215], v[4:7]
	v_mfma_f32_16x16x32_bf16 v[0:3], v[176:179], v[212:215], v[0:3]
	s_setprio 0
	s_barrier
	s_add_i32 s54, s54, 2
	s_add_u32 s34, s34, 0x100
	s_addc_u32 s35, s35, 0
	s_add_u32 s52, s52, 0x100
	s_addc_u32 s53, s53, 0
	s_cmp_gt_u32 s54, 29
	s_cbranch_scc0 .LBB0_374
	s_and_b64 vcc, exec, s[6:7]
	v_readlane_b32 s52, v255, 9
	v_readlane_b32 s53, v255, 10
	s_cbranch_vccz .LBB0_377
	s_barrier

; #define PG8_STAGE(bufoff, gbase, voff) do { _Pragma("unroll") for (int _i = 0; _i < 2; ++_i) \
;         __builtin_amdgcn_global_load_lds((const unsigned*)((const char*)(gbase) + (voff)[_i]), (PG8_LAS unsigned*)(lds + (bufoff) + ldsw + _i * 8192), 16, 0, 0); } while (0)
; #define PG8_LDA(dst, b, h) do { _Pragma("unroll") for (int m = 0; m < 4; ++m) _Pragma("unroll") for (int k = 0; k < 2; ++k) dst[m][k] = *(const PG8_LAS bf16x8*)(lds + PG8_SA(b, h) + aoff + m * 2048 + k * 1024); } while (0)
; #define PG8_LDB(dst, b, h) do { _Pragma("unroll") for (int n = 0; n < 2; ++n) _Pragma("unroll") for (int k = 0; k < 2; ++k) dst[n][k] = *(const PG8_LAS bf16x8*)(lds + PG8_SB(b, h) + boff + n * 2048 + k * 1024); } while (0)
; template <class Epi, class Sched, bool ALIGN_EPI = false, bool SP2 = false>
; __device__ __forceinline__ void gemm_phase(PG8_LAS unsigned char* lds, const Gemm g, const Sched& S, const Epi& E, const int tid_in) {
;     ...
;             const bool last = (t == nt - 2);
;             const char* a1 = cA + (size_t)(t + 1) * kstep;
;             const char* a2 = last ? nA : cA + (size_t)(t + 2) * kstep; const char* b2 = last ? nB : cB + (size_t)(t + 2) * kstep;
;             const char* a3 = a2 + kstep; const char* b3 = b2 + kstep;
;             if (last && has_next) S.a_ready(nxt);
;             if constexpr (SP2) {
;             PG8_LDB(B0, 0, 0); PG8_LDB(B1, 0, 1); PG8_SCHED; PG8_LDA(At, 0, 0); PG8_STAGE(PG8_SA(1, 1), a1 + hstep, voffA);
;             PG8_WAIT_V(8); PG8_WAIT_L(0); PG8_BAR; PG8_MMA(0, 0, At, B0); PG8_MMA(0, 1, At, B1); PG8_BAR; PG8_SCHED;
;             PG8_LDA(At, 0, 1); PG8_STAGE(PG8_SB(0, 0), b2, voffB); PG8_STAGE(PG8_SB(0, 1), b2 + hstep, voffB); PG8_STAGE(PG8_SA(0, 0), a2, voffA);
;             PG8_WAIT_V(8); PG8_WAIT_L(0); PG8_BAR; PG8_MMA(1, 0, At, B0); PG8_MMA(1, 1, At, B1); PG8_BAR; PG8_SCHED;
;             PG8_LDB(B0, 1, 0); PG8_LDB(B1, 1, 1); PG8_SCHED; PG8_LDA(At, 1, 0); PG8_STAGE(PG8_SA(0, 1), a2 + hstep, voffA);
;             PG8_WAIT_V(8); PG8_WAIT_L(0); PG8_BAR; PG8_MMA(0, 0, At, B0); PG8_MMA(0, 1, At, B1); PG8_BAR; PG8_SCHED;
;             PG8_LDA(At, 1, 1); PG8_STAGE(PG8_SB(1, 0), b3, voffB); PG8_STAGE(PG8_SB(1, 1), b3 + hstep, voffB); PG8_STAGE(PG8_SA(1, 0), a3, voffA);
;             PG8_WAIT_V(8); PG8_WAIT_L(0); PG8_BAR; PG8_MMA(1, 0, At, B0); PG8_MMA(1, 1, At, B1); PG8_BAR; PG8_SCHED;
.LBB0_394:
	s_mov_b32 m0, s45
	s_nop 0
	global_load_lds_dwordx4 v132, s[100:101]
	s_add_u32 s30, s28, 0xfff80080
	s_addc_u32 s31, s29, -1
	s_add_i32 s54, 0, 0x10000
	s_cmp_eq_u32 s53, 28
	s_cselect_b32 s35, s23, s31
	s_cselect_b32 s34, s49, s30
	v_add_u32_e32 v144, s54, v21
	s_cselect_b32 s31, s21, s52
	s_cselect_b32 s30, s50, s51
	s_add_i32 s56, 0, 0x14000
	ds_read_b128 v[148:151], v144
	ds_read_b128 v[152:155], v144 offset:1024
	ds_read_b128 v[156:159], v144 offset:2048
	ds_read_b128 v[160:163], v144 offset:3072
	v_add_u32_e32 v144, s56, v21
	ds_read_b128 v[164:167], v144
	ds_read_b128 v[168:171], v144 offset:1024
	ds_read_b128 v[172:175], v144 offset:2048
	ds_read_b128 v[176:179], v144 offset:3072
	s_add_i32 m0, s38, 0xc000
	ds_read_b128 v[180:183], v147
	ds_read_b128 v[184:187], v147 offset:1024
	ds_read_b128 v[188:191], v147 offset:2048
	ds_read_b128 v[192:195], v147 offset:3072
	ds_read_b128 v[196:199], v147 offset:4096
	ds_read_b128 v[200:203], v147 offset:5120
	ds_read_b128 v[208:211], v147 offset:6144
	ds_read_b128 v[212:215], v147 offset:7168
	global_load_lds_dwordx4 v140, s[28:29]
	s_add_i32 m0, s38, 0xe000
	s_nop 0
	global_load_lds_dwordx4 v142, s[28:29]
	s_waitcnt vmcnt(8)
	s_waitcnt lgkmcnt(0)
	s_barrier
	s_setprio 1
	v_mfma_f32_16x16x32_bf16 v[126:129], v[148:151], v[180:183], v[126:129]
	v_mfma_f32_16x16x32_bf16 v[122:125], v[156:159], v[180:183], v[122:125]
	v_mfma_f32_16x16x32_bf16 v[118:121], v[148:151], v[188:191], v[118:121]
	v_mfma_f32_16x16x32_bf16 v[110:113], v[156:159], v[188:191], v[110:113]
	v_mfma_f32_16x16x32_bf16 v[102:105], v[148:151], v[196:199], v[102:105]
	v_mfma_f32_16x16x32_bf16 v[94:97], v[156:159], v[196:199], v[94:97]
	v_mfma_f32_16x16x32_bf16 v[86:89], v[148:151], v[208:211], v[86:89]
	v_mfma_f32_16x16x32_bf16 v[78:81], v[156:159], v[208:211], v[78:81]
	v_mfma_f32_16x16x32_bf16 v[126:129], v[152:155], v[184:187], v[126:129]
	v_mfma_f32_16x16x32_bf16 v[122:125], v[160:163], v[184:187], v[122:125]
	v_mfma_f32_16x16x32_bf16 v[118:121], v[152:155], v[192:195], v[118:121]
	v_mfma_f32_16x16x32_bf16 v[110:113], v[160:163], v[192:195], v[110:113]
	v_mfma_f32_16x16x32_bf16 v[102:105], v[152:155], v[200:203], v[102:105]
	v_mfma_f32_16x16x32_bf16 v[94:97], v[160:163], v[200:203], v[94:97]
	v_mfma_f32_16x16x32_bf16 v[86:89], v[152:155], v[212:215], v[86:89]
	v_mfma_f32_16x16x32_bf16 v[78:81], v[160:163], v[212:215], v[78:81]
	s_setprio 0
	s_setprio 1
	v_mfma_f32_16x16x32_bf16 v[114:117], v[164:167], v[180:183], v[114:117]
	v_mfma_f32_16x16x32_bf16 v[106:109], v[172:175], v[180:183], v[106:109]
	v_mfma_f32_16x16x32_bf16 v[98:101], v[164:167], v[188:191], v[98:101]
	v_mfma_f32_16x16x32_bf16 v[90:93], v[172:175], v[188:191], v[90:93]
	v_mfma_f32_16x16x32_bf16 v[82:85], v[164:167], v[196:199], v[82:85]
	v_mfma_f32_16x16x32_bf16 v[74:77], v[172:175], v[196:199], v[74:77]
	v_mfma_f32_16x16x32_bf16 v[70:73], v[164:167], v[208:211], v[70:73]
	v_mfma_f32_16x16x32_bf16 v[66:69], v[172:175], v[208:211], v[66:69]
	v_mfma_f32_16x16x32_bf16 v[114:117], v[168:171], v[184:187], v[114:117]
	v_mfma_f32_16x16x32_bf16 v[106:109], v[176:179], v[184:187], v[106:109]
	v_mfma_f32_16x16x32_bf16 v[98:101], v[168:171], v[192:195], v[98:101]
	v_mfma_f32_16x16x32_bf16 v[90:93], v[176:179], v[192:195], v[90:93]
	v_mfma_f32_16x16x32_bf16 v[82:85], v[168:171], v[200:203], v[82:85]
	v_mfma_f32_16x16x32_bf16 v[74:77], v[176:179], v[200:203], v[74:77]
	v_mfma_f32_16x16x32_bf16 v[70:73], v[168:171], v[212:215], v[70:73]
	v_mfma_f32_16x16x32_bf16 v[66:69], v[176:179], v[212:215], v[66:69]
	s_setprio 0
	s_barrier
	s_add_i32 s54, s54, s19
	s_add_u32 s98, s30, 0x80
	s_addc_u32 s99, s31, 0
	s_mov_b32 m0, s54
	ds_read_b128 v[180:183], v147 offset:16384
	ds_read_b128 v[184:187], v147 offset:17408
	ds_read_b128 v[188:191], v147 offset:18432
	ds_read_b128 v[192:195], v147 offset:19456
	ds_read_b128 v[196:199], v147 offset:20480
	ds_read_b128 v[200:203], v147 offset:21504
	ds_read_b128 v[208:211], v147 offset:22528
	ds_read_b128 v[212:215], v147 offset:23552
	global_load_lds_dwordx4 v134, s[30:31]
	s_add_i32 m0, s54, 0x2000
	s_add_u32 s54, s30, 0x80000
	s_addc_u32 s55, s31, 0
	s_add_i32 s56, s56, s19
	global_load_lds_dwordx4 v130, s[30:31]
	s_mov_b32 m0, s56
	s_add_u32 s100, s34, 0x80
	s_addc_u32 s101, s35, 0
	global_load_lds_dwordx4 v134, s[54:55]
	s_add_i32 m0, s56, 0x2000
	s_nop 0
	global_load_lds_dwordx4 v130, s[54:55]
	s_mov_b32 m0, s38
	s_nop 0
	global_load_lds_dwordx4 v136, s[34:35]
	s_waitcnt vmcnt(7)
	s_waitcnt lgkmcnt(0)
	s_barrier
	s_setprio 1
	v_mfma_f32_16x16x32_bf16 v[62:65], v[148:151], v[180:183], v[62:65]
	v_mfma_f32_16x16x32_bf16 v[58:61], v[156:159], v[180:183], v[58:61]
	v_mfma_f32_16x16x32_bf16 v[54:57], v[148:151], v[188:191], v[54:57]
	v_mfma_f32_16x16x32_bf16 v[46:49], v[156:159], v[188:191], v[46:49]
	v_mfma_f32_16x16x32_bf16 v[38:41], v[148:151], v[196:199], v[38:41]
	v_mfma_f32_16x16x32_bf16 v[30:33], v[156:159], v[196:199], v[30:33]
	v_mfma_f32_16x16x32_bf16 v[22:25], v[148:151], v[208:211], v[22:25]
	v_mfma_f32_16x16x32_bf16 v[12:15], v[156:159], v[208:211], v[12:15]
	v_mfma_f32_16x16x32_bf16 v[62:65], v[152:155], v[184:187], v[62:65]
	v_mfma_f32_16x16x32_bf16 v[58:61], v[160:163], v[184:187], v[58:61]
	v_mfma_f32_16x16x32_bf16 v[54:57], v[152:155], v[192:195], v[54:57]
	v_mfma_f32_16x16x32_bf16 v[46:49], v[160:163], v[192:195], v[46:49]
	v_mfma_f32_16x16x32_bf16 v[38:41], v[152:155], v[200:203], v[38:41]
	v_mfma_f32_16x16x32_bf16 v[30:33], v[160:163], v[200:203], v[30:33]
	v_mfma_f32_16x16x32_bf16 v[22:25], v[152:155], v[212:215], v[22:25]
	v_mfma_f32_16x16x32_bf16 v[12:15], v[160:163], v[212:215], v[12:15]
	s_setprio 0
	s_setprio 1
	v_mfma_f32_16x16x32_bf16 v[50:53], v[164:167], v[180:183], v[50:53]
	v_mfma_f32_16x16x32_bf16 v[42:45], v[172:175], v[180:183], v[42:45]
	v_mfma_f32_16x16x32_bf16 v[34:37], v[164:167], v[188:191], v[34:37]
	v_mfma_f32_16x16x32_bf16 v[26:29], v[172:175], v[188:191], v[26:29]
	v_mfma_f32_16x16x32_bf16 v[16:19], v[164:167], v[196:199], v[16:19]
	v_mfma_f32_16x16x32_bf16 v[8:11], v[172:175], v[196:199], v[8:11]
	v_mfma_f32_16x16x32_bf16 v[4:7], v[164:167], v[208:211], v[4:7]
	v_mfma_f32_16x16x32_bf16 v[0:3], v[172:175], v[208:211], v[0:3]
	v_mfma_f32_16x16x32_bf16 v[50:53], v[168:171], v[184:187], v[50:53]
	v_mfma_f32_16x16x32_bf16 v[42:45], v[176:179], v[184:187], v[42:45]
	v_mfma_f32_16x16x32_bf16 v[34:37], v[168:171], v[192:195], v[34:37]
	v_mfma_f32_16x16x32_bf16 v[26:29], v[176:179], v[192:195], v[26:29]
	v_mfma_f32_16x16x32_bf16 v[16:19], v[168:171], v[200:203], v[16:19]
	v_mfma_f32_16x16x32_bf16 v[8:11], v[176:179], v[200:203], v[8:11]
	v_mfma_f32_16x16x32_bf16 v[4:7], v[168:171], v[212:215], v[4:7]
	v_mfma_f32_16x16x32_bf16 v[0:3], v[176:179], v[212:215], v[0:3]
	s_setprio 0
	s_barrier
; #define PG8_STAGE(bufoff, gbase, voff) do { _Pragma("unroll") for (int _i = 0; _i < 2; ++_i) \
;         __builtin_amdgcn_global_load_lds((const unsigned*)((const char*)(gbase) + (voff)[_i]), (PG8_LAS unsigned*)(lds + (bufoff) + ldsw + _i * 8192), 16, 0, 0); } while (0)
; #define PG8_LDA(dst, b, h) do { _Pragma("unroll") for (int m = 0; m < 4; ++m) _Pragma("unroll") for (int k = 0; k < 2; ++k) dst[m][k] = *(const PG8_LAS bf16x8*)(lds + PG8_SA(b, h) + aoff + m * 2048 + k * 1024); } while (0)
; #define PG8_LDB(dst, b, h) do { _Pragma("unroll") for (int n = 0; n < 2; ++n) _Pragma("unroll") for (int k = 0; k < 2; ++k) dst[n][k] = *(const PG8_LAS bf16x8*)(lds + PG8_SB(b, h) + boff + n * 2048 + k * 1024); } while (0)
; #define PG8_MMA(ai, bj, At, Bt) do { __builtin_amdgcn_s_setprio(1); _Pragma("unroll") for (int m = 0; m < 4; ++m) _Pragma("unroll") for (int n = 0; n < 2; ++n) _Pragma("unroll") for (int k = 0; k < 2; ++k) \
;         acc[ai][bj][m][n] = __builtin_amdgcn_mfma_f32_16x16x32_bf16(Bt[n][k], At[m][k], acc[ai][bj][m][n], 0, 0, 0); __builtin_amdgcn_s_setprio(0); } while (0)
; #define PG8_WAIT_V(n) asm volatile("s_waitcnt vmcnt(" #n ")" ::: "memory")
; #define PG8_WAIT_L(n) asm volatile("s_waitcnt lgkmcnt(" #n ")" ::: "memory")
; #define PG8_BAR __builtin_amdgcn_s_barrier()
; #define PG8_SCHED __builtin_amdgcn_sched_barrier(0)
; template <class Epi, class Sched, bool ALIGN_EPI = false, bool SP2 = false>
; __device__ __forceinline__ void gemm_phase(PG8_LAS unsigned char* lds, const Gemm g, const Sched& S, const Epi& E, const int tid_in) {
;     ...
;         for (int t = 0; t < nt; t += 2) {
;     ...
;             PG8_LDB(B0, 1, 0); PG8_LDB(B1, 1, 1); PG8_SCHED; PG8_LDA(At, 1, 0); PG8_STAGE(PG8_SA(0, 1), a2 + hstep, voffA);
;             PG8_WAIT_V(8); PG8_WAIT_L(0); PG8_BAR; PG8_MMA(0, 0, At, B0); PG8_MMA(0, 1, At, B1); PG8_BAR; PG8_SCHED;
;             PG8_LDA(At, 1, 1); PG8_STAGE(PG8_SB(1, 0), b3, voffB); PG8_STAGE(PG8_SB(1, 1), b3 + hstep, voffB); PG8_STAGE(PG8_SA(1, 0), a3, voffA);
;             PG8_WAIT_V(8); PG8_WAIT_L(0); PG8_BAR; PG8_MMA(1, 0, At, B0); PG8_MMA(1, 1, At, B1); PG8_BAR; PG8_SCHED;
	s_add_i32 s54, 0, 0x18000
	s_add_i32 s55, 0, 0x1c000
	v_add_u32_e32 v160, s54, v21
	v_add_u32_e32 v176, s55, v21
	ds_read_b128 v[148:151], v160
	ds_read_b128 v[152:155], v160 offset:1024
	ds_read_b128 v[156:159], v160 offset:2048
	ds_read_b128 v[160:163], v160 offset:3072
	ds_read_b128 v[164:167], v176
	ds_read_b128 v[168:171], v176 offset:1024
	ds_read_b128 v[172:175], v176 offset:2048
	ds_read_b128 v[176:179], v176 offset:3072
	s_mov_b32 m0, s39
	s_nop 0
	global_load_lds_dwordx4 v132, s[34:35]
	s_add_u32 s34, s34, 0x80000
	s_addc_u32 s35, s35, 0
	s_mov_b32 m0, s42
	ds_read_b128 v[180:183], v147 offset:32768
	ds_read_b128 v[184:187], v147 offset:33792
	ds_read_b128 v[188:191], v147 offset:34816
	ds_read_b128 v[192:195], v147 offset:35840
	ds_read_b128 v[196:199], v147 offset:36864
	ds_read_b128 v[200:203], v147 offset:37888
	ds_read_b128 v[208:211], v147 offset:38912
	ds_read_b128 v[212:215], v147 offset:39936
	global_load_lds_dwordx4 v136, s[34:35]
	s_mov_b32 m0, s43
	s_nop 0
	global_load_lds_dwordx4 v132, s[34:35]
	s_waitcnt vmcnt(8)
	s_waitcnt lgkmcnt(0)
	s_barrier
	s_setprio 1
	v_mfma_f32_16x16x32_bf16 v[126:129], v[148:151], v[180:183], v[126:129]
	v_mfma_f32_16x16x32_bf16 v[122:125], v[156:159], v[180:183], v[122:125]
	v_mfma_f32_16x16x32_bf16 v[118:121], v[148:151], v[188:191], v[118:121]
	v_mfma_f32_16x16x32_bf16 v[110:113], v[156:159], v[188:191], v[110:113]
	v_mfma_f32_16x16x32_bf16 v[102:105], v[148:151], v[196:199], v[102:105]
	v_mfma_f32_16x16x32_bf16 v[94:97], v[156:159], v[196:199], v[94:97]
	v_mfma_f32_16x16x32_bf16 v[86:89], v[148:151], v[208:211], v[86:89]
	v_mfma_f32_16x16x32_bf16 v[78:81], v[156:159], v[208:211], v[78:81]
	v_mfma_f32_16x16x32_bf16 v[126:129], v[152:155], v[184:187], v[126:129]
	v_mfma_f32_16x16x32_bf16 v[122:125], v[160:163], v[184:187], v[122:125]
	v_mfma_f32_16x16x32_bf16 v[118:121], v[152:155], v[192:195], v[118:121]
	v_mfma_f32_16x16x32_bf16 v[110:113], v[160:163], v[192:195], v[110:113]
	v_mfma_f32_16x16x32_bf16 v[102:105], v[152:155], v[200:203], v[102:105]
	v_mfma_f32_16x16x32_bf16 v[94:97], v[160:163], v[200:203], v[94:97]
	v_mfma_f32_16x16x32_bf16 v[86:89], v[152:155], v[212:215], v[86:89]
	v_mfma_f32_16x16x32_bf16 v[78:81], v[160:163], v[212:215], v[78:81]
	s_setprio 0
	s_setprio 1
	v_mfma_f32_16x16x32_bf16 v[114:117], v[164:167], v[180:183], v[114:117]
	v_mfma_f32_16x16x32_bf16 v[106:109], v[172:175], v[180:183], v[106:109]
	v_mfma_f32_16x16x32_bf16 v[98:101], v[164:167], v[188:191], v[98:101]
	v_mfma_f32_16x16x32_bf16 v[90:93], v[172:175], v[188:191], v[90:93]
	v_mfma_f32_16x16x32_bf16 v[82:85], v[164:167], v[196:199], v[82:85]
	v_mfma_f32_16x16x32_bf16 v[74:77], v[172:175], v[196:199], v[74:77]
	v_mfma_f32_16x16x32_bf16 v[70:73], v[164:167], v[208:211], v[70:73]
	v_mfma_f32_16x16x32_bf16 v[66:69], v[172:175], v[208:211], v[66:69]
	v_mfma_f32_16x16x32_bf16 v[114:117], v[168:171], v[184:187], v[114:117]
	v_mfma_f32_16x16x32_bf16 v[106:109], v[176:179], v[184:187], v[106:109]
	v_mfma_f32_16x16x32_bf16 v[98:101], v[168:171], v[192:195], v[98:101]
	v_mfma_f32_16x16x32_bf16 v[90:93], v[176:179], v[192:195], v[90:93]
	v_mfma_f32_16x16x32_bf16 v[82:85], v[168:171], v[200:203], v[82:85]
	v_mfma_f32_16x16x32_bf16 v[74:77], v[176:179], v[200:203], v[74:77]
	v_mfma_f32_16x16x32_bf16 v[70:73], v[168:171], v[212:215], v[70:73]
	v_mfma_f32_16x16x32_bf16 v[66:69], v[176:179], v[212:215], v[66:69]
	s_setprio 0
	s_barrier
	s_add_i32 s34, s54, s19
	s_mov_b32 m0, s34
	ds_read_b128 v[180:183], v147 offset:49152
	ds_read_b128 v[184:187], v147 offset:50176
	ds_read_b128 v[188:191], v147 offset:51200
	ds_read_b128 v[192:195], v147 offset:52224
	ds_read_b128 v[196:199], v147 offset:53248
	ds_read_b128 v[200:203], v147 offset:54272
	ds_read_b128 v[208:211], v147 offset:55296
	ds_read_b128 v[212:215], v147 offset:56320
	global_load_lds_dwordx4 v134, s[98:99]
	s_add_i32 m0, s34, 0x2000
	s_add_u32 s30, s30, 0x80080
	s_addc_u32 s31, s31, 0
	s_add_i32 s34, s55, s19
	global_load_lds_dwordx4 v130, s[98:99]
	s_mov_b32 m0, s34
	s_nop 0
	global_load_lds_dwordx4 v134, s[30:31]
	s_add_i32 m0, s34, 0x2000
	s_nop 0
	global_load_lds_dwordx4 v130, s[30:31]
	s_mov_b32 m0, s44
	s_nop 0
	global_load_lds_dwordx4 v136, s[100:101]
	s_waitcnt vmcnt(7)
	s_waitcnt lgkmcnt(0)
	s_barrier
	s_setprio 1
	v_mfma_f32_16x16x32_bf16 v[62:65], v[148:151], v[180:183], v[62:65]
	v_mfma_f32_16x16x32_bf16 v[58:61], v[156:159], v[180:183], v[58:61]
	v_mfma_f32_16x16x32_bf16 v[54:57], v[148:151], v[188:191], v[54:57]
	v_mfma_f32_16x16x32_bf16 v[46:49], v[156:159], v[188:191], v[46:49]
	v_mfma_f32_16x16x32_bf16 v[38:41], v[148:151], v[196:199], v[38:41]
	v_mfma_f32_16x16x32_bf16 v[30:33], v[156:159], v[196:199], v[30:33]
	v_mfma_f32_16x16x32_bf16 v[22:25], v[148:151], v[208:211], v[22:25]
	v_mfma_f32_16x16x32_bf16 v[12:15], v[156:159], v[208:211], v[12:15]
	v_mfma_f32_16x16x32_bf16 v[62:65], v[152:155], v[184:187], v[62:65]
	v_mfma_f32_16x16x32_bf16 v[58:61], v[160:163], v[184:187], v[58:61]
	v_mfma_f32_16x16x32_bf16 v[54:57], v[152:155], v[192:195], v[54:57]
	v_mfma_f32_16x16x32_bf16 v[46:49], v[160:163], v[192:195], v[46:49]
	v_mfma_f32_16x16x32_bf16 v[38:41], v[152:155], v[200:203], v[38:41]
	v_mfma_f32_16x16x32_bf16 v[30:33], v[160:163], v[200:203], v[30:33]
	v_mfma_f32_16x16x32_bf16 v[22:25], v[152:155], v[212:215], v[22:25]
	v_mfma_f32_16x16x32_bf16 v[12:15], v[160:163], v[212:215], v[12:15]
	s_setprio 0
	s_setprio 1
	v_mfma_f32_16x16x32_bf16 v[50:53], v[164:167], v[180:183], v[50:53]
	v_mfma_f32_16x16x32_bf16 v[42:45], v[172:175], v[180:183], v[42:45]
	v_mfma_f32_16x16x32_bf16 v[34:37], v[164:167], v[188:191], v[34:37]
	v_mfma_f32_16x16x32_bf16 v[26:29], v[172:175], v[188:191], v[26:29]
	v_mfma_f32_16x16x32_bf16 v[16:19], v[164:167], v[196:199], v[16:19]
	v_mfma_f32_16x16x32_bf16 v[8:11], v[172:175], v[196:199], v[8:11]
	v_mfma_f32_16x16x32_bf16 v[4:7], v[164:167], v[208:211], v[4:7]
	v_mfma_f32_16x16x32_bf16 v[0:3], v[172:175], v[208:211], v[0:3]
	v_mfma_f32_16x16x32_bf16 v[50:53], v[168:171], v[184:187], v[50:53]
	v_mfma_f32_16x16x32_bf16 v[42:45], v[176:179], v[184:187], v[42:45]
	v_mfma_f32_16x16x32_bf16 v[34:37], v[168:171], v[192:195], v[34:37]
	v_mfma_f32_16x16x32_bf16 v[26:29], v[176:179], v[192:195], v[26:29]
	v_mfma_f32_16x16x32_bf16 v[16:19], v[168:171], v[200:203], v[16:19]
	v_mfma_f32_16x16x32_bf16 v[8:11], v[176:179], v[200:203], v[8:11]
	v_mfma_f32_16x16x32_bf16 v[4:7], v[168:171], v[212:215], v[4:7]
	v_mfma_f32_16x16x32_bf16 v[0:3], v[176:179], v[212:215], v[0:3]
	s_setprio 0
	s_barrier
	s_add_i32 s53, s53, 2
	s_add_u32 s28, s28, 0x100
	s_addc_u32 s29, s29, 0
	s_add_u32 s51, s51, 0x100
	s_addc_u32 s52, s52, 0
	s_cmp_gt_u32 s53, 29
	s_cbranch_scc0 .LBB0_394
	s_and_b64 vcc, exec, s[6:7]
	v_readlane_b32 s52, v255, 9
	v_readlane_b32 s53, v255, 10
	s_cbranch_vccz .LBB0_397
	s_barrier

; #define PG8_STAGE(bufoff, gbase, voff) do { _Pragma("unroll") for (int _i = 0; _i < 2; ++_i) \
;         __builtin_amdgcn_global_load_lds((const unsigned*)((const char*)(gbase) + (voff)[_i]), (PG8_LAS unsigned*)(lds + (bufoff) + ldsw + _i * 8192), 16, 0, 0); } while (0)
; #define PG8_LDA(dst, b, h) do { _Pragma("unroll") for (int m = 0; m < 4; ++m) _Pragma("unroll") for (int k = 0; k < 2; ++k) dst[m][k] = *(const PG8_LAS bf16x8*)(lds + PG8_SA(b, h) + aoff + m * 2048 + k * 1024); } while (0)
; #define PG8_LDB(dst, b, h) do { _Pragma("unroll") for (int n = 0; n < 2; ++n) _Pragma("unroll") for (int k = 0; k < 2; ++k) dst[n][k] = *(const PG8_LAS bf16x8*)(lds + PG8_SB(b, h) + boff + n * 2048 + k * 1024); } while (0)
; template <class Epi, class Sched, bool ALIGN_EPI = false, bool SP2 = false>
; __device__ __forceinline__ void gemm_phase(PG8_LAS unsigned char* lds, const Gemm g, const Sched& S, const Epi& E, const int tid_in) {
;     ...
;             const bool last = (t == nt - 2);
;             const char* a1 = cA + (size_t)(t + 1) * kstep;
;             const char* a2 = last ? nA : cA + (size_t)(t + 2) * kstep; const char* b2 = last ? nB : cB + (size_t)(t + 2) * kstep;
;             const char* a3 = a2 + kstep; const char* b3 = b2 + kstep;
;             if (last && has_next) S.a_ready(nxt);
;             if constexpr (SP2) {
;             PG8_LDB(B0, 0, 0); PG8_LDB(B1, 0, 1); PG8_SCHED; PG8_LDA(At, 0, 0); PG8_STAGE(PG8_SA(1, 1), a1 + hstep, voffA);
;             PG8_WAIT_V(8); PG8_WAIT_L(0); PG8_BAR; PG8_MMA(0, 0, At, B0); PG8_MMA(0, 1, At, B1); PG8_BAR; PG8_SCHED;
;             PG8_LDA(At, 0, 1); PG8_STAGE(PG8_SB(0, 0), b2, voffB); PG8_STAGE(PG8_SB(0, 1), b2 + hstep, voffB); PG8_STAGE(PG8_SA(0, 0), a2, voffA);
;             PG8_WAIT_V(8); PG8_WAIT_L(0); PG8_BAR; PG8_MMA(1, 0, At, B0); PG8_MMA(1, 1, At, B1); PG8_BAR; PG8_SCHED;
;             PG8_LDB(B0, 1, 0); PG8_LDB(B1, 1, 1); PG8_SCHED; PG8_LDA(At, 1, 0); PG8_STAGE(PG8_SA(0, 1), a2 + hstep, voffA);
;             PG8_WAIT_V(8); PG8_WAIT_L(0); PG8_BAR; PG8_MMA(0, 0, At, B0); PG8_MMA(0, 1, At, B1); PG8_BAR; PG8_SCHED;
;             PG8_LDA(At, 1, 1); PG8_STAGE(PG8_SB(1, 0), b3, voffB); PG8_STAGE(PG8_SB(1, 1), b3 + hstep, voffB); PG8_STAGE(PG8_SA(1, 0), a3, voffA);
;             PG8_WAIT_V(8); PG8_WAIT_L(0); PG8_BAR; PG8_MMA(1, 0, At, B0); PG8_MMA(1, 1, At, B1); PG8_BAR; PG8_SCHED;
.LBB0_412:
	s_mov_b32 m0, s49
	s_nop 0
	global_load_lds_dwordx4 v150, s[100:101]
	s_add_u32 s38, s34, 0xfff80080
	s_addc_u32 s39, s35, -1
	s_add_i32 s59, 0, 0x10000
	s_cmp_eq_u32 s58, 28
	s_cselect_b32 s43, s27, s39
	s_cselect_b32 s42, s54, s38
	s_cselect_b32 s39, s7, s57
	s_cselect_b32 s38, s55, s56
	s_add_i32 s62, 0, 0x14000
	v_add_u32_e32 v78, s59, v162
	v_add_u32_e32 v160, s62, v162
	ds_read_b128 v[66:69], v78
	ds_read_b128 v[70:73], v78 offset:1024
	ds_read_b128 v[74:77], v78 offset:2048
	ds_read_b128 v[78:81], v78 offset:3072
	ds_read_b128 v[166:169], v160
	ds_read_b128 v[170:173], v160 offset:1024
	ds_read_b128 v[174:177], v160 offset:2048
	ds_read_b128 v[178:181], v160 offset:3072
	s_add_i32 m0, s44, 0xc000
	ds_read_b128 v[182:185], v165
	ds_read_b128 v[186:189], v165 offset:1024
	ds_read_b128 v[190:193], v165 offset:2048
	ds_read_b128 v[194:197], v165 offset:3072
	ds_read_b128 v[198:201], v165 offset:4096
	ds_read_b128 v[202:205], v165 offset:5120
	ds_read_b128 v[208:211], v165 offset:6144
	ds_read_b128 v[212:215], v165 offset:7168
	global_load_lds_dwordx4 v156, s[34:35]
	s_add_i32 m0, s44, 0xe000
	s_nop 0
	global_load_lds_dwordx4 v158, s[34:35]
	s_waitcnt vmcnt(8)
	s_waitcnt lgkmcnt(0)
	s_barrier
	s_setprio 1
	v_mfma_f32_16x16x32_bf16 v[142:145], v[66:69], v[182:185], v[142:145]
	v_mfma_f32_16x16x32_bf16 v[138:141], v[74:77], v[182:185], v[138:141]
	v_mfma_f32_16x16x32_bf16 v[126:129], v[66:69], v[190:193], v[126:129]
	v_mfma_f32_16x16x32_bf16 v[122:125], v[74:77], v[190:193], v[122:125]
	v_mfma_f32_16x16x32_bf16 v[110:113], v[66:69], v[198:201], v[110:113]
	v_mfma_f32_16x16x32_bf16 v[106:109], v[74:77], v[198:201], v[106:109]
	v_mfma_f32_16x16x32_bf16 v[94:97], v[66:69], v[208:211], v[94:97]
	v_mfma_f32_16x16x32_bf16 v[90:93], v[74:77], v[208:211], v[90:93]
	v_mfma_f32_16x16x32_bf16 v[142:145], v[70:73], v[186:189], v[142:145]
	v_mfma_f32_16x16x32_bf16 v[138:141], v[78:81], v[186:189], v[138:141]
	v_mfma_f32_16x16x32_bf16 v[126:129], v[70:73], v[194:197], v[126:129]
	v_mfma_f32_16x16x32_bf16 v[122:125], v[78:81], v[194:197], v[122:125]
	v_mfma_f32_16x16x32_bf16 v[110:113], v[70:73], v[202:205], v[110:113]
	v_mfma_f32_16x16x32_bf16 v[106:109], v[78:81], v[202:205], v[106:109]
	v_mfma_f32_16x16x32_bf16 v[94:97], v[70:73], v[212:215], v[94:97]
	v_mfma_f32_16x16x32_bf16 v[90:93], v[78:81], v[212:215], v[90:93]
	s_setprio 0
	s_setprio 1
	v_mfma_f32_16x16x32_bf16 v[134:137], v[166:169], v[182:185], v[134:137]
	v_mfma_f32_16x16x32_bf16 v[130:133], v[174:177], v[182:185], v[130:133]
	v_mfma_f32_16x16x32_bf16 v[118:121], v[166:169], v[190:193], v[118:121]
	v_mfma_f32_16x16x32_bf16 v[114:117], v[174:177], v[190:193], v[114:117]
	v_mfma_f32_16x16x32_bf16 v[102:105], v[166:169], v[198:201], v[102:105]
	v_mfma_f32_16x16x32_bf16 v[98:101], v[174:177], v[198:201], v[98:101]
	v_mfma_f32_16x16x32_bf16 v[86:89], v[166:169], v[208:211], v[86:89]
	v_mfma_f32_16x16x32_bf16 v[82:85], v[174:177], v[208:211], v[82:85]
	v_mfma_f32_16x16x32_bf16 v[134:137], v[170:173], v[186:189], v[134:137]
	v_mfma_f32_16x16x32_bf16 v[130:133], v[178:181], v[186:189], v[130:133]
	v_mfma_f32_16x16x32_bf16 v[118:121], v[170:173], v[194:197], v[118:121]
	v_mfma_f32_16x16x32_bf16 v[114:117], v[178:181], v[194:197], v[114:117]
	v_mfma_f32_16x16x32_bf16 v[102:105], v[170:173], v[202:205], v[102:105]
	v_mfma_f32_16x16x32_bf16 v[98:101], v[178:181], v[202:205], v[98:101]
	v_mfma_f32_16x16x32_bf16 v[86:89], v[170:173], v[212:215], v[86:89]
	v_mfma_f32_16x16x32_bf16 v[82:85], v[178:181], v[212:215], v[82:85]
	s_setprio 0
	s_barrier
	s_add_i32 s59, s59, s19
	s_add_u32 s98, s38, 0x80
	s_addc_u32 s99, s39, 0
	s_mov_b32 m0, s59
	ds_read_b128 v[182:185], v165 offset:16384
	ds_read_b128 v[186:189], v165 offset:17408
	ds_read_b128 v[190:193], v165 offset:18432
	ds_read_b128 v[194:197], v165 offset:19456
	ds_read_b128 v[198:201], v165 offset:20480
	ds_read_b128 v[202:205], v165 offset:21504
	ds_read_b128 v[208:211], v165 offset:22528
	ds_read_b128 v[212:215], v165 offset:23552
	global_load_lds_dwordx4 v148, s[38:39]
	s_add_i32 m0, s59, 0x2000
	s_add_u32 s60, s38, 0x80000
	s_addc_u32 s61, s39, 0
	s_add_i32 s59, s62, s19
	global_load_lds_dwordx4 v152, s[38:39]
	s_mov_b32 m0, s59
	s_add_u32 s100, s42, 0x80
	s_addc_u32 s101, s43, 0
	global_load_lds_dwordx4 v148, s[60:61]
	s_add_i32 m0, s59, 0x2000
	s_nop 0
	global_load_lds_dwordx4 v152, s[60:61]
	s_mov_b32 m0, s44
	s_nop 0
	global_load_lds_dwordx4 v146, s[42:43]
	s_waitcnt vmcnt(7)
	s_waitcnt lgkmcnt(0)
	s_barrier
	s_setprio 1
	v_mfma_f32_16x16x32_bf16 v[62:65], v[66:69], v[182:185], v[62:65]
	v_mfma_f32_16x16x32_bf16 v[58:61], v[74:77], v[182:185], v[58:61]
	v_mfma_f32_16x16x32_bf16 v[46:49], v[66:69], v[190:193], v[46:49]
	v_mfma_f32_16x16x32_bf16 v[42:45], v[74:77], v[190:193], v[42:45]
	v_mfma_f32_16x16x32_bf16 v[30:33], v[66:69], v[198:201], v[30:33]
	v_mfma_f32_16x16x32_bf16 v[26:29], v[74:77], v[198:201], v[26:29]
	v_mfma_f32_16x16x32_bf16 v[12:15], v[66:69], v[208:211], v[12:15]
	v_mfma_f32_16x16x32_bf16 v[8:11], v[74:77], v[208:211], v[8:11]
	v_mfma_f32_16x16x32_bf16 v[62:65], v[70:73], v[186:189], v[62:65]
	v_mfma_f32_16x16x32_bf16 v[58:61], v[78:81], v[186:189], v[58:61]
	v_mfma_f32_16x16x32_bf16 v[46:49], v[70:73], v[194:197], v[46:49]
	v_mfma_f32_16x16x32_bf16 v[42:45], v[78:81], v[194:197], v[42:45]
	v_mfma_f32_16x16x32_bf16 v[30:33], v[70:73], v[202:205], v[30:33]
	v_mfma_f32_16x16x32_bf16 v[26:29], v[78:81], v[202:205], v[26:29]
	v_mfma_f32_16x16x32_bf16 v[12:15], v[70:73], v[212:215], v[12:15]
	v_mfma_f32_16x16x32_bf16 v[8:11], v[78:81], v[212:215], v[8:11]
	s_setprio 0
	s_setprio 1
	v_mfma_f32_16x16x32_bf16 v[54:57], v[166:169], v[182:185], v[54:57]
	v_mfma_f32_16x16x32_bf16 v[50:53], v[174:177], v[182:185], v[50:53]
	v_mfma_f32_16x16x32_bf16 v[38:41], v[166:169], v[190:193], v[38:41]
	v_mfma_f32_16x16x32_bf16 v[34:37], v[174:177], v[190:193], v[34:37]
	v_mfma_f32_16x16x32_bf16 v[22:25], v[166:169], v[198:201], v[22:25]
	v_mfma_f32_16x16x32_bf16 v[16:19], v[174:177], v[198:201], v[16:19]
	v_mfma_f32_16x16x32_bf16 v[4:7], v[166:169], v[208:211], v[4:7]
	v_mfma_f32_16x16x32_bf16 v[0:3], v[174:177], v[208:211], v[0:3]
	v_mfma_f32_16x16x32_bf16 v[54:57], v[170:173], v[186:189], v[54:57]
	v_mfma_f32_16x16x32_bf16 v[50:53], v[178:181], v[186:189], v[50:53]
	v_mfma_f32_16x16x32_bf16 v[38:41], v[170:173], v[194:197], v[38:41]
	v_mfma_f32_16x16x32_bf16 v[34:37], v[178:181], v[194:197], v[34:37]
	v_mfma_f32_16x16x32_bf16 v[22:25], v[170:173], v[202:205], v[22:25]
	v_mfma_f32_16x16x32_bf16 v[16:19], v[178:181], v[202:205], v[16:19]
	v_mfma_f32_16x16x32_bf16 v[4:7], v[170:173], v[212:215], v[4:7]
	v_mfma_f32_16x16x32_bf16 v[0:3], v[178:181], v[212:215], v[0:3]
	s_setprio 0
	s_barrier
; #define PG8_STAGE(bufoff, gbase, voff) do { _Pragma("unroll") for (int _i = 0; _i < 2; ++_i) \
;         __builtin_amdgcn_global_load_lds((const unsigned*)((const char*)(gbase) + (voff)[_i]), (PG8_LAS unsigned*)(lds + (bufoff) + ldsw + _i * 8192), 16, 0, 0); } while (0)
; #define PG8_LDA(dst, b, h) do { _Pragma("unroll") for (int m = 0; m < 4; ++m) _Pragma("unroll") for (int k = 0; k < 2; ++k) dst[m][k] = *(const PG8_LAS bf16x8*)(lds + PG8_SA(b, h) + aoff + m * 2048 + k * 1024); } while (0)
; #define PG8_LDB(dst, b, h) do { _Pragma("unroll") for (int n = 0; n < 2; ++n) _Pragma("unroll") for (int k = 0; k < 2; ++k) dst[n][k] = *(const PG8_LAS bf16x8*)(lds + PG8_SB(b, h) + boff + n * 2048 + k * 1024); } while (0)
; #define PG8_MMA(ai, bj, At, Bt) do { __builtin_amdgcn_s_setprio(1); _Pragma("unroll") for (int m = 0; m < 4; ++m) _Pragma("unroll") for (int n = 0; n < 2; ++n) _Pragma("unroll") for (int k = 0; k < 2; ++k) \
;         acc[ai][bj][m][n] = __builtin_amdgcn_mfma_f32_16x16x32_bf16(Bt[n][k], At[m][k], acc[ai][bj][m][n], 0, 0, 0); __builtin_amdgcn_s_setprio(0); } while (0)
; #define PG8_WAIT_V(n) asm volatile("s_waitcnt vmcnt(" #n ")" ::: "memory")
; #define PG8_WAIT_L(n) asm volatile("s_waitcnt lgkmcnt(" #n ")" ::: "memory")
; #define PG8_BAR __builtin_amdgcn_s_barrier()
; #define PG8_SCHED __builtin_amdgcn_sched_barrier(0)
; template <class Epi, class Sched, bool ALIGN_EPI = false, bool SP2 = false>
; __device__ __forceinline__ void gemm_phase(PG8_LAS unsigned char* lds, const Gemm g, const Sched& S, const Epi& E, const int tid_in) {
;     ...
;         for (int t = 0; t < nt; t += 2) {
;     ...
;             PG8_LDB(B0, 1, 0); PG8_LDB(B1, 1, 1); PG8_SCHED; PG8_LDA(At, 1, 0); PG8_STAGE(PG8_SA(0, 1), a2 + hstep, voffA);
;             PG8_WAIT_V(8); PG8_WAIT_L(0); PG8_BAR; PG8_MMA(0, 0, At, B0); PG8_MMA(0, 1, At, B1); PG8_BAR; PG8_SCHED;
;             PG8_LDA(At, 1, 1); PG8_STAGE(PG8_SB(1, 0), b3, voffB); PG8_STAGE(PG8_SB(1, 1), b3 + hstep, voffB); PG8_STAGE(PG8_SA(1, 0), a3, voffA);
;             PG8_WAIT_V(8); PG8_WAIT_L(0); PG8_BAR; PG8_MMA(1, 0, At, B0); PG8_MMA(1, 1, At, B1); PG8_BAR; PG8_SCHED;
	s_add_i32 s59, 0, 0x18000
	s_add_i32 s60, 0, 0x1c000
	v_add_u32_e32 v78, s59, v162
	v_add_u32_e32 v178, s60, v162
	ds_read_b128 v[66:69], v78
	ds_read_b128 v[70:73], v78 offset:1024
	ds_read_b128 v[74:77], v78 offset:2048
	ds_read_b128 v[78:81], v78 offset:3072
	ds_read_b128 v[166:169], v178
	ds_read_b128 v[170:173], v178 offset:1024
	ds_read_b128 v[174:177], v178 offset:2048
	ds_read_b128 v[178:181], v178 offset:3072
	s_mov_b32 m0, s45
	s_nop 0
	global_load_lds_dwordx4 v150, s[42:43]
	s_add_u32 s42, s42, 0x80000
	s_addc_u32 s43, s43, 0
	s_mov_b32 m0, s46
	ds_read_b128 v[182:185], v165 offset:32768
	ds_read_b128 v[186:189], v165 offset:33792
	ds_read_b128 v[190:193], v165 offset:34816
	ds_read_b128 v[194:197], v165 offset:35840
	ds_read_b128 v[198:201], v165 offset:36864
	ds_read_b128 v[202:205], v165 offset:37888
	ds_read_b128 v[208:211], v165 offset:38912
	ds_read_b128 v[212:215], v165 offset:39936
	global_load_lds_dwordx4 v146, s[42:43]
	s_mov_b32 m0, s47
	s_nop 0
	global_load_lds_dwordx4 v150, s[42:43]
	s_waitcnt vmcnt(8)
	s_waitcnt lgkmcnt(0)
	s_barrier
	s_setprio 1
	v_mfma_f32_16x16x32_bf16 v[142:145], v[66:69], v[182:185], v[142:145]
	v_mfma_f32_16x16x32_bf16 v[138:141], v[74:77], v[182:185], v[138:141]
	v_mfma_f32_16x16x32_bf16 v[126:129], v[66:69], v[190:193], v[126:129]
	v_mfma_f32_16x16x32_bf16 v[122:125], v[74:77], v[190:193], v[122:125]
	v_mfma_f32_16x16x32_bf16 v[110:113], v[66:69], v[198:201], v[110:113]
	v_mfma_f32_16x16x32_bf16 v[106:109], v[74:77], v[198:201], v[106:109]
	v_mfma_f32_16x16x32_bf16 v[94:97], v[66:69], v[208:211], v[94:97]
	v_mfma_f32_16x16x32_bf16 v[90:93], v[74:77], v[208:211], v[90:93]
	v_mfma_f32_16x16x32_bf16 v[142:145], v[70:73], v[186:189], v[142:145]
	v_mfma_f32_16x16x32_bf16 v[138:141], v[78:81], v[186:189], v[138:141]
	v_mfma_f32_16x16x32_bf16 v[126:129], v[70:73], v[194:197], v[126:129]
	v_mfma_f32_16x16x32_bf16 v[122:125], v[78:81], v[194:197], v[122:125]
	v_mfma_f32_16x16x32_bf16 v[110:113], v[70:73], v[202:205], v[110:113]
	v_mfma_f32_16x16x32_bf16 v[106:109], v[78:81], v[202:205], v[106:109]
	v_mfma_f32_16x16x32_bf16 v[94:97], v[70:73], v[212:215], v[94:97]
	v_mfma_f32_16x16x32_bf16 v[90:93], v[78:81], v[212:215], v[90:93]
	s_setprio 0
	s_setprio 1
	v_mfma_f32_16x16x32_bf16 v[134:137], v[166:169], v[182:185], v[134:137]
	v_mfma_f32_16x16x32_bf16 v[130:133], v[174:177], v[182:185], v[130:133]
	v_mfma_f32_16x16x32_bf16 v[118:121], v[166:169], v[190:193], v[118:121]
	v_mfma_f32_16x16x32_bf16 v[114:117], v[174:177], v[190:193], v[114:117]
	v_mfma_f32_16x16x32_bf16 v[102:105], v[166:169], v[198:201], v[102:105]
	v_mfma_f32_16x16x32_bf16 v[98:101], v[174:177], v[198:201], v[98:101]
	v_mfma_f32_16x16x32_bf16 v[86:89], v[166:169], v[208:211], v[86:89]
	v_mfma_f32_16x16x32_bf16 v[82:85], v[174:177], v[208:211], v[82:85]
	v_mfma_f32_16x16x32_bf16 v[134:137], v[170:173], v[186:189], v[134:137]
	v_mfma_f32_16x16x32_bf16 v[130:133], v[178:181], v[186:189], v[130:133]
	v_mfma_f32_16x16x32_bf16 v[118:121], v[170:173], v[194:197], v[118:121]
	v_mfma_f32_16x16x32_bf16 v[114:117], v[178:181], v[194:197], v[114:117]
	v_mfma_f32_16x16x32_bf16 v[102:105], v[170:173], v[202:205], v[102:105]
	v_mfma_f32_16x16x32_bf16 v[98:101], v[178:181], v[202:205], v[98:101]
	v_mfma_f32_16x16x32_bf16 v[86:89], v[170:173], v[212:215], v[86:89]
	v_mfma_f32_16x16x32_bf16 v[82:85], v[178:181], v[212:215], v[82:85]
	s_setprio 0
	s_barrier
	s_add_i32 s42, s59, s19
	s_mov_b32 m0, s42
	ds_read_b128 v[182:185], v165 offset:49152
	ds_read_b128 v[186:189], v165 offset:50176
	ds_read_b128 v[190:193], v165 offset:51200
	ds_read_b128 v[194:197], v165 offset:52224
	ds_read_b128 v[198:201], v165 offset:53248
	ds_read_b128 v[202:205], v165 offset:54272
	ds_read_b128 v[208:211], v165 offset:55296
	ds_read_b128 v[212:215], v165 offset:56320
	global_load_lds_dwordx4 v148, s[98:99]
	s_add_i32 m0, s42, 0x2000
	s_add_u32 s38, s38, 0x80080
	s_addc_u32 s39, s39, 0
	s_add_i32 s42, s60, s19
	global_load_lds_dwordx4 v152, s[98:99]
	s_mov_b32 m0, s42
	s_nop 0
	global_load_lds_dwordx4 v148, s[38:39]
	s_add_i32 m0, s42, 0x2000
	s_nop 0
	global_load_lds_dwordx4 v152, s[38:39]
	s_mov_b32 m0, s48
	s_nop 0
	global_load_lds_dwordx4 v146, s[100:101]
	s_waitcnt vmcnt(7)
	s_waitcnt lgkmcnt(0)
	s_barrier
	s_setprio 1
	v_mfma_f32_16x16x32_bf16 v[62:65], v[66:69], v[182:185], v[62:65]
	v_mfma_f32_16x16x32_bf16 v[58:61], v[74:77], v[182:185], v[58:61]
	v_mfma_f32_16x16x32_bf16 v[46:49], v[66:69], v[190:193], v[46:49]
	v_mfma_f32_16x16x32_bf16 v[42:45], v[74:77], v[190:193], v[42:45]
	v_mfma_f32_16x16x32_bf16 v[30:33], v[66:69], v[198:201], v[30:33]
	v_mfma_f32_16x16x32_bf16 v[26:29], v[74:77], v[198:201], v[26:29]
	v_mfma_f32_16x16x32_bf16 v[12:15], v[66:69], v[208:211], v[12:15]
	v_mfma_f32_16x16x32_bf16 v[8:11], v[74:77], v[208:211], v[8:11]
	v_mfma_f32_16x16x32_bf16 v[62:65], v[70:73], v[186:189], v[62:65]
	v_mfma_f32_16x16x32_bf16 v[58:61], v[78:81], v[186:189], v[58:61]
	v_mfma_f32_16x16x32_bf16 v[46:49], v[70:73], v[194:197], v[46:49]
	v_mfma_f32_16x16x32_bf16 v[42:45], v[78:81], v[194:197], v[42:45]
	v_mfma_f32_16x16x32_bf16 v[30:33], v[70:73], v[202:205], v[30:33]
	v_mfma_f32_16x16x32_bf16 v[26:29], v[78:81], v[202:205], v[26:29]
	v_mfma_f32_16x16x32_bf16 v[12:15], v[70:73], v[212:215], v[12:15]
	v_mfma_f32_16x16x32_bf16 v[8:11], v[78:81], v[212:215], v[8:11]
	s_setprio 0
	s_setprio 1
	v_mfma_f32_16x16x32_bf16 v[54:57], v[166:169], v[182:185], v[54:57]
	v_mfma_f32_16x16x32_bf16 v[50:53], v[174:177], v[182:185], v[50:53]
	v_mfma_f32_16x16x32_bf16 v[38:41], v[166:169], v[190:193], v[38:41]
	v_mfma_f32_16x16x32_bf16 v[34:37], v[174:177], v[190:193], v[34:37]
	v_mfma_f32_16x16x32_bf16 v[22:25], v[166:169], v[198:201], v[22:25]
	v_mfma_f32_16x16x32_bf16 v[16:19], v[174:177], v[198:201], v[16:19]
	v_mfma_f32_16x16x32_bf16 v[4:7], v[166:169], v[208:211], v[4:7]
	v_mfma_f32_16x16x32_bf16 v[0:3], v[174:177], v[208:211], v[0:3]
	v_mfma_f32_16x16x32_bf16 v[54:57], v[170:173], v[186:189], v[54:57]
	v_mfma_f32_16x16x32_bf16 v[50:53], v[178:181], v[186:189], v[50:53]
	v_mfma_f32_16x16x32_bf16 v[38:41], v[170:173], v[194:197], v[38:41]
	v_mfma_f32_16x16x32_bf16 v[34:37], v[178:181], v[194:197], v[34:37]
	v_mfma_f32_16x16x32_bf16 v[22:25], v[170:173], v[202:205], v[22:25]
	v_mfma_f32_16x16x32_bf16 v[16:19], v[178:181], v[202:205], v[16:19]
	v_mfma_f32_16x16x32_bf16 v[4:7], v[170:173], v[212:215], v[4:7]
	v_mfma_f32_16x16x32_bf16 v[0:3], v[178:181], v[212:215], v[0:3]
	s_setprio 0
	s_barrier
	s_add_i32 s58, s58, 2
	s_add_u32 s34, s34, 0x100
	s_addc_u32 s35, s35, 0
	s_add_u32 s56, s56, 0x100
	s_addc_u32 s57, s57, 0
	s_cmp_gt_u32 s58, 29
	s_cbranch_scc0 .LBB0_412
	s_and_b64 vcc, exec, s[2:3]
	s_cbranch_vccz .LBB0_415
	s_barrier

; #define PG8_STAGE(bufoff, gbase, voff) do { _Pragma("unroll") for (int _i = 0; _i < 2; ++_i) \
;         __builtin_amdgcn_global_load_lds((const unsigned*)((const char*)(gbase) + (voff)[_i]), (PG8_LAS unsigned*)(lds + (bufoff) + ldsw + _i * 8192), 16, 0, 0); } while (0)
; #define PG8_LDA(dst, b, h) do { _Pragma("unroll") for (int m = 0; m < 4; ++m) _Pragma("unroll") for (int k = 0; k < 2; ++k) dst[m][k] = *(const PG8_LAS bf16x8*)(lds + PG8_SA(b, h) + aoff + m * 2048 + k * 1024); } while (0)
; #define PG8_LDB(dst, b, h) do { _Pragma("unroll") for (int n = 0; n < 2; ++n) _Pragma("unroll") for (int k = 0; k < 2; ++k) dst[n][k] = *(const PG8_LAS bf16x8*)(lds + PG8_SB(b, h) + boff + n * 2048 + k * 1024); } while (0)
; template <class Epi, class Sched, bool ALIGN_EPI = false, bool SP2 = false>
; __device__ __forceinline__ void gemm_phase(PG8_LAS unsigned char* lds, const Gemm g, const Sched& S, const Epi& E, const int tid_in) {
;     ...
;             const bool last = (t == nt - 2);
;             const char* a1 = cA + (size_t)(t + 1) * kstep;
;             const char* a2 = last ? nA : cA + (size_t)(t + 2) * kstep; const char* b2 = last ? nB : cB + (size_t)(t + 2) * kstep;
;             const char* a3 = a2 + kstep; const char* b3 = b2 + kstep;
;             if (last && has_next) S.a_ready(nxt);
;             if constexpr (SP2) {
;             PG8_LDB(B0, 0, 0); PG8_LDB(B1, 0, 1); PG8_SCHED; PG8_LDA(At, 0, 0); PG8_STAGE(PG8_SA(1, 1), a1 + hstep, voffA);
;             PG8_WAIT_V(8); PG8_WAIT_L(0); PG8_BAR; PG8_MMA(0, 0, At, B0); PG8_MMA(0, 1, At, B1); PG8_BAR; PG8_SCHED;
;             PG8_LDA(At, 0, 1); PG8_STAGE(PG8_SB(0, 0), b2, voffB); PG8_STAGE(PG8_SB(0, 1), b2 + hstep, voffB); PG8_STAGE(PG8_SA(0, 0), a2, voffA);
;             PG8_WAIT_V(8); PG8_WAIT_L(0); PG8_BAR; PG8_MMA(1, 0, At, B0); PG8_MMA(1, 1, At, B1); PG8_BAR; PG8_SCHED;
;             PG8_LDB(B0, 1, 0); PG8_LDB(B1, 1, 1); PG8_SCHED; PG8_LDA(At, 1, 0); PG8_STAGE(PG8_SA(0, 1), a2 + hstep, voffA);
;             PG8_WAIT_V(8); PG8_WAIT_L(0); PG8_BAR; PG8_MMA(0, 0, At, B0); PG8_MMA(0, 1, At, B1); PG8_BAR; PG8_SCHED;
;             PG8_LDA(At, 1, 1); PG8_STAGE(PG8_SB(1, 0), b3, voffB); PG8_STAGE(PG8_SB(1, 1), b3 + hstep, voffB); PG8_STAGE(PG8_SA(1, 0), a3, voffA);
;             PG8_WAIT_V(8); PG8_WAIT_L(0); PG8_BAR; PG8_MMA(1, 0, At, B0); PG8_MMA(1, 1, At, B1); PG8_BAR; PG8_SCHED;
.LBB0_960:
	s_mov_b32 m0, s48
	s_nop 0
	global_load_lds_dwordx4 v196, s[100:101]
	s_add_u32 s36, s30, s34
	s_addc_u32 s37, s31, s35
	s_add_u32 s36, s36, 0x100
	s_addc_u32 s37, s37, 0
	s_add_u32 s61, s58, s34
	s_addc_u32 s62, s59, s35
	s_add_i32 s63, 0, 0x10000
	s_cmpk_eq_i32 s34, 0xb00
	s_cselect_b32 s41, s27, s37
	s_cselect_b32 s40, s26, s36
	s_cselect_b32 s37, s29, s62
	s_cselect_b32 s36, s28, s61
	s_add_i32 s61, 0, 0x14000
	v_add_u32_e32 v142, s63, v230
	v_add_u32_e32 v158, s61, v230
	ds_read_b128 v[130:133], v142
	ds_read_b128 v[134:137], v142 offset:1024
	ds_read_b128 v[138:141], v142 offset:2048
	ds_read_b128 v[142:145], v142 offset:3072
	ds_read_b128 v[146:149], v158
	ds_read_b128 v[150:153], v158 offset:1024
	ds_read_b128 v[154:157], v158 offset:2048
	ds_read_b128 v[158:161], v158 offset:3072
	v_lshl_add_u64 v[214:215], v[182:183], 0, s[34:35]
	s_add_i32 m0, s42, 0xc000
	ds_read_b128 v[162:165], v233
	ds_read_b128 v[166:169], v233 offset:1024
	ds_read_b128 v[170:173], v233 offset:2048
	ds_read_b128 v[174:177], v233 offset:3072
	ds_read_b128 v[178:181], v233 offset:4096
	ds_read_b128 v[186:189], v233 offset:5120
	ds_read_b128 v[190:193], v233 offset:6144
	ds_read_b128 v[210:213], v233 offset:7168
	global_load_lds_dwordx4 v[214:215], off
	v_lshl_add_u64 v[214:215], v[184:185], 0, s[34:35]
	s_add_i32 m0, s42, 0xe000
	s_nop 0
	global_load_lds_dwordx4 v[214:215], off
	s_waitcnt vmcnt(8)
	s_waitcnt lgkmcnt(0)
	s_barrier
	s_setprio 1
	v_mfma_f32_16x16x32_bf16 v[126:129], v[130:133], v[162:165], v[126:129]
	v_mfma_f32_16x16x32_bf16 v[122:125], v[138:141], v[162:165], v[122:125]
	v_mfma_f32_16x16x32_bf16 v[110:113], v[130:133], v[170:173], v[110:113]
	v_mfma_f32_16x16x32_bf16 v[106:109], v[138:141], v[170:173], v[106:109]
	v_mfma_f32_16x16x32_bf16 v[102:105], v[130:133], v[178:181], v[102:105]
	v_mfma_f32_16x16x32_bf16 v[94:97], v[138:141], v[178:181], v[94:97]
	v_mfma_f32_16x16x32_bf16 v[86:89], v[130:133], v[190:193], v[86:89]
	v_mfma_f32_16x16x32_bf16 v[78:81], v[138:141], v[190:193], v[78:81]
	v_mfma_f32_16x16x32_bf16 v[126:129], v[134:137], v[166:169], v[126:129]
	v_mfma_f32_16x16x32_bf16 v[122:125], v[142:145], v[166:169], v[122:125]
	v_mfma_f32_16x16x32_bf16 v[110:113], v[134:137], v[174:177], v[110:113]
	v_mfma_f32_16x16x32_bf16 v[106:109], v[142:145], v[174:177], v[106:109]
	v_mfma_f32_16x16x32_bf16 v[102:105], v[134:137], v[186:189], v[102:105]
	v_mfma_f32_16x16x32_bf16 v[94:97], v[142:145], v[186:189], v[94:97]
	v_mfma_f32_16x16x32_bf16 v[86:89], v[134:137], v[210:213], v[86:89]
	v_mfma_f32_16x16x32_bf16 v[78:81], v[142:145], v[210:213], v[78:81]
	s_setprio 0
	s_setprio 1
	v_mfma_f32_16x16x32_bf16 v[118:121], v[146:149], v[162:165], v[118:121]
	v_mfma_f32_16x16x32_bf16 v[114:117], v[154:157], v[162:165], v[114:117]
	v_mfma_f32_16x16x32_bf16 v[98:101], v[146:149], v[170:173], v[98:101]
	v_mfma_f32_16x16x32_bf16 v[90:93], v[154:157], v[170:173], v[90:93]
	v_mfma_f32_16x16x32_bf16 v[82:85], v[146:149], v[178:181], v[82:85]
	v_mfma_f32_16x16x32_bf16 v[74:77], v[154:157], v[178:181], v[74:77]
	v_mfma_f32_16x16x32_bf16 v[70:73], v[146:149], v[190:193], v[70:73]
	v_mfma_f32_16x16x32_bf16 v[66:69], v[154:157], v[190:193], v[66:69]
	v_mfma_f32_16x16x32_bf16 v[118:121], v[150:153], v[166:169], v[118:121]
	v_mfma_f32_16x16x32_bf16 v[114:117], v[158:161], v[166:169], v[114:117]
	v_mfma_f32_16x16x32_bf16 v[98:101], v[150:153], v[174:177], v[98:101]
	v_mfma_f32_16x16x32_bf16 v[90:93], v[158:161], v[174:177], v[90:93]
	v_mfma_f32_16x16x32_bf16 v[82:85], v[150:153], v[186:189], v[82:85]
	v_mfma_f32_16x16x32_bf16 v[74:77], v[158:161], v[186:189], v[74:77]
	v_mfma_f32_16x16x32_bf16 v[70:73], v[150:153], v[210:213], v[70:73]
	v_mfma_f32_16x16x32_bf16 v[66:69], v[158:161], v[210:213], v[66:69]
	s_setprio 0
	s_barrier
	s_add_i32 s62, s63, s19
	s_add_u32 s98, s36, 0x80
	s_addc_u32 s99, s37, 0
	s_mov_b32 m0, s62
	ds_read_b128 v[162:165], v233 offset:16384
	ds_read_b128 v[166:169], v233 offset:17408
	ds_read_b128 v[170:173], v233 offset:18432
	ds_read_b128 v[174:177], v233 offset:19456
	ds_read_b128 v[178:181], v233 offset:20480
	ds_read_b128 v[186:189], v233 offset:21504
	ds_read_b128 v[190:193], v233 offset:22528
	ds_read_b128 v[210:213], v233 offset:23552
	global_load_lds_dwordx4 v198, s[36:37]
	s_add_i32 m0, s62, 0x2000
	s_add_u32 s62, s36, 0x60000
	s_addc_u32 s63, s37, 0
	s_add_i32 s61, s61, s19
	global_load_lds_dwordx4 v194, s[36:37]
	s_mov_b32 m0, s61
	s_add_u32 s100, s40, 0x80
	s_addc_u32 s101, s41, 0
	global_load_lds_dwordx4 v198, s[62:63]
	s_add_i32 m0, s61, 0x2000
	s_nop 0
	global_load_lds_dwordx4 v194, s[62:63]
	s_mov_b32 m0, s42
	s_nop 0
	global_load_lds_dwordx4 v200, s[40:41]
	s_waitcnt vmcnt(7)
	s_waitcnt lgkmcnt(0)
	s_barrier
; #define PG8_STAGE(bufoff, gbase, voff) do { _Pragma("unroll") for (int _i = 0; _i < 2; ++_i) \
;         __builtin_amdgcn_global_load_lds((const unsigned*)((const char*)(gbase) + (voff)[_i]), (PG8_LAS unsigned*)(lds + (bufoff) + ldsw + _i * 8192), 16, 0, 0); } while (0)
; #define PG8_LDA(dst, b, h) do { _Pragma("unroll") for (int m = 0; m < 4; ++m) _Pragma("unroll") for (int k = 0; k < 2; ++k) dst[m][k] = *(const PG8_LAS bf16x8*)(lds + PG8_SA(b, h) + aoff + m * 2048 + k * 1024); } while (0)
; #define PG8_LDB(dst, b, h) do { _Pragma("unroll") for (int n = 0; n < 2; ++n) _Pragma("unroll") for (int k = 0; k < 2; ++k) dst[n][k] = *(const PG8_LAS bf16x8*)(lds + PG8_SB(b, h) + boff + n * 2048 + k * 1024); } while (0)
; #define PG8_MMA(ai, bj, At, Bt) do { __builtin_amdgcn_s_setprio(1); _Pragma("unroll") for (int m = 0; m < 4; ++m) _Pragma("unroll") for (int n = 0; n < 2; ++n) _Pragma("unroll") for (int k = 0; k < 2; ++k) \
;         acc[ai][bj][m][n] = __builtin_amdgcn_mfma_f32_16x16x32_bf16(Bt[n][k], At[m][k], acc[ai][bj][m][n], 0, 0, 0); __builtin_amdgcn_s_setprio(0); } while (0)
; #define PG8_WAIT_V(n) asm volatile("s_waitcnt vmcnt(" #n ")" ::: "memory")
; #define PG8_WAIT_L(n) asm volatile("s_waitcnt lgkmcnt(" #n ")" ::: "memory")
; #define PG8_BAR __builtin_amdgcn_s_barrier()
; #define PG8_SCHED __builtin_amdgcn_sched_barrier(0)
; template <class Epi, class Sched, bool ALIGN_EPI = false, bool SP2 = false>
; __device__ __forceinline__ void gemm_phase(PG8_LAS unsigned char* lds, const Gemm g, const Sched& S, const Epi& E, const int tid_in) {
;     ...
;             PG8_WAIT_V(8); PG8_WAIT_L(0); PG8_BAR; PG8_MMA(1, 0, At, B0); PG8_MMA(1, 1, At, B1); PG8_BAR; PG8_SCHED;
;             PG8_LDB(B0, 1, 0); PG8_LDB(B1, 1, 1); PG8_SCHED; PG8_LDA(At, 1, 0); PG8_STAGE(PG8_SA(0, 1), a2 + hstep, voffA);
;             PG8_WAIT_V(8); PG8_WAIT_L(0); PG8_BAR; PG8_MMA(0, 0, At, B0); PG8_MMA(0, 1, At, B1); PG8_BAR; PG8_SCHED;
;             PG8_LDA(At, 1, 1); PG8_STAGE(PG8_SB(1, 0), b3, voffB); PG8_STAGE(PG8_SB(1, 1), b3 + hstep, voffB); PG8_STAGE(PG8_SA(1, 0), a3, voffA);
	s_setprio 1
	v_mfma_f32_16x16x32_bf16 v[62:65], v[130:133], v[162:165], v[62:65]
	v_mfma_f32_16x16x32_bf16 v[58:61], v[138:141], v[162:165], v[58:61]
	v_mfma_f32_16x16x32_bf16 v[54:57], v[130:133], v[170:173], v[54:57]
	v_mfma_f32_16x16x32_bf16 v[46:49], v[138:141], v[170:173], v[46:49]
	v_mfma_f32_16x16x32_bf16 v[38:41], v[130:133], v[178:181], v[38:41]
	v_mfma_f32_16x16x32_bf16 v[30:33], v[138:141], v[178:181], v[30:33]
	v_mfma_f32_16x16x32_bf16 v[22:25], v[130:133], v[190:193], v[22:25]
	v_mfma_f32_16x16x32_bf16 v[12:15], v[138:141], v[190:193], v[12:15]
	v_mfma_f32_16x16x32_bf16 v[62:65], v[134:137], v[166:169], v[62:65]
	v_mfma_f32_16x16x32_bf16 v[58:61], v[142:145], v[166:169], v[58:61]
	v_mfma_f32_16x16x32_bf16 v[54:57], v[134:137], v[174:177], v[54:57]
	v_mfma_f32_16x16x32_bf16 v[46:49], v[142:145], v[174:177], v[46:49]
	v_mfma_f32_16x16x32_bf16 v[38:41], v[134:137], v[186:189], v[38:41]
	v_mfma_f32_16x16x32_bf16 v[30:33], v[142:145], v[186:189], v[30:33]
	v_mfma_f32_16x16x32_bf16 v[22:25], v[134:137], v[210:213], v[22:25]
	v_mfma_f32_16x16x32_bf16 v[12:15], v[142:145], v[210:213], v[12:15]
	s_setprio 0
	s_setprio 1
	v_mfma_f32_16x16x32_bf16 v[50:53], v[146:149], v[162:165], v[50:53]
	v_mfma_f32_16x16x32_bf16 v[42:45], v[154:157], v[162:165], v[42:45]
	v_mfma_f32_16x16x32_bf16 v[34:37], v[146:149], v[170:173], v[34:37]
	v_mfma_f32_16x16x32_bf16 v[26:29], v[154:157], v[170:173], v[26:29]
	v_mfma_f32_16x16x32_bf16 v[16:19], v[146:149], v[178:181], v[16:19]
	v_mfma_f32_16x16x32_bf16 v[8:11], v[154:157], v[178:181], v[8:11]
	v_mfma_f32_16x16x32_bf16 v[4:7], v[146:149], v[190:193], v[4:7]
	v_mfma_f32_16x16x32_bf16 v[0:3], v[154:157], v[190:193], v[0:3]
	v_mfma_f32_16x16x32_bf16 v[50:53], v[150:153], v[166:169], v[50:53]
	v_mfma_f32_16x16x32_bf16 v[42:45], v[158:161], v[166:169], v[42:45]
	v_mfma_f32_16x16x32_bf16 v[34:37], v[150:153], v[174:177], v[34:37]
	v_mfma_f32_16x16x32_bf16 v[26:29], v[158:161], v[174:177], v[26:29]
	v_mfma_f32_16x16x32_bf16 v[16:19], v[150:153], v[186:189], v[16:19]
	v_mfma_f32_16x16x32_bf16 v[8:11], v[158:161], v[186:189], v[8:11]
	v_mfma_f32_16x16x32_bf16 v[4:7], v[150:153], v[210:213], v[4:7]
	v_mfma_f32_16x16x32_bf16 v[0:3], v[158:161], v[210:213], v[0:3]
	s_setprio 0
	s_barrier
	s_add_i32 s61, 0, 0x18000
	s_add_i32 s62, 0, 0x1c000
	v_add_u32_e32 v142, s61, v230
	v_add_u32_e32 v158, s62, v230
	ds_read_b128 v[130:133], v142
	ds_read_b128 v[134:137], v142 offset:1024
	ds_read_b128 v[138:141], v142 offset:2048
	ds_read_b128 v[142:145], v142 offset:3072
	ds_read_b128 v[146:149], v158
	ds_read_b128 v[150:153], v158 offset:1024
	ds_read_b128 v[154:157], v158 offset:2048
	ds_read_b128 v[158:161], v158 offset:3072
	s_mov_b32 m0, s43
	s_nop 0
	global_load_lds_dwordx4 v196, s[40:41]
	s_add_u32 s40, s40, 0x60000
	s_addc_u32 s41, s41, 0
	s_mov_b32 m0, s44
	ds_read_b128 v[162:165], v233 offset:32768
	ds_read_b128 v[166:169], v233 offset:33792
	ds_read_b128 v[170:173], v233 offset:34816
	ds_read_b128 v[174:177], v233 offset:35840
	ds_read_b128 v[178:181], v233 offset:36864
	ds_read_b128 v[186:189], v233 offset:37888
	ds_read_b128 v[190:193], v233 offset:38912
	ds_read_b128 v[210:213], v233 offset:39936
	global_load_lds_dwordx4 v200, s[40:41]
	s_mov_b32 m0, s45
	s_nop 0
	global_load_lds_dwordx4 v196, s[40:41]
	s_waitcnt vmcnt(8)
	s_waitcnt lgkmcnt(0)
	s_barrier
; #define PG8_STAGE(bufoff, gbase, voff) do { _Pragma("unroll") for (int _i = 0; _i < 2; ++_i) \
;         __builtin_amdgcn_global_load_lds((const unsigned*)((const char*)(gbase) + (voff)[_i]), (PG8_LAS unsigned*)(lds + (bufoff) + ldsw + _i * 8192), 16, 0, 0); } while (0)
; #define PG8_LDA(dst, b, h) do { _Pragma("unroll") for (int m = 0; m < 4; ++m) _Pragma("unroll") for (int k = 0; k < 2; ++k) dst[m][k] = *(const PG8_LAS bf16x8*)(lds + PG8_SA(b, h) + aoff + m * 2048 + k * 1024); } while (0)
; #define PG8_MMA(ai, bj, At, Bt) do { __builtin_amdgcn_s_setprio(1); _Pragma("unroll") for (int m = 0; m < 4; ++m) _Pragma("unroll") for (int n = 0; n < 2; ++n) _Pragma("unroll") for (int k = 0; k < 2; ++k) \
;         acc[ai][bj][m][n] = __builtin_amdgcn_mfma_f32_16x16x32_bf16(Bt[n][k], At[m][k], acc[ai][bj][m][n], 0, 0, 0); __builtin_amdgcn_s_setprio(0); } while (0)
; #define PG8_WAIT_V(n) asm volatile("s_waitcnt vmcnt(" #n ")" ::: "memory")
; #define PG8_WAIT_L(n) asm volatile("s_waitcnt lgkmcnt(" #n ")" ::: "memory")
; #define PG8_BAR __builtin_amdgcn_s_barrier()
; #define PG8_SCHED __builtin_amdgcn_sched_barrier(0)
; template <class Epi, class Sched, bool ALIGN_EPI = false, bool SP2 = false>
; __device__ __forceinline__ void gemm_phase(PG8_LAS unsigned char* lds, const Gemm g, const Sched& S, const Epi& E, const int tid_in) {
;     ...
;         for (int t = 0; t < nt; t += 2) {
;     ...
;             PG8_WAIT_V(8); PG8_WAIT_L(0); PG8_BAR; PG8_MMA(0, 0, At, B0); PG8_MMA(0, 1, At, B1); PG8_BAR; PG8_SCHED;
;             PG8_LDA(At, 1, 1); PG8_STAGE(PG8_SB(1, 0), b3, voffB); PG8_STAGE(PG8_SB(1, 1), b3 + hstep, voffB); PG8_STAGE(PG8_SA(1, 0), a3, voffA);
;             PG8_WAIT_V(8); PG8_WAIT_L(0); PG8_BAR; PG8_MMA(1, 0, At, B0); PG8_MMA(1, 1, At, B1); PG8_BAR; PG8_SCHED;
	s_setprio 1
	v_mfma_f32_16x16x32_bf16 v[126:129], v[130:133], v[162:165], v[126:129]
	v_mfma_f32_16x16x32_bf16 v[122:125], v[138:141], v[162:165], v[122:125]
	v_mfma_f32_16x16x32_bf16 v[110:113], v[130:133], v[170:173], v[110:113]
	v_mfma_f32_16x16x32_bf16 v[106:109], v[138:141], v[170:173], v[106:109]
	v_mfma_f32_16x16x32_bf16 v[102:105], v[130:133], v[178:181], v[102:105]
	v_mfma_f32_16x16x32_bf16 v[94:97], v[138:141], v[178:181], v[94:97]
	v_mfma_f32_16x16x32_bf16 v[86:89], v[130:133], v[190:193], v[86:89]
	v_mfma_f32_16x16x32_bf16 v[78:81], v[138:141], v[190:193], v[78:81]
	v_mfma_f32_16x16x32_bf16 v[126:129], v[134:137], v[166:169], v[126:129]
	v_mfma_f32_16x16x32_bf16 v[122:125], v[142:145], v[166:169], v[122:125]
	v_mfma_f32_16x16x32_bf16 v[110:113], v[134:137], v[174:177], v[110:113]
	v_mfma_f32_16x16x32_bf16 v[106:109], v[142:145], v[174:177], v[106:109]
	v_mfma_f32_16x16x32_bf16 v[102:105], v[134:137], v[186:189], v[102:105]
	v_mfma_f32_16x16x32_bf16 v[94:97], v[142:145], v[186:189], v[94:97]
	v_mfma_f32_16x16x32_bf16 v[86:89], v[134:137], v[210:213], v[86:89]
	v_mfma_f32_16x16x32_bf16 v[78:81], v[142:145], v[210:213], v[78:81]
	s_setprio 0
	s_setprio 1
	v_mfma_f32_16x16x32_bf16 v[118:121], v[146:149], v[162:165], v[118:121]
	v_mfma_f32_16x16x32_bf16 v[114:117], v[154:157], v[162:165], v[114:117]
	v_mfma_f32_16x16x32_bf16 v[98:101], v[146:149], v[170:173], v[98:101]
	v_mfma_f32_16x16x32_bf16 v[90:93], v[154:157], v[170:173], v[90:93]
	v_mfma_f32_16x16x32_bf16 v[82:85], v[146:149], v[178:181], v[82:85]
	v_mfma_f32_16x16x32_bf16 v[74:77], v[154:157], v[178:181], v[74:77]
	v_mfma_f32_16x16x32_bf16 v[70:73], v[146:149], v[190:193], v[70:73]
	v_mfma_f32_16x16x32_bf16 v[66:69], v[154:157], v[190:193], v[66:69]
	v_mfma_f32_16x16x32_bf16 v[118:121], v[150:153], v[166:169], v[118:121]
	v_mfma_f32_16x16x32_bf16 v[114:117], v[158:161], v[166:169], v[114:117]
	v_mfma_f32_16x16x32_bf16 v[98:101], v[150:153], v[174:177], v[98:101]
	v_mfma_f32_16x16x32_bf16 v[90:93], v[158:161], v[174:177], v[90:93]
	v_mfma_f32_16x16x32_bf16 v[82:85], v[150:153], v[186:189], v[82:85]
	v_mfma_f32_16x16x32_bf16 v[74:77], v[158:161], v[186:189], v[74:77]
	v_mfma_f32_16x16x32_bf16 v[70:73], v[150:153], v[210:213], v[70:73]
	v_mfma_f32_16x16x32_bf16 v[66:69], v[158:161], v[210:213], v[66:69]
	s_setprio 0
	s_barrier
	s_add_i32 s40, s61, s19
	s_mov_b32 m0, s40
	ds_read_b128 v[162:165], v233 offset:49152
	ds_read_b128 v[166:169], v233 offset:50176
	ds_read_b128 v[170:173], v233 offset:51200
	ds_read_b128 v[174:177], v233 offset:52224
	ds_read_b128 v[178:181], v233 offset:53248
	ds_read_b128 v[186:189], v233 offset:54272
	ds_read_b128 v[190:193], v233 offset:55296
	ds_read_b128 v[210:213], v233 offset:56320
	global_load_lds_dwordx4 v198, s[98:99]
	s_add_i32 m0, s40, 0x2000
	s_add_u32 s36, s36, 0x60080
	s_addc_u32 s37, s37, 0
	s_add_i32 s40, s62, s19
	global_load_lds_dwordx4 v194, s[98:99]
	s_mov_b32 m0, s40
	s_nop 0
	global_load_lds_dwordx4 v198, s[36:37]
	s_add_i32 m0, s40, 0x2000
	s_nop 0
	global_load_lds_dwordx4 v194, s[36:37]
	s_mov_b32 m0, s47
	s_nop 0
	global_load_lds_dwordx4 v200, s[100:101]
	s_waitcnt vmcnt(7)
	s_waitcnt lgkmcnt(0)
	s_barrier
	s_setprio 1
	v_mfma_f32_16x16x32_bf16 v[62:65], v[130:133], v[162:165], v[62:65]
	v_mfma_f32_16x16x32_bf16 v[58:61], v[138:141], v[162:165], v[58:61]
	v_mfma_f32_16x16x32_bf16 v[54:57], v[130:133], v[170:173], v[54:57]
	v_mfma_f32_16x16x32_bf16 v[46:49], v[138:141], v[170:173], v[46:49]
	v_mfma_f32_16x16x32_bf16 v[38:41], v[130:133], v[178:181], v[38:41]
	v_mfma_f32_16x16x32_bf16 v[30:33], v[138:141], v[178:181], v[30:33]
	v_mfma_f32_16x16x32_bf16 v[22:25], v[130:133], v[190:193], v[22:25]
	v_mfma_f32_16x16x32_bf16 v[12:15], v[138:141], v[190:193], v[12:15]
	v_mfma_f32_16x16x32_bf16 v[62:65], v[134:137], v[166:169], v[62:65]
	v_mfma_f32_16x16x32_bf16 v[58:61], v[142:145], v[166:169], v[58:61]
	v_mfma_f32_16x16x32_bf16 v[54:57], v[134:137], v[174:177], v[54:57]
	v_mfma_f32_16x16x32_bf16 v[46:49], v[142:145], v[174:177], v[46:49]
	v_mfma_f32_16x16x32_bf16 v[38:41], v[134:137], v[186:189], v[38:41]
	v_mfma_f32_16x16x32_bf16 v[30:33], v[142:145], v[186:189], v[30:33]
	v_mfma_f32_16x16x32_bf16 v[22:25], v[134:137], v[210:213], v[22:25]
	v_mfma_f32_16x16x32_bf16 v[12:15], v[142:145], v[210:213], v[12:15]
	s_setprio 0
	s_setprio 1
	v_mfma_f32_16x16x32_bf16 v[50:53], v[146:149], v[162:165], v[50:53]
	v_mfma_f32_16x16x32_bf16 v[42:45], v[154:157], v[162:165], v[42:45]
	v_mfma_f32_16x16x32_bf16 v[34:37], v[146:149], v[170:173], v[34:37]
	v_mfma_f32_16x16x32_bf16 v[26:29], v[154:157], v[170:173], v[26:29]
	v_mfma_f32_16x16x32_bf16 v[16:19], v[146:149], v[178:181], v[16:19]
	v_mfma_f32_16x16x32_bf16 v[8:11], v[154:157], v[178:181], v[8:11]
	v_mfma_f32_16x16x32_bf16 v[4:7], v[146:149], v[190:193], v[4:7]
	v_mfma_f32_16x16x32_bf16 v[0:3], v[154:157], v[190:193], v[0:3]
	v_mfma_f32_16x16x32_bf16 v[50:53], v[150:153], v[166:169], v[50:53]
	v_mfma_f32_16x16x32_bf16 v[42:45], v[158:161], v[166:169], v[42:45]
	v_mfma_f32_16x16x32_bf16 v[34:37], v[150:153], v[174:177], v[34:37]
	v_mfma_f32_16x16x32_bf16 v[26:29], v[158:161], v[174:177], v[26:29]
	v_mfma_f32_16x16x32_bf16 v[16:19], v[150:153], v[186:189], v[16:19]
	v_mfma_f32_16x16x32_bf16 v[8:11], v[158:161], v[186:189], v[8:11]
	v_mfma_f32_16x16x32_bf16 v[4:7], v[150:153], v[210:213], v[4:7]
	v_mfma_f32_16x16x32_bf16 v[0:3], v[158:161], v[210:213], v[0:3]
	s_setprio 0
	s_barrier
	s_add_i32 s60, s60, 2
	s_add_u32 s34, s34, 0x100
	s_addc_u32 s35, s35, 0
	s_cmp_gt_u32 s60, 21
	s_cbranch_scc1 .LBB0_963

; #define PG8_STAGE(bufoff, gbase, voff) do { _Pragma("unroll") for (int _i = 0; _i < 2; ++_i) \
;         __builtin_amdgcn_global_load_lds((const unsigned*)((const char*)(gbase) + (voff)[_i]), (PG8_LAS unsigned*)(lds + (bufoff) + ldsw + _i * 8192), 16, 0, 0); } while (0)
; #define PG8_LDA(dst, b, h) do { _Pragma("unroll") for (int m = 0; m < 4; ++m) _Pragma("unroll") for (int k = 0; k < 2; ++k) dst[m][k] = *(const PG8_LAS bf16x8*)(lds + PG8_SA(b, h) + aoff + m * 2048 + k * 1024); } while (0)
; #define PG8_LDB(dst, b, h) do { _Pragma("unroll") for (int n = 0; n < 2; ++n) _Pragma("unroll") for (int k = 0; k < 2; ++k) dst[n][k] = *(const PG8_LAS bf16x8*)(lds + PG8_SB(b, h) + boff + n * 2048 + k * 1024); } while (0)
; template <class Epi, class Sched, bool ALIGN_EPI = false, bool SP2 = false>
; __device__ __forceinline__ void gemm_phase(PG8_LAS unsigned char* lds, const Gemm g, const Sched& S, const Epi& E, const int tid_in) {
;     ...
;             const bool last = (t == nt - 2);
;             const char* a1 = cA + (size_t)(t + 1) * kstep;
;             const char* a2 = last ? nA : cA + (size_t)(t + 2) * kstep; const char* b2 = last ? nB : cB + (size_t)(t + 2) * kstep;
;             const char* a3 = a2 + kstep; const char* b3 = b2 + kstep;
;             if (last && has_next) S.a_ready(nxt);
;             if constexpr (SP2) {
;             PG8_LDB(B0, 0, 0); PG8_LDB(B1, 0, 1); PG8_SCHED; PG8_LDA(At, 0, 0); PG8_STAGE(PG8_SA(1, 1), a1 + hstep, voffA);
;             PG8_WAIT_V(8); PG8_WAIT_L(0); PG8_BAR; PG8_MMA(0, 0, At, B0); PG8_MMA(0, 1, At, B1); PG8_BAR; PG8_SCHED;
;             PG8_LDA(At, 0, 1); PG8_STAGE(PG8_SB(0, 0), b2, voffB); PG8_STAGE(PG8_SB(0, 1), b2 + hstep, voffB); PG8_STAGE(PG8_SA(0, 0), a2, voffA);
;             PG8_WAIT_V(8); PG8_WAIT_L(0); PG8_BAR; PG8_MMA(1, 0, At, B0); PG8_MMA(1, 1, At, B1); PG8_BAR; PG8_SCHED;
;             PG8_LDB(B0, 1, 0); PG8_LDB(B1, 1, 1); PG8_SCHED; PG8_LDA(At, 1, 0); PG8_STAGE(PG8_SA(0, 1), a2 + hstep, voffA);
;             PG8_WAIT_V(8); PG8_WAIT_L(0); PG8_BAR; PG8_MMA(0, 0, At, B0); PG8_MMA(0, 1, At, B1); PG8_BAR; PG8_SCHED;
;             PG8_LDA(At, 1, 1); PG8_STAGE(PG8_SB(1, 0), b3, voffB); PG8_STAGE(PG8_SB(1, 1), b3 + hstep, voffB); PG8_STAGE(PG8_SA(1, 0), a3, voffA);
;             PG8_WAIT_V(8); PG8_WAIT_L(0); PG8_BAR; PG8_MMA(1, 0, At, B0); PG8_MMA(1, 1, At, B1); PG8_BAR; PG8_SCHED;
.LBB0_1037:
	s_mov_b32 m0, s76
	s_nop 0
	global_load_lds_dwordx4 v214, s[100:101]
	s_add_u32 s30, s28, 0xfff80080
	s_addc_u32 s31, s29, -1
	s_add_i32 s46, 0, 0x10000
	s_cmp_eq_u32 vcc_lo, 28
	s_cselect_b32 s35, s38, s31
	s_cselect_b32 s34, s39, s30
	s_cselect_b32 s31, s40, s92
	s_cselect_b32 s30, s41, s57
	s_add_i32 vcc_hi, 0, 0x14000
	v_add_u32_e32 v142, s46, v21
	v_add_u32_e32 v158, vcc_hi, v21
	ds_read_b128 v[130:133], v142
	ds_read_b128 v[134:137], v142 offset:1024
	ds_read_b128 v[138:141], v142 offset:2048
	ds_read_b128 v[142:145], v142 offset:3072
	ds_read_b128 v[146:149], v158
	ds_read_b128 v[150:153], v158 offset:1024
	ds_read_b128 v[154:157], v158 offset:2048
	ds_read_b128 v[158:161], v158 offset:3072
	s_add_i32 m0, s64, 0xc000
	ds_read_b128 v[162:165], v208
	ds_read_b128 v[166:169], v208 offset:1024
	ds_read_b128 v[170:173], v208 offset:2048
	ds_read_b128 v[174:177], v208 offset:3072
	ds_read_b128 v[178:181], v208 offset:4096
	ds_read_b128 v[182:185], v208 offset:5120
	ds_read_b128 v[186:189], v208 offset:6144
	ds_read_b128 v[190:193], v208 offset:7168
	global_load_lds_dwordx4 v218, s[28:29]
	s_add_i32 m0, s64, 0xe000
	s_nop 0
	global_load_lds_dwordx4 v220, s[28:29]
	s_waitcnt vmcnt(8)
	s_waitcnt lgkmcnt(0)
	s_barrier
	s_setprio 1
	v_mfma_f32_16x16x32_bf16 v[126:129], v[130:133], v[162:165], v[126:129]
	v_mfma_f32_16x16x32_bf16 v[122:125], v[138:141], v[162:165], v[122:125]
	v_mfma_f32_16x16x32_bf16 v[110:113], v[130:133], v[170:173], v[110:113]
	v_mfma_f32_16x16x32_bf16 v[106:109], v[138:141], v[170:173], v[106:109]
	v_mfma_f32_16x16x32_bf16 v[94:97], v[130:133], v[178:181], v[94:97]
	v_mfma_f32_16x16x32_bf16 v[90:93], v[138:141], v[178:181], v[90:93]
	v_mfma_f32_16x16x32_bf16 v[78:81], v[130:133], v[186:189], v[78:81]
	v_mfma_f32_16x16x32_bf16 v[74:77], v[138:141], v[186:189], v[74:77]
	v_mfma_f32_16x16x32_bf16 v[126:129], v[134:137], v[166:169], v[126:129]
	v_mfma_f32_16x16x32_bf16 v[122:125], v[142:145], v[166:169], v[122:125]
	v_mfma_f32_16x16x32_bf16 v[110:113], v[134:137], v[174:177], v[110:113]
	v_mfma_f32_16x16x32_bf16 v[106:109], v[142:145], v[174:177], v[106:109]
	v_mfma_f32_16x16x32_bf16 v[94:97], v[134:137], v[182:185], v[94:97]
	v_mfma_f32_16x16x32_bf16 v[90:93], v[142:145], v[182:185], v[90:93]
	v_mfma_f32_16x16x32_bf16 v[78:81], v[134:137], v[190:193], v[78:81]
	v_mfma_f32_16x16x32_bf16 v[74:77], v[142:145], v[190:193], v[74:77]
	s_setprio 0
	s_setprio 1
	v_mfma_f32_16x16x32_bf16 v[118:121], v[146:149], v[162:165], v[118:121]
	v_mfma_f32_16x16x32_bf16 v[114:117], v[154:157], v[162:165], v[114:117]
	v_mfma_f32_16x16x32_bf16 v[102:105], v[146:149], v[170:173], v[102:105]
	v_mfma_f32_16x16x32_bf16 v[98:101], v[154:157], v[170:173], v[98:101]
	v_mfma_f32_16x16x32_bf16 v[86:89], v[146:149], v[178:181], v[86:89]
	v_mfma_f32_16x16x32_bf16 v[82:85], v[154:157], v[178:181], v[82:85]
	v_mfma_f32_16x16x32_bf16 v[70:73], v[146:149], v[186:189], v[70:73]
	v_mfma_f32_16x16x32_bf16 v[66:69], v[154:157], v[186:189], v[66:69]
	v_mfma_f32_16x16x32_bf16 v[118:121], v[150:153], v[166:169], v[118:121]
	v_mfma_f32_16x16x32_bf16 v[114:117], v[158:161], v[166:169], v[114:117]
	v_mfma_f32_16x16x32_bf16 v[102:105], v[150:153], v[174:177], v[102:105]
	v_mfma_f32_16x16x32_bf16 v[98:101], v[158:161], v[174:177], v[98:101]
	v_mfma_f32_16x16x32_bf16 v[86:89], v[150:153], v[182:185], v[86:89]
	v_mfma_f32_16x16x32_bf16 v[82:85], v[158:161], v[182:185], v[82:85]
	v_mfma_f32_16x16x32_bf16 v[70:73], v[150:153], v[190:193], v[70:73]
	v_mfma_f32_16x16x32_bf16 v[66:69], v[158:161], v[190:193], v[66:69]
	s_setprio 0
	s_barrier
	s_add_i32 s46, s46, s8
	s_add_u32 s98, s30, 0x80
	s_addc_u32 s99, s31, 0
	s_mov_b32 m0, s46
	ds_read_b128 v[162:165], v208 offset:16384
	ds_read_b128 v[166:169], v208 offset:17408
	ds_read_b128 v[170:173], v208 offset:18432
	ds_read_b128 v[174:177], v208 offset:19456
	ds_read_b128 v[178:181], v208 offset:20480
	ds_read_b128 v[182:185], v208 offset:21504
	ds_read_b128 v[186:189], v208 offset:22528
	ds_read_b128 v[190:193], v208 offset:23552
	global_load_lds_dwordx4 v204, s[30:31]
	s_add_i32 m0, s46, 0x2000
	s_add_u32 s46, s30, 0x80000
	s_addc_u32 s47, s31, 0
	s_add_i32 vcc_hi, vcc_hi, s8
	global_load_lds_dwordx4 v216, s[30:31]
	s_mov_b32 m0, vcc_hi
	s_add_u32 s100, s34, 0x80
	s_addc_u32 s101, s35, 0
	global_load_lds_dwordx4 v204, s[46:47]
	s_add_i32 m0, vcc_hi, 0x2000
	s_nop 0
	global_load_lds_dwordx4 v216, s[46:47]
	s_mov_b32 m0, s64
	s_nop 0
	global_load_lds_dwordx4 v202, s[34:35]
	s_waitcnt vmcnt(7)
	s_waitcnt lgkmcnt(0)
	s_barrier
; #define PG8_STAGE(bufoff, gbase, voff) do { _Pragma("unroll") for (int _i = 0; _i < 2; ++_i) \
;         __builtin_amdgcn_global_load_lds((const unsigned*)((const char*)(gbase) + (voff)[_i]), (PG8_LAS unsigned*)(lds + (bufoff) + ldsw + _i * 8192), 16, 0, 0); } while (0)
; #define PG8_LDA(dst, b, h) do { _Pragma("unroll") for (int m = 0; m < 4; ++m) _Pragma("unroll") for (int k = 0; k < 2; ++k) dst[m][k] = *(const PG8_LAS bf16x8*)(lds + PG8_SA(b, h) + aoff + m * 2048 + k * 1024); } while (0)
; #define PG8_LDB(dst, b, h) do { _Pragma("unroll") for (int n = 0; n < 2; ++n) _Pragma("unroll") for (int k = 0; k < 2; ++k) dst[n][k] = *(const PG8_LAS bf16x8*)(lds + PG8_SB(b, h) + boff + n * 2048 + k * 1024); } while (0)
; #define PG8_MMA(ai, bj, At, Bt) do { __builtin_amdgcn_s_setprio(1); _Pragma("unroll") for (int m = 0; m < 4; ++m) _Pragma("unroll") for (int n = 0; n < 2; ++n) _Pragma("unroll") for (int k = 0; k < 2; ++k) \
;         acc[ai][bj][m][n] = __builtin_amdgcn_mfma_f32_16x16x32_bf16(Bt[n][k], At[m][k], acc[ai][bj][m][n], 0, 0, 0); __builtin_amdgcn_s_setprio(0); } while (0)
; #define PG8_WAIT_V(n) asm volatile("s_waitcnt vmcnt(" #n ")" ::: "memory")
; #define PG8_WAIT_L(n) asm volatile("s_waitcnt lgkmcnt(" #n ")" ::: "memory")
; #define PG8_BAR __builtin_amdgcn_s_barrier()
; #define PG8_SCHED __builtin_amdgcn_sched_barrier(0)
; template <class Epi, class Sched, bool ALIGN_EPI = false, bool SP2 = false>
; __device__ __forceinline__ void gemm_phase(PG8_LAS unsigned char* lds, const Gemm g, const Sched& S, const Epi& E, const int tid_in) {
;     ...
;             PG8_WAIT_V(8); PG8_WAIT_L(0); PG8_BAR; PG8_MMA(1, 0, At, B0); PG8_MMA(1, 1, At, B1); PG8_BAR; PG8_SCHED;
;             PG8_LDB(B0, 1, 0); PG8_LDB(B1, 1, 1); PG8_SCHED; PG8_LDA(At, 1, 0); PG8_STAGE(PG8_SA(0, 1), a2 + hstep, voffA);
;             PG8_WAIT_V(8); PG8_WAIT_L(0); PG8_BAR; PG8_MMA(0, 0, At, B0); PG8_MMA(0, 1, At, B1); PG8_BAR; PG8_SCHED;
;             PG8_LDA(At, 1, 1); PG8_STAGE(PG8_SB(1, 0), b3, voffB); PG8_STAGE(PG8_SB(1, 1), b3 + hstep, voffB); PG8_STAGE(PG8_SA(1, 0), a3, voffA);
	s_setprio 1
	v_mfma_f32_16x16x32_bf16 v[62:65], v[130:133], v[162:165], v[62:65]
	v_mfma_f32_16x16x32_bf16 v[58:61], v[138:141], v[162:165], v[58:61]
	v_mfma_f32_16x16x32_bf16 v[46:49], v[130:133], v[170:173], v[46:49]
	v_mfma_f32_16x16x32_bf16 v[42:45], v[138:141], v[170:173], v[42:45]
	v_mfma_f32_16x16x32_bf16 v[30:33], v[130:133], v[178:181], v[30:33]
	v_mfma_f32_16x16x32_bf16 v[26:29], v[138:141], v[178:181], v[26:29]
	v_mfma_f32_16x16x32_bf16 v[12:15], v[130:133], v[186:189], v[12:15]
	v_mfma_f32_16x16x32_bf16 v[8:11], v[138:141], v[186:189], v[8:11]
	v_mfma_f32_16x16x32_bf16 v[62:65], v[134:137], v[166:169], v[62:65]
	v_mfma_f32_16x16x32_bf16 v[58:61], v[142:145], v[166:169], v[58:61]
	v_mfma_f32_16x16x32_bf16 v[46:49], v[134:137], v[174:177], v[46:49]
	v_mfma_f32_16x16x32_bf16 v[42:45], v[142:145], v[174:177], v[42:45]
	v_mfma_f32_16x16x32_bf16 v[30:33], v[134:137], v[182:185], v[30:33]
	v_mfma_f32_16x16x32_bf16 v[26:29], v[142:145], v[182:185], v[26:29]
	v_mfma_f32_16x16x32_bf16 v[12:15], v[134:137], v[190:193], v[12:15]
	v_mfma_f32_16x16x32_bf16 v[8:11], v[142:145], v[190:193], v[8:11]
	s_setprio 0
	s_setprio 1
	v_mfma_f32_16x16x32_bf16 v[54:57], v[146:149], v[162:165], v[54:57]
	v_mfma_f32_16x16x32_bf16 v[50:53], v[154:157], v[162:165], v[50:53]
	v_mfma_f32_16x16x32_bf16 v[38:41], v[146:149], v[170:173], v[38:41]
	v_mfma_f32_16x16x32_bf16 v[34:37], v[154:157], v[170:173], v[34:37]
	v_mfma_f32_16x16x32_bf16 v[22:25], v[146:149], v[178:181], v[22:25]
	v_mfma_f32_16x16x32_bf16 v[16:19], v[154:157], v[178:181], v[16:19]
	v_mfma_f32_16x16x32_bf16 v[4:7], v[146:149], v[186:189], v[4:7]
	v_mfma_f32_16x16x32_bf16 v[0:3], v[154:157], v[186:189], v[0:3]
	v_mfma_f32_16x16x32_bf16 v[54:57], v[150:153], v[166:169], v[54:57]
	v_mfma_f32_16x16x32_bf16 v[50:53], v[158:161], v[166:169], v[50:53]
	v_mfma_f32_16x16x32_bf16 v[38:41], v[150:153], v[174:177], v[38:41]
	v_mfma_f32_16x16x32_bf16 v[34:37], v[158:161], v[174:177], v[34:37]
	v_mfma_f32_16x16x32_bf16 v[22:25], v[150:153], v[182:185], v[22:25]
	v_mfma_f32_16x16x32_bf16 v[16:19], v[158:161], v[182:185], v[16:19]
	v_mfma_f32_16x16x32_bf16 v[4:7], v[150:153], v[190:193], v[4:7]
	v_mfma_f32_16x16x32_bf16 v[0:3], v[158:161], v[190:193], v[0:3]
	s_setprio 0
	s_barrier
	s_add_i32 s46, 0, 0x18000
	s_add_i32 s47, 0, 0x1c000
	v_add_u32_e32 v142, s46, v21
	v_add_u32_e32 v158, s47, v21
	ds_read_b128 v[130:133], v142
	ds_read_b128 v[134:137], v142 offset:1024
	ds_read_b128 v[138:141], v142 offset:2048
	ds_read_b128 v[142:145], v142 offset:3072
	ds_read_b128 v[146:149], v158
	ds_read_b128 v[150:153], v158 offset:1024
	ds_read_b128 v[154:157], v158 offset:2048
	ds_read_b128 v[158:161], v158 offset:3072
	s_mov_b32 m0, s65
	s_nop 0
	global_load_lds_dwordx4 v214, s[34:35]
	s_add_u32 s34, s34, 0x80000
	s_addc_u32 s35, s35, 0
	s_mov_b32 m0, s66
	ds_read_b128 v[162:165], v208 offset:32768
	ds_read_b128 v[166:169], v208 offset:33792
	ds_read_b128 v[170:173], v208 offset:34816
	ds_read_b128 v[174:177], v208 offset:35840
	ds_read_b128 v[178:181], v208 offset:36864
	ds_read_b128 v[182:185], v208 offset:37888
	ds_read_b128 v[186:189], v208 offset:38912
	ds_read_b128 v[190:193], v208 offset:39936
	global_load_lds_dwordx4 v202, s[34:35]
	s_mov_b32 m0, s67
	s_nop 0
	global_load_lds_dwordx4 v214, s[34:35]
	s_waitcnt vmcnt(8)
	s_waitcnt lgkmcnt(0)
	s_barrier
	s_setprio 1
	v_mfma_f32_16x16x32_bf16 v[126:129], v[130:133], v[162:165], v[126:129]
	v_mfma_f32_16x16x32_bf16 v[122:125], v[138:141], v[162:165], v[122:125]
	v_mfma_f32_16x16x32_bf16 v[110:113], v[130:133], v[170:173], v[110:113]
	v_mfma_f32_16x16x32_bf16 v[106:109], v[138:141], v[170:173], v[106:109]
	v_mfma_f32_16x16x32_bf16 v[94:97], v[130:133], v[178:181], v[94:97]
	v_mfma_f32_16x16x32_bf16 v[90:93], v[138:141], v[178:181], v[90:93]
	v_mfma_f32_16x16x32_bf16 v[78:81], v[130:133], v[186:189], v[78:81]
	v_mfma_f32_16x16x32_bf16 v[74:77], v[138:141], v[186:189], v[74:77]
	v_mfma_f32_16x16x32_bf16 v[126:129], v[134:137], v[166:169], v[126:129]
	v_mfma_f32_16x16x32_bf16 v[122:125], v[142:145], v[166:169], v[122:125]
	v_mfma_f32_16x16x32_bf16 v[110:113], v[134:137], v[174:177], v[110:113]
	v_mfma_f32_16x16x32_bf16 v[106:109], v[142:145], v[174:177], v[106:109]
	v_mfma_f32_16x16x32_bf16 v[94:97], v[134:137], v[182:185], v[94:97]
	v_mfma_f32_16x16x32_bf16 v[90:93], v[142:145], v[182:185], v[90:93]
	v_mfma_f32_16x16x32_bf16 v[78:81], v[134:137], v[190:193], v[78:81]
	v_mfma_f32_16x16x32_bf16 v[74:77], v[142:145], v[190:193], v[74:77]
	s_setprio 0
	s_setprio 1
	v_mfma_f32_16x16x32_bf16 v[118:121], v[146:149], v[162:165], v[118:121]
	v_mfma_f32_16x16x32_bf16 v[114:117], v[154:157], v[162:165], v[114:117]
	v_mfma_f32_16x16x32_bf16 v[102:105], v[146:149], v[170:173], v[102:105]
	v_mfma_f32_16x16x32_bf16 v[98:101], v[154:157], v[170:173], v[98:101]
	v_mfma_f32_16x16x32_bf16 v[86:89], v[146:149], v[178:181], v[86:89]
	v_mfma_f32_16x16x32_bf16 v[82:85], v[154:157], v[178:181], v[82:85]
	v_mfma_f32_16x16x32_bf16 v[70:73], v[146:149], v[186:189], v[70:73]
	v_mfma_f32_16x16x32_bf16 v[66:69], v[154:157], v[186:189], v[66:69]
	v_mfma_f32_16x16x32_bf16 v[118:121], v[150:153], v[166:169], v[118:121]
	v_mfma_f32_16x16x32_bf16 v[114:117], v[158:161], v[166:169], v[114:117]
	v_mfma_f32_16x16x32_bf16 v[102:105], v[150:153], v[174:177], v[102:105]
	v_mfma_f32_16x16x32_bf16 v[98:101], v[158:161], v[174:177], v[98:101]
	v_mfma_f32_16x16x32_bf16 v[86:89], v[150:153], v[182:185], v[86:89]
	v_mfma_f32_16x16x32_bf16 v[82:85], v[158:161], v[182:185], v[82:85]
	v_mfma_f32_16x16x32_bf16 v[70:73], v[150:153], v[190:193], v[70:73]
	v_mfma_f32_16x16x32_bf16 v[66:69], v[158:161], v[190:193], v[66:69]
	s_setprio 0
	s_barrier
; #define PG8_STAGE(bufoff, gbase, voff) do { _Pragma("unroll") for (int _i = 0; _i < 2; ++_i) \
;         __builtin_amdgcn_global_load_lds((const unsigned*)((const char*)(gbase) + (voff)[_i]), (PG8_LAS unsigned*)(lds + (bufoff) + ldsw + _i * 8192), 16, 0, 0); } while (0)
; #define PG8_LDA(dst, b, h) do { _Pragma("unroll") for (int m = 0; m < 4; ++m) _Pragma("unroll") for (int k = 0; k < 2; ++k) dst[m][k] = *(const PG8_LAS bf16x8*)(lds + PG8_SA(b, h) + aoff + m * 2048 + k * 1024); } while (0)
; #define PG8_MMA(ai, bj, At, Bt) do { __builtin_amdgcn_s_setprio(1); _Pragma("unroll") for (int m = 0; m < 4; ++m) _Pragma("unroll") for (int n = 0; n < 2; ++n) _Pragma("unroll") for (int k = 0; k < 2; ++k) \
;         acc[ai][bj][m][n] = __builtin_amdgcn_mfma_f32_16x16x32_bf16(Bt[n][k], At[m][k], acc[ai][bj][m][n], 0, 0, 0); __builtin_amdgcn_s_setprio(0); } while (0)
; #define PG8_WAIT_V(n) asm volatile("s_waitcnt vmcnt(" #n ")" ::: "memory")
; #define PG8_WAIT_L(n) asm volatile("s_waitcnt lgkmcnt(" #n ")" ::: "memory")
; #define PG8_BAR __builtin_amdgcn_s_barrier()
; #define PG8_SCHED __builtin_amdgcn_sched_barrier(0)
; template <class Epi, class Sched, bool ALIGN_EPI = false, bool SP2 = false>
; __device__ __forceinline__ void gemm_phase(PG8_LAS unsigned char* lds, const Gemm g, const Sched& S, const Epi& E, const int tid_in) {
;     ...
;         for (int t = 0; t < nt; t += 2) {
;     ...
;             PG8_WAIT_V(8); PG8_WAIT_L(0); PG8_BAR; PG8_MMA(0, 0, At, B0); PG8_MMA(0, 1, At, B1); PG8_BAR; PG8_SCHED;
;             PG8_LDA(At, 1, 1); PG8_STAGE(PG8_SB(1, 0), b3, voffB); PG8_STAGE(PG8_SB(1, 1), b3 + hstep, voffB); PG8_STAGE(PG8_SA(1, 0), a3, voffA);
;             PG8_WAIT_V(8); PG8_WAIT_L(0); PG8_BAR; PG8_MMA(1, 0, At, B0); PG8_MMA(1, 1, At, B1); PG8_BAR; PG8_SCHED;
	s_add_i32 s34, s46, s8
	s_mov_b32 m0, s34
	ds_read_b128 v[162:165], v208 offset:49152
	ds_read_b128 v[166:169], v208 offset:50176
	ds_read_b128 v[170:173], v208 offset:51200
	ds_read_b128 v[174:177], v208 offset:52224
	ds_read_b128 v[178:181], v208 offset:53248
	ds_read_b128 v[182:185], v208 offset:54272
	ds_read_b128 v[186:189], v208 offset:55296
	ds_read_b128 v[190:193], v208 offset:56320
	global_load_lds_dwordx4 v204, s[98:99]
	s_add_i32 m0, s34, 0x2000
	s_add_u32 s30, s30, 0x80080
	s_addc_u32 s31, s31, 0
	s_add_i32 s34, s47, s8
	global_load_lds_dwordx4 v216, s[98:99]
	s_mov_b32 m0, s34
	s_nop 0
	global_load_lds_dwordx4 v204, s[30:31]
	s_add_i32 m0, s34, 0x2000
	s_nop 0
	global_load_lds_dwordx4 v216, s[30:31]
	s_mov_b32 m0, s75
	s_nop 0
	global_load_lds_dwordx4 v202, s[100:101]
	s_waitcnt vmcnt(7)
	s_waitcnt lgkmcnt(0)
	s_barrier
	s_setprio 1
	v_mfma_f32_16x16x32_bf16 v[62:65], v[130:133], v[162:165], v[62:65]
	v_mfma_f32_16x16x32_bf16 v[58:61], v[138:141], v[162:165], v[58:61]
	v_mfma_f32_16x16x32_bf16 v[46:49], v[130:133], v[170:173], v[46:49]
	v_mfma_f32_16x16x32_bf16 v[42:45], v[138:141], v[170:173], v[42:45]
	v_mfma_f32_16x16x32_bf16 v[30:33], v[130:133], v[178:181], v[30:33]
	v_mfma_f32_16x16x32_bf16 v[26:29], v[138:141], v[178:181], v[26:29]
	v_mfma_f32_16x16x32_bf16 v[12:15], v[130:133], v[186:189], v[12:15]
	v_mfma_f32_16x16x32_bf16 v[8:11], v[138:141], v[186:189], v[8:11]
	v_mfma_f32_16x16x32_bf16 v[62:65], v[134:137], v[166:169], v[62:65]
	v_mfma_f32_16x16x32_bf16 v[58:61], v[142:145], v[166:169], v[58:61]
	v_mfma_f32_16x16x32_bf16 v[46:49], v[134:137], v[174:177], v[46:49]
	v_mfma_f32_16x16x32_bf16 v[42:45], v[142:145], v[174:177], v[42:45]
	v_mfma_f32_16x16x32_bf16 v[30:33], v[134:137], v[182:185], v[30:33]
	v_mfma_f32_16x16x32_bf16 v[26:29], v[142:145], v[182:185], v[26:29]
	v_mfma_f32_16x16x32_bf16 v[12:15], v[134:137], v[190:193], v[12:15]
	v_mfma_f32_16x16x32_bf16 v[8:11], v[142:145], v[190:193], v[8:11]
	s_setprio 0
	s_setprio 1
	v_mfma_f32_16x16x32_bf16 v[54:57], v[146:149], v[162:165], v[54:57]
	v_mfma_f32_16x16x32_bf16 v[50:53], v[154:157], v[162:165], v[50:53]
	v_mfma_f32_16x16x32_bf16 v[38:41], v[146:149], v[170:173], v[38:41]
	v_mfma_f32_16x16x32_bf16 v[34:37], v[154:157], v[170:173], v[34:37]
	v_mfma_f32_16x16x32_bf16 v[22:25], v[146:149], v[178:181], v[22:25]
	v_mfma_f32_16x16x32_bf16 v[16:19], v[154:157], v[178:181], v[16:19]
	v_mfma_f32_16x16x32_bf16 v[4:7], v[146:149], v[186:189], v[4:7]
	v_mfma_f32_16x16x32_bf16 v[0:3], v[154:157], v[186:189], v[0:3]
	v_mfma_f32_16x16x32_bf16 v[54:57], v[150:153], v[166:169], v[54:57]
	v_mfma_f32_16x16x32_bf16 v[50:53], v[158:161], v[166:169], v[50:53]
	v_mfma_f32_16x16x32_bf16 v[38:41], v[150:153], v[174:177], v[38:41]
	v_mfma_f32_16x16x32_bf16 v[34:37], v[158:161], v[174:177], v[34:37]
	v_mfma_f32_16x16x32_bf16 v[22:25], v[150:153], v[182:185], v[22:25]
	v_mfma_f32_16x16x32_bf16 v[16:19], v[158:161], v[182:185], v[16:19]
	v_mfma_f32_16x16x32_bf16 v[4:7], v[150:153], v[190:193], v[4:7]
	v_mfma_f32_16x16x32_bf16 v[0:3], v[158:161], v[190:193], v[0:3]
	s_setprio 0
	s_barrier
	s_add_i32 vcc_lo, vcc_lo, 2
	s_add_u32 s28, s28, 0x100
	s_addc_u32 s29, s29, 0
	s_add_u32 s57, s57, 0x100
	s_addc_u32 s92, s92, 0
	s_cmp_gt_u32 vcc_lo, 29
	s_cbranch_scc0 .LBB0_1037
	s_and_b64 vcc, exec, s[48:49]
	s_cbranch_vccz .LBB0_1040
	s_barrier

; #define PG8_STAGE(bufoff, gbase, voff) do { _Pragma("unroll") for (int _i = 0; _i < 2; ++_i) \
;         __builtin_amdgcn_global_load_lds((const unsigned*)((const char*)(gbase) + (voff)[_i]), (PG8_LAS unsigned*)(lds + (bufoff) + ldsw + _i * 8192), 16, 0, 0); } while (0)
; #define PG8_LDA(dst, b, h) do { _Pragma("unroll") for (int m = 0; m < 4; ++m) _Pragma("unroll") for (int k = 0; k < 2; ++k) dst[m][k] = *(const PG8_LAS bf16x8*)(lds + PG8_SA(b, h) + aoff + m * 2048 + k * 1024); } while (0)
; #define PG8_LDB(dst, b, h) do { _Pragma("unroll") for (int n = 0; n < 2; ++n) _Pragma("unroll") for (int k = 0; k < 2; ++k) dst[n][k] = *(const PG8_LAS bf16x8*)(lds + PG8_SB(b, h) + boff + n * 2048 + k * 1024); } while (0)
; template <class Epi, class Sched, bool ALIGN_EPI = false, bool SP2 = false>
; __device__ __forceinline__ void gemm_phase(PG8_LAS unsigned char* lds, const Gemm g, const Sched& S, const Epi& E, const int tid_in) {
;     ...
;             const bool last = (t == nt - 2);
;             const char* a1 = cA + (size_t)(t + 1) * kstep;
;             const char* a2 = last ? nA : cA + (size_t)(t + 2) * kstep; const char* b2 = last ? nB : cB + (size_t)(t + 2) * kstep;
;             const char* a3 = a2 + kstep; const char* b3 = b2 + kstep;
;             if (last && has_next) S.a_ready(nxt);
;             if constexpr (SP2) {
;             PG8_LDB(B0, 0, 0); PG8_LDB(B1, 0, 1); PG8_SCHED; PG8_LDA(At, 0, 0); PG8_STAGE(PG8_SA(1, 1), a1 + hstep, voffA);
;             PG8_WAIT_V(8); PG8_WAIT_L(0); PG8_BAR; PG8_MMA(0, 0, At, B0); PG8_MMA(0, 1, At, B1); PG8_BAR; PG8_SCHED;
;             PG8_LDA(At, 0, 1); PG8_STAGE(PG8_SB(0, 0), b2, voffB); PG8_STAGE(PG8_SB(0, 1), b2 + hstep, voffB); PG8_STAGE(PG8_SA(0, 0), a2, voffA);
;             PG8_WAIT_V(8); PG8_WAIT_L(0); PG8_BAR; PG8_MMA(1, 0, At, B0); PG8_MMA(1, 1, At, B1); PG8_BAR; PG8_SCHED;
;             PG8_LDB(B0, 1, 0); PG8_LDB(B1, 1, 1); PG8_SCHED; PG8_LDA(At, 1, 0); PG8_STAGE(PG8_SA(0, 1), a2 + hstep, voffA);
;             PG8_WAIT_V(8); PG8_WAIT_L(0); PG8_BAR; PG8_MMA(0, 0, At, B0); PG8_MMA(0, 1, At, B1); PG8_BAR; PG8_SCHED;
;             PG8_LDA(At, 1, 1); PG8_STAGE(PG8_SB(1, 0), b3, voffB); PG8_STAGE(PG8_SB(1, 1), b3 + hstep, voffB); PG8_STAGE(PG8_SA(1, 0), a3, voffA);
;             PG8_WAIT_V(8); PG8_WAIT_L(0); PG8_BAR; PG8_MMA(1, 0, At, B0); PG8_MMA(1, 1, At, B1); PG8_BAR; PG8_SCHED;
.LBB0_1157:
	s_mov_b32 m0, s25
	s_nop 0
	global_load_lds_dwordx4 v166, s[100:101]
	s_add_u32 s52, s50, 0xfff80080
	s_addc_u32 s53, s51, -1
	s_add_i32 s63, 0, 0x10000
	s_cmp_eq_u32 s62, 28
	s_cselect_b32 s55, s35, s53
	s_cselect_b32 s54, s58, s52
	s_cselect_b32 s53, s31, s61
	s_cselect_b32 s52, s59, s60
	s_add_i32 s66, 0, 0x14000
	v_add_u32_e32 v78, s63, v177
	v_add_u32_e32 v134, s66, v177
	ds_read_b128 v[66:69], v78
	ds_read_b128 v[70:73], v78 offset:1024
	ds_read_b128 v[74:77], v78 offset:2048
	ds_read_b128 v[78:81], v78 offset:3072
	ds_read_b128 v[122:125], v134
	ds_read_b128 v[126:129], v134 offset:1024
	ds_read_b128 v[130:133], v134 offset:2048
	ds_read_b128 v[134:137], v134 offset:3072
	s_add_i32 m0, s89, 0xc000
	ds_read_b128 v[188:191], v193
	ds_read_b128 v[194:197], v193 offset:1024
	ds_read_b128 v[198:201], v193 offset:2048
	ds_read_b128 v[202:205], v193 offset:3072
	ds_read_b128 v[208:211], v193 offset:4096
	ds_read_b128 v[212:215], v193 offset:5120
	ds_read_b128 v[216:219], v193 offset:6144
	ds_read_b128 v[220:223], v193 offset:7168
	global_load_lds_dwordx4 v184, s[50:51]
	s_add_i32 m0, s89, 0xe000
	s_nop 0
	global_load_lds_dwordx4 v186, s[50:51]
	s_waitcnt vmcnt(8)
	s_waitcnt lgkmcnt(0)
	s_barrier
	s_setprio 1
	v_mfma_f32_16x16x32_bf16 v[150:153], v[66:69], v[188:191], v[150:153]
	v_mfma_f32_16x16x32_bf16 v[110:113], v[74:77], v[188:191], v[110:113]
	v_mfma_f32_16x16x32_bf16 v[146:149], v[66:69], v[198:201], v[146:149]
	v_mfma_f32_16x16x32_bf16 v[106:109], v[74:77], v[198:201], v[106:109]
	v_mfma_f32_16x16x32_bf16 v[142:145], v[66:69], v[208:211], v[142:145]
	v_mfma_f32_16x16x32_bf16 v[102:105], v[74:77], v[208:211], v[102:105]
	v_mfma_f32_16x16x32_bf16 v[138:141], v[66:69], v[216:219], v[138:141]
	v_mfma_f32_16x16x32_bf16 v[98:101], v[74:77], v[216:219], v[98:101]
	v_mfma_f32_16x16x32_bf16 v[150:153], v[70:73], v[194:197], v[150:153]
	v_mfma_f32_16x16x32_bf16 v[110:113], v[78:81], v[194:197], v[110:113]
	v_mfma_f32_16x16x32_bf16 v[146:149], v[70:73], v[202:205], v[146:149]
	v_mfma_f32_16x16x32_bf16 v[106:109], v[78:81], v[202:205], v[106:109]
	v_mfma_f32_16x16x32_bf16 v[142:145], v[70:73], v[212:215], v[142:145]
	v_mfma_f32_16x16x32_bf16 v[102:105], v[78:81], v[212:215], v[102:105]
	v_mfma_f32_16x16x32_bf16 v[138:141], v[70:73], v[220:223], v[138:141]
	v_mfma_f32_16x16x32_bf16 v[98:101], v[78:81], v[220:223], v[98:101]
	s_setprio 0
	s_setprio 1
	v_mfma_f32_16x16x32_bf16 v[94:97], v[122:125], v[188:191], v[94:97]
	v_mfma_f32_16x16x32_bf16 v[90:93], v[130:133], v[188:191], v[90:93]
	v_mfma_f32_16x16x32_bf16 v[158:161], v[122:125], v[198:201], v[158:161]
	v_mfma_f32_16x16x32_bf16 v[118:121], v[130:133], v[198:201], v[118:121]
	v_mfma_f32_16x16x32_bf16 v[154:157], v[122:125], v[208:211], v[154:157]
	v_mfma_f32_16x16x32_bf16 v[114:117], v[130:133], v[208:211], v[114:117]
	v_mfma_f32_16x16x32_bf16 v[86:89], v[122:125], v[216:219], v[86:89]
	v_mfma_f32_16x16x32_bf16 v[82:85], v[130:133], v[216:219], v[82:85]
	v_mfma_f32_16x16x32_bf16 v[94:97], v[126:129], v[194:197], v[94:97]
	v_mfma_f32_16x16x32_bf16 v[90:93], v[134:137], v[194:197], v[90:93]
	v_mfma_f32_16x16x32_bf16 v[158:161], v[126:129], v[202:205], v[158:161]
	v_mfma_f32_16x16x32_bf16 v[118:121], v[134:137], v[202:205], v[118:121]
	v_mfma_f32_16x16x32_bf16 v[154:157], v[126:129], v[212:215], v[154:157]
	v_mfma_f32_16x16x32_bf16 v[114:117], v[134:137], v[212:215], v[114:117]
	v_mfma_f32_16x16x32_bf16 v[86:89], v[126:129], v[220:223], v[86:89]
	v_mfma_f32_16x16x32_bf16 v[82:85], v[134:137], v[220:223], v[82:85]
	s_setprio 0
	s_barrier
	s_add_i32 s63, s63, s1
	s_add_u32 s98, s52, 0x80
	s_addc_u32 s99, s53, 0
	s_mov_b32 m0, s63
	ds_read_b128 v[188:191], v193 offset:16384
	ds_read_b128 v[194:197], v193 offset:17408
	ds_read_b128 v[198:201], v193 offset:18432
	ds_read_b128 v[202:205], v193 offset:19456
	ds_read_b128 v[208:211], v193 offset:20480
	ds_read_b128 v[212:215], v193 offset:21504
	ds_read_b128 v[216:219], v193 offset:22528
	ds_read_b128 v[220:223], v193 offset:23552
	global_load_lds_dwordx4 v164, s[52:53]
	s_add_i32 m0, s63, 0x2000
	s_add_u32 s64, s52, 0x80000
	s_addc_u32 s65, s53, 0
	s_add_i32 s63, s66, s1
	global_load_lds_dwordx4 v168, s[52:53]
	s_mov_b32 m0, s63
	s_add_u32 s100, s54, 0x80
	s_addc_u32 s101, s55, 0
	global_load_lds_dwordx4 v164, s[64:65]
	s_add_i32 m0, s63, 0x2000
	s_nop 0
	global_load_lds_dwordx4 v168, s[64:65]
	s_mov_b32 m0, s89
	s_nop 0
	global_load_lds_dwordx4 v162, s[54:55]
	s_waitcnt vmcnt(7)
	s_waitcnt lgkmcnt(0)
	s_barrier
	s_setprio 1
	v_mfma_f32_16x16x32_bf16 v[54:57], v[66:69], v[188:191], v[54:57]
	v_mfma_f32_16x16x32_bf16 v[30:33], v[74:77], v[188:191], v[30:33]
	v_mfma_f32_16x16x32_bf16 v[50:53], v[66:69], v[198:201], v[50:53]
	v_mfma_f32_16x16x32_bf16 v[26:29], v[74:77], v[198:201], v[26:29]
	v_mfma_f32_16x16x32_bf16 v[46:49], v[66:69], v[208:211], v[46:49]
	v_mfma_f32_16x16x32_bf16 v[22:25], v[74:77], v[208:211], v[22:25]
	v_mfma_f32_16x16x32_bf16 v[42:45], v[66:69], v[216:219], v[42:45]
	v_mfma_f32_16x16x32_bf16 v[16:19], v[74:77], v[216:219], v[16:19]
	v_mfma_f32_16x16x32_bf16 v[54:57], v[70:73], v[194:197], v[54:57]
	v_mfma_f32_16x16x32_bf16 v[30:33], v[78:81], v[194:197], v[30:33]
	v_mfma_f32_16x16x32_bf16 v[50:53], v[70:73], v[202:205], v[50:53]
	v_mfma_f32_16x16x32_bf16 v[26:29], v[78:81], v[202:205], v[26:29]
	v_mfma_f32_16x16x32_bf16 v[46:49], v[70:73], v[212:215], v[46:49]
	v_mfma_f32_16x16x32_bf16 v[22:25], v[78:81], v[212:215], v[22:25]
	v_mfma_f32_16x16x32_bf16 v[42:45], v[70:73], v[220:223], v[42:45]
	v_mfma_f32_16x16x32_bf16 v[16:19], v[78:81], v[220:223], v[16:19]
	s_setprio 0
	s_setprio 1
	v_mfma_f32_16x16x32_bf16 v[12:15], v[122:125], v[188:191], v[12:15]
	v_mfma_f32_16x16x32_bf16 v[8:11], v[130:133], v[188:191], v[8:11]
	v_mfma_f32_16x16x32_bf16 v[62:65], v[122:125], v[198:201], v[62:65]
	v_mfma_f32_16x16x32_bf16 v[38:41], v[130:133], v[198:201], v[38:41]
	v_mfma_f32_16x16x32_bf16 v[58:61], v[122:125], v[208:211], v[58:61]
	v_mfma_f32_16x16x32_bf16 v[34:37], v[130:133], v[208:211], v[34:37]
	v_mfma_f32_16x16x32_bf16 v[4:7], v[122:125], v[216:219], v[4:7]
	v_mfma_f32_16x16x32_bf16 v[0:3], v[130:133], v[216:219], v[0:3]
	v_mfma_f32_16x16x32_bf16 v[12:15], v[126:129], v[194:197], v[12:15]
	v_mfma_f32_16x16x32_bf16 v[8:11], v[134:137], v[194:197], v[8:11]
	v_mfma_f32_16x16x32_bf16 v[62:65], v[126:129], v[202:205], v[62:65]
	v_mfma_f32_16x16x32_bf16 v[38:41], v[134:137], v[202:205], v[38:41]
	v_mfma_f32_16x16x32_bf16 v[58:61], v[126:129], v[212:215], v[58:61]
	v_mfma_f32_16x16x32_bf16 v[34:37], v[134:137], v[212:215], v[34:37]
	v_mfma_f32_16x16x32_bf16 v[4:7], v[126:129], v[220:223], v[4:7]
	v_mfma_f32_16x16x32_bf16 v[0:3], v[134:137], v[220:223], v[0:3]
	s_setprio 0
	s_barrier
; #define PG8_STAGE(bufoff, gbase, voff) do { _Pragma("unroll") for (int _i = 0; _i < 2; ++_i) \
;         __builtin_amdgcn_global_load_lds((const unsigned*)((const char*)(gbase) + (voff)[_i]), (PG8_LAS unsigned*)(lds + (bufoff) + ldsw + _i * 8192), 16, 0, 0); } while (0)
; #define PG8_LDA(dst, b, h) do { _Pragma("unroll") for (int m = 0; m < 4; ++m) _Pragma("unroll") for (int k = 0; k < 2; ++k) dst[m][k] = *(const PG8_LAS bf16x8*)(lds + PG8_SA(b, h) + aoff + m * 2048 + k * 1024); } while (0)
; #define PG8_LDB(dst, b, h) do { _Pragma("unroll") for (int n = 0; n < 2; ++n) _Pragma("unroll") for (int k = 0; k < 2; ++k) dst[n][k] = *(const PG8_LAS bf16x8*)(lds + PG8_SB(b, h) + boff + n * 2048 + k * 1024); } while (0)
; #define PG8_MMA(ai, bj, At, Bt) do { __builtin_amdgcn_s_setprio(1); _Pragma("unroll") for (int m = 0; m < 4; ++m) _Pragma("unroll") for (int n = 0; n < 2; ++n) _Pragma("unroll") for (int k = 0; k < 2; ++k) \
;         acc[ai][bj][m][n] = __builtin_amdgcn_mfma_f32_16x16x32_bf16(Bt[n][k], At[m][k], acc[ai][bj][m][n], 0, 0, 0); __builtin_amdgcn_s_setprio(0); } while (0)
; #define PG8_WAIT_V(n) asm volatile("s_waitcnt vmcnt(" #n ")" ::: "memory")
; #define PG8_WAIT_L(n) asm volatile("s_waitcnt lgkmcnt(" #n ")" ::: "memory")
; #define PG8_BAR __builtin_amdgcn_s_barrier()
; #define PG8_SCHED __builtin_amdgcn_sched_barrier(0)
; template <class Epi, class Sched, bool ALIGN_EPI = false, bool SP2 = false>
; __device__ __forceinline__ void gemm_phase(PG8_LAS unsigned char* lds, const Gemm g, const Sched& S, const Epi& E, const int tid_in) {
;     ...
;         for (int t = 0; t < nt; t += 2) {
;     ...
;             PG8_LDB(B0, 1, 0); PG8_LDB(B1, 1, 1); PG8_SCHED; PG8_LDA(At, 1, 0); PG8_STAGE(PG8_SA(0, 1), a2 + hstep, voffA);
;             PG8_WAIT_V(8); PG8_WAIT_L(0); PG8_BAR; PG8_MMA(0, 0, At, B0); PG8_MMA(0, 1, At, B1); PG8_BAR; PG8_SCHED;
;             PG8_LDA(At, 1, 1); PG8_STAGE(PG8_SB(1, 0), b3, voffB); PG8_STAGE(PG8_SB(1, 1), b3 + hstep, voffB); PG8_STAGE(PG8_SA(1, 0), a3, voffA);
;             PG8_WAIT_V(8); PG8_WAIT_L(0); PG8_BAR; PG8_MMA(1, 0, At, B0); PG8_MMA(1, 1, At, B1); PG8_BAR; PG8_SCHED;
	s_add_i32 s63, 0, 0x18000
	s_add_i32 s64, 0, 0x1c000
	v_add_u32_e32 v78, s63, v177
	v_add_u32_e32 v134, s64, v177
	ds_read_b128 v[66:69], v78
	ds_read_b128 v[70:73], v78 offset:1024
	ds_read_b128 v[74:77], v78 offset:2048
	ds_read_b128 v[78:81], v78 offset:3072
	ds_read_b128 v[122:125], v134
	ds_read_b128 v[126:129], v134 offset:1024
	ds_read_b128 v[130:133], v134 offset:2048
	ds_read_b128 v[134:137], v134 offset:3072
	s_mov_b32 m0, s92
	s_nop 0
	global_load_lds_dwordx4 v166, s[54:55]
	s_add_u32 s54, s54, 0x80000
	s_addc_u32 s55, s55, 0
	s_mov_b32 m0, s2
	ds_read_b128 v[188:191], v193 offset:32768
	ds_read_b128 v[194:197], v193 offset:33792
	ds_read_b128 v[198:201], v193 offset:34816
	ds_read_b128 v[202:205], v193 offset:35840
	ds_read_b128 v[208:211], v193 offset:36864
	ds_read_b128 v[212:215], v193 offset:37888
	ds_read_b128 v[216:219], v193 offset:38912
	ds_read_b128 v[220:223], v193 offset:39936
	global_load_lds_dwordx4 v162, s[54:55]
	s_mov_b32 m0, s3
	s_nop 0
	global_load_lds_dwordx4 v166, s[54:55]
	s_waitcnt vmcnt(8)
	s_waitcnt lgkmcnt(0)
	s_barrier
	s_setprio 1
	v_mfma_f32_16x16x32_bf16 v[150:153], v[66:69], v[188:191], v[150:153]
	v_mfma_f32_16x16x32_bf16 v[110:113], v[74:77], v[188:191], v[110:113]
	v_mfma_f32_16x16x32_bf16 v[146:149], v[66:69], v[198:201], v[146:149]
	v_mfma_f32_16x16x32_bf16 v[106:109], v[74:77], v[198:201], v[106:109]
	v_mfma_f32_16x16x32_bf16 v[142:145], v[66:69], v[208:211], v[142:145]
	v_mfma_f32_16x16x32_bf16 v[102:105], v[74:77], v[208:211], v[102:105]
	v_mfma_f32_16x16x32_bf16 v[138:141], v[66:69], v[216:219], v[138:141]
	v_mfma_f32_16x16x32_bf16 v[98:101], v[74:77], v[216:219], v[98:101]
	v_mfma_f32_16x16x32_bf16 v[150:153], v[70:73], v[194:197], v[150:153]
	v_mfma_f32_16x16x32_bf16 v[110:113], v[78:81], v[194:197], v[110:113]
	v_mfma_f32_16x16x32_bf16 v[146:149], v[70:73], v[202:205], v[146:149]
	v_mfma_f32_16x16x32_bf16 v[106:109], v[78:81], v[202:205], v[106:109]
	v_mfma_f32_16x16x32_bf16 v[142:145], v[70:73], v[212:215], v[142:145]
	v_mfma_f32_16x16x32_bf16 v[102:105], v[78:81], v[212:215], v[102:105]
	v_mfma_f32_16x16x32_bf16 v[138:141], v[70:73], v[220:223], v[138:141]
	v_mfma_f32_16x16x32_bf16 v[98:101], v[78:81], v[220:223], v[98:101]
	s_setprio 0
	s_setprio 1
	v_mfma_f32_16x16x32_bf16 v[94:97], v[122:125], v[188:191], v[94:97]
	v_mfma_f32_16x16x32_bf16 v[90:93], v[130:133], v[188:191], v[90:93]
	v_mfma_f32_16x16x32_bf16 v[158:161], v[122:125], v[198:201], v[158:161]
	v_mfma_f32_16x16x32_bf16 v[118:121], v[130:133], v[198:201], v[118:121]
	v_mfma_f32_16x16x32_bf16 v[154:157], v[122:125], v[208:211], v[154:157]
	v_mfma_f32_16x16x32_bf16 v[114:117], v[130:133], v[208:211], v[114:117]
	v_mfma_f32_16x16x32_bf16 v[86:89], v[122:125], v[216:219], v[86:89]
	v_mfma_f32_16x16x32_bf16 v[82:85], v[130:133], v[216:219], v[82:85]
	v_mfma_f32_16x16x32_bf16 v[94:97], v[126:129], v[194:197], v[94:97]
	v_mfma_f32_16x16x32_bf16 v[90:93], v[134:137], v[194:197], v[90:93]
	v_mfma_f32_16x16x32_bf16 v[158:161], v[126:129], v[202:205], v[158:161]
	v_mfma_f32_16x16x32_bf16 v[118:121], v[134:137], v[202:205], v[118:121]
	v_mfma_f32_16x16x32_bf16 v[154:157], v[126:129], v[212:215], v[154:157]
	v_mfma_f32_16x16x32_bf16 v[114:117], v[134:137], v[212:215], v[114:117]
	v_mfma_f32_16x16x32_bf16 v[86:89], v[126:129], v[220:223], v[86:89]
	v_mfma_f32_16x16x32_bf16 v[82:85], v[134:137], v[220:223], v[82:85]
	s_setprio 0
	s_barrier
	s_add_i32 s54, s63, s1
	s_mov_b32 m0, s54
	ds_read_b128 v[188:191], v193 offset:49152
	ds_read_b128 v[194:197], v193 offset:50176
	ds_read_b128 v[198:201], v193 offset:51200
	ds_read_b128 v[202:205], v193 offset:52224
	ds_read_b128 v[208:211], v193 offset:53248
	ds_read_b128 v[212:215], v193 offset:54272
	ds_read_b128 v[216:219], v193 offset:55296
	ds_read_b128 v[220:223], v193 offset:56320
	global_load_lds_dwordx4 v164, s[98:99]
	s_add_i32 m0, s54, 0x2000
	s_add_u32 s52, s52, 0x80080
	s_addc_u32 s53, s53, 0
	s_add_i32 s54, s64, s1
	global_load_lds_dwordx4 v168, s[98:99]
	s_mov_b32 m0, s54
	s_nop 0
	global_load_lds_dwordx4 v164, s[52:53]
	s_add_i32 m0, s54, 0x2000
	s_nop 0
	global_load_lds_dwordx4 v168, s[52:53]
	s_mov_b32 m0, s24
	s_nop 0
	global_load_lds_dwordx4 v162, s[100:101]
	s_waitcnt vmcnt(7)
	s_waitcnt lgkmcnt(0)
	s_barrier
	s_setprio 1
	v_mfma_f32_16x16x32_bf16 v[54:57], v[66:69], v[188:191], v[54:57]
	v_mfma_f32_16x16x32_bf16 v[30:33], v[74:77], v[188:191], v[30:33]
	v_mfma_f32_16x16x32_bf16 v[50:53], v[66:69], v[198:201], v[50:53]
	v_mfma_f32_16x16x32_bf16 v[26:29], v[74:77], v[198:201], v[26:29]
	v_mfma_f32_16x16x32_bf16 v[46:49], v[66:69], v[208:211], v[46:49]
	v_mfma_f32_16x16x32_bf16 v[22:25], v[74:77], v[208:211], v[22:25]
	v_mfma_f32_16x16x32_bf16 v[42:45], v[66:69], v[216:219], v[42:45]
	v_mfma_f32_16x16x32_bf16 v[16:19], v[74:77], v[216:219], v[16:19]
	v_mfma_f32_16x16x32_bf16 v[54:57], v[70:73], v[194:197], v[54:57]
	v_mfma_f32_16x16x32_bf16 v[30:33], v[78:81], v[194:197], v[30:33]
	v_mfma_f32_16x16x32_bf16 v[50:53], v[70:73], v[202:205], v[50:53]
	v_mfma_f32_16x16x32_bf16 v[26:29], v[78:81], v[202:205], v[26:29]
	v_mfma_f32_16x16x32_bf16 v[46:49], v[70:73], v[212:215], v[46:49]
	v_mfma_f32_16x16x32_bf16 v[22:25], v[78:81], v[212:215], v[22:25]
	v_mfma_f32_16x16x32_bf16 v[42:45], v[70:73], v[220:223], v[42:45]
	v_mfma_f32_16x16x32_bf16 v[16:19], v[78:81], v[220:223], v[16:19]
	s_setprio 0
	s_setprio 1
	v_mfma_f32_16x16x32_bf16 v[12:15], v[122:125], v[188:191], v[12:15]
	v_mfma_f32_16x16x32_bf16 v[8:11], v[130:133], v[188:191], v[8:11]
	v_mfma_f32_16x16x32_bf16 v[62:65], v[122:125], v[198:201], v[62:65]
	v_mfma_f32_16x16x32_bf16 v[38:41], v[130:133], v[198:201], v[38:41]
	v_mfma_f32_16x16x32_bf16 v[58:61], v[122:125], v[208:211], v[58:61]
	v_mfma_f32_16x16x32_bf16 v[34:37], v[130:133], v[208:211], v[34:37]
	v_mfma_f32_16x16x32_bf16 v[4:7], v[122:125], v[216:219], v[4:7]
	v_mfma_f32_16x16x32_bf16 v[0:3], v[130:133], v[216:219], v[0:3]
	v_mfma_f32_16x16x32_bf16 v[12:15], v[126:129], v[194:197], v[12:15]
	v_mfma_f32_16x16x32_bf16 v[8:11], v[134:137], v[194:197], v[8:11]
	v_mfma_f32_16x16x32_bf16 v[62:65], v[126:129], v[202:205], v[62:65]
	v_mfma_f32_16x16x32_bf16 v[38:41], v[134:137], v[202:205], v[38:41]
	v_mfma_f32_16x16x32_bf16 v[58:61], v[126:129], v[212:215], v[58:61]
	v_mfma_f32_16x16x32_bf16 v[34:37], v[134:137], v[212:215], v[34:37]
	v_mfma_f32_16x16x32_bf16 v[4:7], v[126:129], v[220:223], v[4:7]
	v_mfma_f32_16x16x32_bf16 v[0:3], v[134:137], v[220:223], v[0:3]
	s_setprio 0
	s_barrier
	s_add_i32 s62, s62, 2
	s_add_u32 s50, s50, 0x100
	s_addc_u32 s51, s51, 0
	s_add_u32 s60, s60, 0x100
	s_addc_u32 s61, s61, 0
	s_cmp_gt_u32 s62, 29
	s_cbranch_scc0 .LBB0_1157
	s_and_b64 vcc, exec, s[28:29]
	s_cbranch_vccz .LBB0_1160
	s_barrier

; #define PG8_STAGE(bufoff, gbase, voff) do { _Pragma("unroll") for (int _i = 0; _i < 2; ++_i) \
;         __builtin_amdgcn_global_load_lds((const unsigned*)((const char*)(gbase) + (voff)[_i]), (PG8_LAS unsigned*)(lds + (bufoff) + ldsw + _i * 8192), 16, 0, 0); } while (0)
; #define PG8_LDA(dst, b, h) do { _Pragma("unroll") for (int m = 0; m < 4; ++m) _Pragma("unroll") for (int k = 0; k < 2; ++k) dst[m][k] = *(const PG8_LAS bf16x8*)(lds + PG8_SA(b, h) + aoff + m * 2048 + k * 1024); } while (0)
; #define PG8_LDB(dst, b, h) do { _Pragma("unroll") for (int n = 0; n < 2; ++n) _Pragma("unroll") for (int k = 0; k < 2; ++k) dst[n][k] = *(const PG8_LAS bf16x8*)(lds + PG8_SB(b, h) + boff + n * 2048 + k * 1024); } while (0)
; template <class Epi, class Sched, bool ALIGN_EPI = false, bool SP2 = false>
; __device__ __forceinline__ void gemm_phase(PG8_LAS unsigned char* lds, const Gemm g, const Sched& S, const Epi& E, const int tid_in) {
;     ...
;             const bool last = (t == nt - 2);
;             const char* a1 = cA + (size_t)(t + 1) * kstep;
;             const char* a2 = last ? nA : cA + (size_t)(t + 2) * kstep; const char* b2 = last ? nB : cB + (size_t)(t + 2) * kstep;
;             const char* a3 = a2 + kstep; const char* b3 = b2 + kstep;
;             if (last && has_next) S.a_ready(nxt);
;             if constexpr (SP2) {
;             PG8_LDB(B0, 0, 0); PG8_LDB(B1, 0, 1); PG8_SCHED; PG8_LDA(At, 0, 0); PG8_STAGE(PG8_SA(1, 1), a1 + hstep, voffA);
;             PG8_WAIT_V(8); PG8_WAIT_L(0); PG8_BAR; PG8_MMA(0, 0, At, B0); PG8_MMA(0, 1, At, B1); PG8_BAR; PG8_SCHED;
;             PG8_LDA(At, 0, 1); PG8_STAGE(PG8_SB(0, 0), b2, voffB); PG8_STAGE(PG8_SB(0, 1), b2 + hstep, voffB); PG8_STAGE(PG8_SA(0, 0), a2, voffA);
;             PG8_WAIT_V(8); PG8_WAIT_L(0); PG8_BAR; PG8_MMA(1, 0, At, B0); PG8_MMA(1, 1, At, B1); PG8_BAR; PG8_SCHED;
;             PG8_LDB(B0, 1, 0); PG8_LDB(B1, 1, 1); PG8_SCHED; PG8_LDA(At, 1, 0); PG8_STAGE(PG8_SA(0, 1), a2 + hstep, voffA);
;             PG8_WAIT_V(8); PG8_WAIT_L(0); PG8_BAR; PG8_MMA(0, 0, At, B0); PG8_MMA(0, 1, At, B1); PG8_BAR; PG8_SCHED;
;             PG8_LDA(At, 1, 1); PG8_STAGE(PG8_SB(1, 0), b3, voffB); PG8_STAGE(PG8_SB(1, 1), b3 + hstep, voffB); PG8_STAGE(PG8_SA(1, 0), a3, voffA);
;             PG8_WAIT_V(8); PG8_WAIT_L(0); PG8_BAR; PG8_MMA(1, 0, At, B0); PG8_MMA(1, 1, At, B1); PG8_BAR; PG8_SCHED;
.LBB0_1305:
	s_mov_b32 m0, s47
	s_nop 0
	global_load_lds_dwordx4 v216, s[100:101]
	s_add_u32 s30, s28, 0x100
	s_addc_u32 s31, s29, 0
	s_add_i32 s57, 0, 0x10000
	s_cmpk_eq_i32 s56, 0x54
	s_cselect_b32 s39, s25, s31
	s_cselect_b32 s38, s24, s30
	s_cselect_b32 s35, s27, s55
	s_cselect_b32 s34, s26, s54
	s_add_i32 s58, 0, 0x14000
	v_add_u32_e32 v102, s57, v208
	v_add_u32_e32 v142, s58, v208
	ds_read_b128 v[78:81], v102
	ds_read_b128 v[86:89], v102 offset:1024
	ds_read_b128 v[94:97], v102 offset:2048
	ds_read_b128 v[102:105], v102 offset:3072
	ds_read_b128 v[118:121], v142
	ds_read_b128 v[126:129], v142 offset:1024
	ds_read_b128 v[134:137], v142 offset:2048
	ds_read_b128 v[142:145], v142 offset:3072
	v_lshl_add_u64 v[194:195], s[28:29], 0, v[222:223]
	s_add_i32 m0, s40, 0xc000
	ds_read_b128 v[154:157], v244
	ds_read_b128 v[158:161], v244 offset:1024
	ds_read_b128 v[162:165], v244 offset:2048
	ds_read_b128 v[166:169], v244 offset:3072
	ds_read_b128 v[170:173], v244 offset:4096
	ds_read_b128 v[182:185], v244 offset:5120
	ds_read_b128 v[186:189], v244 offset:6144
	ds_read_b128 v[190:193], v244 offset:7168
	global_load_lds_dwordx4 v[194:195], off
	v_lshl_add_u64 v[194:195], s[28:29], 0, v[224:225]
	s_add_i32 m0, s40, 0xe000
	s_nop 0
	global_load_lds_dwordx4 v[194:195], off
	s_waitcnt vmcnt(8)
	s_waitcnt lgkmcnt(0)
	s_barrier
	s_setprio 1
	v_mfma_f32_16x16x32_bf16 v[178:181], v[78:81], v[154:157], v[178:181]
	v_mfma_f32_16x16x32_bf16 v[174:177], v[94:97], v[154:157], v[174:177]
	v_mfma_f32_16x16x32_bf16 v[138:141], v[78:81], v[162:165], v[138:141]
	v_mfma_f32_16x16x32_bf16 v[130:133], v[94:97], v[162:165], v[130:133]
	v_mfma_f32_16x16x32_bf16 v[110:113], v[78:81], v[170:173], v[110:113]
	v_mfma_f32_16x16x32_bf16 v[106:109], v[94:97], v[170:173], v[106:109]
	v_mfma_f32_16x16x32_bf16 v[82:85], v[78:81], v[186:189], v[82:85]
	v_mfma_f32_16x16x32_bf16 v[74:77], v[94:97], v[186:189], v[74:77]
	v_mfma_f32_16x16x32_bf16 v[178:181], v[86:89], v[158:161], v[178:181]
	v_mfma_f32_16x16x32_bf16 v[174:177], v[102:105], v[158:161], v[174:177]
	v_mfma_f32_16x16x32_bf16 v[138:141], v[86:89], v[166:169], v[138:141]
	v_mfma_f32_16x16x32_bf16 v[130:133], v[102:105], v[166:169], v[130:133]
	v_mfma_f32_16x16x32_bf16 v[110:113], v[86:89], v[182:185], v[110:113]
	v_mfma_f32_16x16x32_bf16 v[106:109], v[102:105], v[182:185], v[106:109]
	v_mfma_f32_16x16x32_bf16 v[82:85], v[86:89], v[190:193], v[82:85]
	v_mfma_f32_16x16x32_bf16 v[74:77], v[102:105], v[190:193], v[74:77]
	s_setprio 0
	s_setprio 1
	v_mfma_f32_16x16x32_bf16 v[150:153], v[118:121], v[154:157], v[150:153]
	v_mfma_f32_16x16x32_bf16 v[146:149], v[134:137], v[154:157], v[146:149]
	v_mfma_f32_16x16x32_bf16 v[122:125], v[118:121], v[162:165], v[122:125]
	v_mfma_f32_16x16x32_bf16 v[114:117], v[134:137], v[162:165], v[114:117]
	v_mfma_f32_16x16x32_bf16 v[98:101], v[118:121], v[170:173], v[98:101]
	v_mfma_f32_16x16x32_bf16 v[90:93], v[134:137], v[170:173], v[90:93]
	v_mfma_f32_16x16x32_bf16 v[70:73], v[118:121], v[186:189], v[70:73]
	v_mfma_f32_16x16x32_bf16 v[66:69], v[134:137], v[186:189], v[66:69]
	v_mfma_f32_16x16x32_bf16 v[150:153], v[126:129], v[158:161], v[150:153]
	v_mfma_f32_16x16x32_bf16 v[146:149], v[142:145], v[158:161], v[146:149]
	v_mfma_f32_16x16x32_bf16 v[122:125], v[126:129], v[166:169], v[122:125]
	v_mfma_f32_16x16x32_bf16 v[114:117], v[142:145], v[166:169], v[114:117]
	v_mfma_f32_16x16x32_bf16 v[98:101], v[126:129], v[182:185], v[98:101]
	v_mfma_f32_16x16x32_bf16 v[90:93], v[142:145], v[182:185], v[90:93]
	v_mfma_f32_16x16x32_bf16 v[70:73], v[126:129], v[190:193], v[70:73]
	v_mfma_f32_16x16x32_bf16 v[66:69], v[142:145], v[190:193], v[66:69]
	s_setprio 0
	s_barrier
	s_add_i32 s28, s57, s19
	s_add_u32 s98, s34, 0x80
	s_addc_u32 s99, s35, 0
	s_mov_b32 m0, s28
	ds_read_b128 v[154:157], v244 offset:16384
	ds_read_b128 v[158:161], v244 offset:17408
	ds_read_b128 v[162:165], v244 offset:18432
	ds_read_b128 v[166:169], v244 offset:19456
	ds_read_b128 v[170:173], v244 offset:20480
	ds_read_b128 v[182:185], v244 offset:21504
	ds_read_b128 v[186:189], v244 offset:22528
	ds_read_b128 v[190:193], v244 offset:23552
	global_load_lds_dwordx4 v218, s[34:35]
	s_add_i32 m0, s28, 0x2000
	s_add_u32 s28, s34, 0x160000
	s_addc_u32 s29, s35, 0
	s_add_i32 s57, s58, s19
	global_load_lds_dwordx4 v214, s[34:35]
	s_mov_b32 m0, s57
	s_add_u32 s100, s38, 0x80
	s_addc_u32 s101, s39, 0
	global_load_lds_dwordx4 v218, s[28:29]
	s_add_i32 m0, s57, 0x2000
	s_nop 0
	global_load_lds_dwordx4 v214, s[28:29]
	s_mov_b32 m0, s40
	s_nop 0
	global_load_lds_dwordx4 v220, s[38:39]
	s_waitcnt vmcnt(7)
	s_waitcnt lgkmcnt(0)
	s_barrier
; #define PG8_STAGE(bufoff, gbase, voff) do { _Pragma("unroll") for (int _i = 0; _i < 2; ++_i) \
;         __builtin_amdgcn_global_load_lds((const unsigned*)((const char*)(gbase) + (voff)[_i]), (PG8_LAS unsigned*)(lds + (bufoff) + ldsw + _i * 8192), 16, 0, 0); } while (0)
; #define PG8_LDA(dst, b, h) do { _Pragma("unroll") for (int m = 0; m < 4; ++m) _Pragma("unroll") for (int k = 0; k < 2; ++k) dst[m][k] = *(const PG8_LAS bf16x8*)(lds + PG8_SA(b, h) + aoff + m * 2048 + k * 1024); } while (0)
; #define PG8_LDB(dst, b, h) do { _Pragma("unroll") for (int n = 0; n < 2; ++n) _Pragma("unroll") for (int k = 0; k < 2; ++k) dst[n][k] = *(const PG8_LAS bf16x8*)(lds + PG8_SB(b, h) + boff + n * 2048 + k * 1024); } while (0)
; #define PG8_MMA(ai, bj, At, Bt) do { __builtin_amdgcn_s_setprio(1); _Pragma("unroll") for (int m = 0; m < 4; ++m) _Pragma("unroll") for (int n = 0; n < 2; ++n) _Pragma("unroll") for (int k = 0; k < 2; ++k) \
;         acc[ai][bj][m][n] = __builtin_amdgcn_mfma_f32_16x16x32_bf16(Bt[n][k], At[m][k], acc[ai][bj][m][n], 0, 0, 0); __builtin_amdgcn_s_setprio(0); } while (0)
; #define PG8_WAIT_V(n) asm volatile("s_waitcnt vmcnt(" #n ")" ::: "memory")
; #define PG8_WAIT_L(n) asm volatile("s_waitcnt lgkmcnt(" #n ")" ::: "memory")
; #define PG8_BAR __builtin_amdgcn_s_barrier()
; #define PG8_SCHED __builtin_amdgcn_sched_barrier(0)
; template <class Epi, class Sched, bool ALIGN_EPI = false, bool SP2 = false>
; __device__ __forceinline__ void gemm_phase(PG8_LAS unsigned char* lds, const Gemm g, const Sched& S, const Epi& E, const int tid_in) {
;     ...
;             PG8_WAIT_V(8); PG8_WAIT_L(0); PG8_BAR; PG8_MMA(1, 0, At, B0); PG8_MMA(1, 1, At, B1); PG8_BAR; PG8_SCHED;
;             PG8_LDB(B0, 1, 0); PG8_LDB(B1, 1, 1); PG8_SCHED; PG8_LDA(At, 1, 0); PG8_STAGE(PG8_SA(0, 1), a2 + hstep, voffA);
;             PG8_WAIT_V(8); PG8_WAIT_L(0); PG8_BAR; PG8_MMA(0, 0, At, B0); PG8_MMA(0, 1, At, B1); PG8_BAR; PG8_SCHED;
;             PG8_LDA(At, 1, 1); PG8_STAGE(PG8_SB(1, 0), b3, voffB); PG8_STAGE(PG8_SB(1, 1), b3 + hstep, voffB); PG8_STAGE(PG8_SA(1, 0), a3, voffA);
	s_setprio 1
	v_mfma_f32_16x16x32_bf16 v[62:65], v[78:81], v[154:157], v[62:65]
	v_mfma_f32_16x16x32_bf16 v[58:61], v[94:97], v[154:157], v[58:61]
	v_mfma_f32_16x16x32_bf16 v[46:49], v[78:81], v[162:165], v[46:49]
	v_mfma_f32_16x16x32_bf16 v[42:45], v[94:97], v[162:165], v[42:45]
	v_mfma_f32_16x16x32_bf16 v[30:33], v[78:81], v[170:173], v[30:33]
	v_mfma_f32_16x16x32_bf16 v[26:29], v[94:97], v[170:173], v[26:29]
	v_mfma_f32_16x16x32_bf16 v[12:15], v[78:81], v[186:189], v[12:15]
	v_mfma_f32_16x16x32_bf16 v[8:11], v[94:97], v[186:189], v[8:11]
	v_mfma_f32_16x16x32_bf16 v[62:65], v[86:89], v[158:161], v[62:65]
	v_mfma_f32_16x16x32_bf16 v[58:61], v[102:105], v[158:161], v[58:61]
	v_mfma_f32_16x16x32_bf16 v[46:49], v[86:89], v[166:169], v[46:49]
	v_mfma_f32_16x16x32_bf16 v[42:45], v[102:105], v[166:169], v[42:45]
	v_mfma_f32_16x16x32_bf16 v[30:33], v[86:89], v[182:185], v[30:33]
	v_mfma_f32_16x16x32_bf16 v[26:29], v[102:105], v[182:185], v[26:29]
	v_mfma_f32_16x16x32_bf16 v[12:15], v[86:89], v[190:193], v[12:15]
	v_mfma_f32_16x16x32_bf16 v[8:11], v[102:105], v[190:193], v[8:11]
	s_setprio 0
	s_setprio 1
	v_mfma_f32_16x16x32_bf16 v[54:57], v[118:121], v[154:157], v[54:57]
	v_mfma_f32_16x16x32_bf16 v[50:53], v[134:137], v[154:157], v[50:53]
	v_mfma_f32_16x16x32_bf16 v[38:41], v[118:121], v[162:165], v[38:41]
	v_mfma_f32_16x16x32_bf16 v[34:37], v[134:137], v[162:165], v[34:37]
	v_mfma_f32_16x16x32_bf16 v[22:25], v[118:121], v[170:173], v[22:25]
	v_mfma_f32_16x16x32_bf16 v[16:19], v[134:137], v[170:173], v[16:19]
	v_mfma_f32_16x16x32_bf16 v[4:7], v[118:121], v[186:189], v[4:7]
	v_mfma_f32_16x16x32_bf16 v[0:3], v[134:137], v[186:189], v[0:3]
	v_mfma_f32_16x16x32_bf16 v[54:57], v[126:129], v[158:161], v[54:57]
	v_mfma_f32_16x16x32_bf16 v[50:53], v[142:145], v[158:161], v[50:53]
	v_mfma_f32_16x16x32_bf16 v[38:41], v[126:129], v[166:169], v[38:41]
	v_mfma_f32_16x16x32_bf16 v[34:37], v[142:145], v[166:169], v[34:37]
	v_mfma_f32_16x16x32_bf16 v[22:25], v[126:129], v[182:185], v[22:25]
	v_mfma_f32_16x16x32_bf16 v[16:19], v[142:145], v[182:185], v[16:19]
	v_mfma_f32_16x16x32_bf16 v[4:7], v[126:129], v[190:193], v[4:7]
	v_mfma_f32_16x16x32_bf16 v[0:3], v[142:145], v[190:193], v[0:3]
	s_setprio 0
	s_barrier
	s_add_i32 s57, 0, 0x18000
	s_add_i32 s58, 0, 0x1c000
	v_add_u32_e32 v102, s57, v208
	v_add_u32_e32 v142, s58, v208
	ds_read_b128 v[78:81], v102
	ds_read_b128 v[86:89], v102 offset:1024
	ds_read_b128 v[94:97], v102 offset:2048
	ds_read_b128 v[102:105], v102 offset:3072
	ds_read_b128 v[118:121], v142
	ds_read_b128 v[126:129], v142 offset:1024
	ds_read_b128 v[134:137], v142 offset:2048
	ds_read_b128 v[142:145], v142 offset:3072
	s_add_u32 s28, s38, 0x160000
	s_addc_u32 s29, s39, 0
	s_mov_b32 m0, s41
	s_nop 0
	global_load_lds_dwordx4 v216, s[38:39]
	s_mov_b32 m0, s42
	ds_read_b128 v[154:157], v244 offset:32768
	ds_read_b128 v[158:161], v244 offset:33792
	ds_read_b128 v[162:165], v244 offset:34816
	ds_read_b128 v[166:169], v244 offset:35840
	ds_read_b128 v[170:173], v244 offset:36864
	ds_read_b128 v[182:185], v244 offset:37888
	ds_read_b128 v[186:189], v244 offset:38912
	ds_read_b128 v[190:193], v244 offset:39936
	global_load_lds_dwordx4 v220, s[28:29]
	s_mov_b32 m0, s43
	s_nop 0
	global_load_lds_dwordx4 v216, s[28:29]
	s_waitcnt vmcnt(8)
	s_waitcnt lgkmcnt(0)
	s_barrier
	s_setprio 1
	v_mfma_f32_16x16x32_bf16 v[178:181], v[78:81], v[154:157], v[178:181]
	v_mfma_f32_16x16x32_bf16 v[174:177], v[94:97], v[154:157], v[174:177]
	v_mfma_f32_16x16x32_bf16 v[138:141], v[78:81], v[162:165], v[138:141]
	v_mfma_f32_16x16x32_bf16 v[130:133], v[94:97], v[162:165], v[130:133]
	v_mfma_f32_16x16x32_bf16 v[110:113], v[78:81], v[170:173], v[110:113]
	v_mfma_f32_16x16x32_bf16 v[106:109], v[94:97], v[170:173], v[106:109]
	v_mfma_f32_16x16x32_bf16 v[82:85], v[78:81], v[186:189], v[82:85]
	v_mfma_f32_16x16x32_bf16 v[74:77], v[94:97], v[186:189], v[74:77]
	v_mfma_f32_16x16x32_bf16 v[178:181], v[86:89], v[158:161], v[178:181]
	v_mfma_f32_16x16x32_bf16 v[174:177], v[102:105], v[158:161], v[174:177]
	v_mfma_f32_16x16x32_bf16 v[138:141], v[86:89], v[166:169], v[138:141]
	v_mfma_f32_16x16x32_bf16 v[130:133], v[102:105], v[166:169], v[130:133]
	v_mfma_f32_16x16x32_bf16 v[110:113], v[86:89], v[182:185], v[110:113]
	v_mfma_f32_16x16x32_bf16 v[106:109], v[102:105], v[182:185], v[106:109]
	v_mfma_f32_16x16x32_bf16 v[82:85], v[86:89], v[190:193], v[82:85]
	v_mfma_f32_16x16x32_bf16 v[74:77], v[102:105], v[190:193], v[74:77]
	s_setprio 0
	s_setprio 1
	v_mfma_f32_16x16x32_bf16 v[150:153], v[118:121], v[154:157], v[150:153]
	v_mfma_f32_16x16x32_bf16 v[146:149], v[134:137], v[154:157], v[146:149]
	v_mfma_f32_16x16x32_bf16 v[122:125], v[118:121], v[162:165], v[122:125]
	v_mfma_f32_16x16x32_bf16 v[114:117], v[134:137], v[162:165], v[114:117]
	v_mfma_f32_16x16x32_bf16 v[98:101], v[118:121], v[170:173], v[98:101]
	v_mfma_f32_16x16x32_bf16 v[90:93], v[134:137], v[170:173], v[90:93]
	v_mfma_f32_16x16x32_bf16 v[70:73], v[118:121], v[186:189], v[70:73]
	v_mfma_f32_16x16x32_bf16 v[66:69], v[134:137], v[186:189], v[66:69]
	v_mfma_f32_16x16x32_bf16 v[150:153], v[126:129], v[158:161], v[150:153]
	v_mfma_f32_16x16x32_bf16 v[146:149], v[142:145], v[158:161], v[146:149]
	v_mfma_f32_16x16x32_bf16 v[122:125], v[126:129], v[166:169], v[122:125]
	v_mfma_f32_16x16x32_bf16 v[114:117], v[142:145], v[166:169], v[114:117]
	v_mfma_f32_16x16x32_bf16 v[98:101], v[126:129], v[182:185], v[98:101]
	v_mfma_f32_16x16x32_bf16 v[90:93], v[142:145], v[182:185], v[90:93]
	v_mfma_f32_16x16x32_bf16 v[70:73], v[126:129], v[190:193], v[70:73]
	v_mfma_f32_16x16x32_bf16 v[66:69], v[142:145], v[190:193], v[66:69]
	s_setprio 0
	s_barrier
; #define PG8_STAGE(bufoff, gbase, voff) do { _Pragma("unroll") for (int _i = 0; _i < 2; ++_i) \
;         __builtin_amdgcn_global_load_lds((const unsigned*)((const char*)(gbase) + (voff)[_i]), (PG8_LAS unsigned*)(lds + (bufoff) + ldsw + _i * 8192), 16, 0, 0); } while (0)
; #define PG8_LDA(dst, b, h) do { _Pragma("unroll") for (int m = 0; m < 4; ++m) _Pragma("unroll") for (int k = 0; k < 2; ++k) dst[m][k] = *(const PG8_LAS bf16x8*)(lds + PG8_SA(b, h) + aoff + m * 2048 + k * 1024); } while (0)
; #define PG8_MMA(ai, bj, At, Bt) do { __builtin_amdgcn_s_setprio(1); _Pragma("unroll") for (int m = 0; m < 4; ++m) _Pragma("unroll") for (int n = 0; n < 2; ++n) _Pragma("unroll") for (int k = 0; k < 2; ++k) \
;         acc[ai][bj][m][n] = __builtin_amdgcn_mfma_f32_16x16x32_bf16(Bt[n][k], At[m][k], acc[ai][bj][m][n], 0, 0, 0); __builtin_amdgcn_s_setprio(0); } while (0)
; #define PG8_WAIT_V(n) asm volatile("s_waitcnt vmcnt(" #n ")" ::: "memory")
; #define PG8_WAIT_L(n) asm volatile("s_waitcnt lgkmcnt(" #n ")" ::: "memory")
; #define PG8_BAR __builtin_amdgcn_s_barrier()
; #define PG8_SCHED __builtin_amdgcn_sched_barrier(0)
; template <class Epi, class Sched, bool ALIGN_EPI = false, bool SP2 = false>
; __device__ __forceinline__ void gemm_phase(PG8_LAS unsigned char* lds, const Gemm g, const Sched& S, const Epi& E, const int tid_in) {
;     ...
;         for (int t = 0; t < nt; t += 2) {
;     ...
;             PG8_WAIT_V(8); PG8_WAIT_L(0); PG8_BAR; PG8_MMA(0, 0, At, B0); PG8_MMA(0, 1, At, B1); PG8_BAR; PG8_SCHED;
;             PG8_LDA(At, 1, 1); PG8_STAGE(PG8_SB(1, 0), b3, voffB); PG8_STAGE(PG8_SB(1, 1), b3 + hstep, voffB); PG8_STAGE(PG8_SA(1, 0), a3, voffA);
;             PG8_WAIT_V(8); PG8_WAIT_L(0); PG8_BAR; PG8_MMA(1, 0, At, B0); PG8_MMA(1, 1, At, B1); PG8_BAR; PG8_SCHED;
	s_add_i32 s28, s57, s19
	s_mov_b32 m0, s28
	ds_read_b128 v[154:157], v244 offset:49152
	ds_read_b128 v[158:161], v244 offset:50176
	ds_read_b128 v[162:165], v244 offset:51200
	ds_read_b128 v[166:169], v244 offset:52224
	ds_read_b128 v[170:173], v244 offset:53248
	ds_read_b128 v[182:185], v244 offset:54272
	ds_read_b128 v[186:189], v244 offset:55296
	ds_read_b128 v[190:193], v244 offset:56320
	global_load_lds_dwordx4 v218, s[98:99]
	s_add_i32 m0, s28, 0x2000
	s_add_u32 s28, s34, 0x160080
	s_addc_u32 s29, s35, 0
	s_add_i32 s34, s58, s19
	global_load_lds_dwordx4 v214, s[98:99]
	s_mov_b32 m0, s34
	s_nop 0
	global_load_lds_dwordx4 v218, s[28:29]
	s_add_i32 m0, s34, 0x2000
	s_nop 0
	global_load_lds_dwordx4 v214, s[28:29]
	s_mov_b32 m0, s46
	s_nop 0
	global_load_lds_dwordx4 v220, s[100:101]
	s_waitcnt vmcnt(7)
	s_waitcnt lgkmcnt(0)
	s_barrier
	s_setprio 1
	v_mfma_f32_16x16x32_bf16 v[62:65], v[78:81], v[154:157], v[62:65]
	v_mfma_f32_16x16x32_bf16 v[58:61], v[94:97], v[154:157], v[58:61]
	v_mfma_f32_16x16x32_bf16 v[46:49], v[78:81], v[162:165], v[46:49]
	v_mfma_f32_16x16x32_bf16 v[42:45], v[94:97], v[162:165], v[42:45]
	v_mfma_f32_16x16x32_bf16 v[30:33], v[78:81], v[170:173], v[30:33]
	v_mfma_f32_16x16x32_bf16 v[26:29], v[94:97], v[170:173], v[26:29]
	v_mfma_f32_16x16x32_bf16 v[12:15], v[78:81], v[186:189], v[12:15]
	v_mfma_f32_16x16x32_bf16 v[8:11], v[94:97], v[186:189], v[8:11]
	v_mfma_f32_16x16x32_bf16 v[62:65], v[86:89], v[158:161], v[62:65]
	v_mfma_f32_16x16x32_bf16 v[58:61], v[102:105], v[158:161], v[58:61]
	v_mfma_f32_16x16x32_bf16 v[46:49], v[86:89], v[166:169], v[46:49]
	v_mfma_f32_16x16x32_bf16 v[42:45], v[102:105], v[166:169], v[42:45]
	v_mfma_f32_16x16x32_bf16 v[30:33], v[86:89], v[182:185], v[30:33]
	v_mfma_f32_16x16x32_bf16 v[26:29], v[102:105], v[182:185], v[26:29]
	v_mfma_f32_16x16x32_bf16 v[12:15], v[86:89], v[190:193], v[12:15]
	v_mfma_f32_16x16x32_bf16 v[8:11], v[102:105], v[190:193], v[8:11]
	s_setprio 0
	s_setprio 1
	v_mfma_f32_16x16x32_bf16 v[54:57], v[118:121], v[154:157], v[54:57]
	v_mfma_f32_16x16x32_bf16 v[50:53], v[134:137], v[154:157], v[50:53]
	v_mfma_f32_16x16x32_bf16 v[38:41], v[118:121], v[162:165], v[38:41]
	v_mfma_f32_16x16x32_bf16 v[34:37], v[134:137], v[162:165], v[34:37]
	v_mfma_f32_16x16x32_bf16 v[22:25], v[118:121], v[170:173], v[22:25]
	v_mfma_f32_16x16x32_bf16 v[16:19], v[134:137], v[170:173], v[16:19]
	v_mfma_f32_16x16x32_bf16 v[4:7], v[118:121], v[186:189], v[4:7]
	v_mfma_f32_16x16x32_bf16 v[0:3], v[134:137], v[186:189], v[0:3]
	v_mfma_f32_16x16x32_bf16 v[54:57], v[126:129], v[158:161], v[54:57]
	v_mfma_f32_16x16x32_bf16 v[50:53], v[142:145], v[158:161], v[50:53]
	v_mfma_f32_16x16x32_bf16 v[38:41], v[126:129], v[166:169], v[38:41]
	v_mfma_f32_16x16x32_bf16 v[34:37], v[142:145], v[166:169], v[34:37]
	v_mfma_f32_16x16x32_bf16 v[22:25], v[126:129], v[182:185], v[22:25]
	v_mfma_f32_16x16x32_bf16 v[16:19], v[142:145], v[182:185], v[16:19]
	v_mfma_f32_16x16x32_bf16 v[4:7], v[126:129], v[190:193], v[4:7]
	v_mfma_f32_16x16x32_bf16 v[0:3], v[142:145], v[190:193], v[0:3]
	s_setprio 0
	s_barrier
	s_add_i32 s56, s56, 2
	s_add_u32 s54, s54, 0x100
	s_addc_u32 s55, s55, 0
	s_cmpk_gt_u32 s56, 0x55
	s_mov_b64 s[28:29], s[30:31]
	s_cbranch_scc0 .LBB0_1305
	v_mov_b32_e32 v207, 0x7f800000
	s_and_b64 vcc, exec, s[22:23]
	s_cbranch_vccz .LBB0_1308
	s_barrier
